# in-proj conv epilogue: n=0 block rows parked in dead accumulator registers, the n=1 block stores both column quads with one dwordx4 (18 stores per wave instead of 32)
# speedup vs baseline: 1.0109x; 1.0061x over previous
; __device__ __forceinline__ unsigned cvt_pk_bf16(float lo, float hi) { unsigned r; asm("v_cvt_pk_bf16_f32 %0, %1, %2" : "=v"(r) : "v"(lo), "v"(hi)); return r; }
; __device__ __forceinline__ float siluf_(float x) { return x * sigmoidf_(x); }
; __device__ __forceinline__ float dpp_ror1(float v) { return __builtin_bit_cast(float, __builtin_amdgcn_update_dpp(0, __builtin_bit_cast(int, v), 0x121, 0xf, 0xf, false)); }
;     __device__ __forceinline__ void operator()(f32x4 (&acc)[2][2][4][2], const pg8::Unit& u, int wr, int wc, int fr, int fq) const {
;     ...
;                 for (int n = 0; n < 2; ++n) { const int ch = ch0 + bj * 128 + 4 * n;
;                     const f32x4 w0 = *(const f32x4*)(cw + ch), w1 = *(const f32x4*)(cw + CW + ch), w2 = *(const f32x4*)(cw + 2 * CW + ch), w3 = *(const f32x4*)(cw + 3 * CW + ch), bb = *(const f32x4*)(cb + ch);
; #pragma unroll
;                     for (int m = 0; m < 4; ++m) { const int row = row0 + ai * 128 + m * 16; const f32x4 g = acc[ai][bj][m][n]; f32x4 p1, p2, p3;
;                         if (prompt) { const f32x4 gp = (m == 0) ? hal[n] : acc[ai][bj][m > 0 ? m - 1 : 0][n];
; #pragma unroll
;                             for (int j = 0; j < 4; ++j) { p1[j] = dpp_ror1(fr == 15 ? gp[j] : g[j]); p2[j] = dpp_ror2(fr >= 14 ? gp[j] : g[j]); p3[j] = dpp_ror3(fr >= 13 ? gp[j] : g[j]); } }
;                         else { const int t = fr & 3; const float* sp = stp + (size_t)((row - MP) >> 2) * 3 * CW + ch;
;                             const f32x4 b0 = *(const f32x4*)sp, b1 = *(const f32x4*)(sp + CW), b2 = *(const f32x4*)(sp + 2 * CW);
; #pragma unroll
;                             for (int j = 0; j < 4; ++j) { const float r1 = dpp_ror1(g[j]), r2 = dpp_ror2(g[j]), r3 = dpp_ror3(g[j]);
;                                 p1[j] = t >= 1 ? r1 : b2[j]; p2[j] = t >= 2 ? r2 : (t == 1 ? b2[j] : b1[j]); p3[j] = t >= 3 ? r3 : (t == 2 ? b2[j] : (t == 1 ? b1[j] : b0[j])); } }
;                         float o[4];
; #pragma unroll
;                         for (int j = 0; j < 4; ++j) { const float y = bb[j] + w0[j] * p3[j] + w1[j] * p2[j] + w2[j] * p1[j] + w3[j] * g[j]; o[j] = is_rg ? y : siluf_(y); }
;                         u32x2 w; w.x = cvt_pk_bf16(o[0], o[1]); w.y = cvt_pk_bf16(o[2], o[3]);
;                         *(u32x2*)(dst + (size_t)row * ld + bj * 128 + 4 * n) = w; }
.LBB0_375:
	v_mov_b32_e32 v224, v150
	v_mov_b32_e32 v225, v146
	v_pk_mul_f32 v[224:225], v[166:167], v[224:225]
	v_mov_b32_e32 v173, v158
	v_add_f32_e32 v146, v142, v225
	v_add_f32_e32 v146, v224, v146
	v_pk_mul_f32 v[172:173], v[168:169], v[172:173]
	v_mov_b32_e32 v165, v159
	v_add_f32_e32 v146, v173, v146
	v_add_f32_e32 v150, v172, v146
	v_mul_f32_e32 v146, 0xbfb8aa3b, v150
	v_exp_f32_e32 v146, v146
	v_mov_b32_e32 v157, v160
	s_mov_b64 s[2:3], -1
	s_and_b64 vcc, exec, s[18:19]
	v_add_f32_e32 v146, 1.0, v146
	v_rcp_f32_e32 v155, v146
	v_mov_b32_e32 v146, v151
	v_pk_mul_f32 v[146:147], v[134:135], v[146:147]
	v_mov_b32_e32 v172, v94
	v_add_f32_e32 v147, v143, v147
	v_add_f32_e32 v151, v146, v147
	v_pk_mul_f32 v[146:147], v[138:139], v[164:165]
	v_mov_b32_e32 v164, v95
	v_add_f32_e32 v147, v147, v151
	v_add_f32_e32 v151, v146, v147
	v_mul_f32_e32 v146, 0xbfb8aa3b, v151
	v_exp_f32_e32 v146, v146
	v_mul_f32_e32 v147, v150, v155
	v_cndmask_b32_e64 v150, v147, v150, s[4:5]
	v_mov_b32_e32 v147, v148
	v_add_f32_e32 v146, 1.0, v146
	v_rcp_f32_e32 v158, v146
	v_mov_b32_e32 v146, v152
	v_pk_mul_f32 v[146:147], v[162:163], v[146:147]
	v_mov_b32_e32 v155, v161
	v_add_f32_e32 v147, v144, v147
	v_add_f32_e32 v148, v146, v147
	v_pk_mul_f32 v[146:147], v[170:171], v[156:157]
	s_nop 0
	v_add_f32_e32 v147, v147, v148
	v_add_f32_e32 v152, v146, v147
	v_mul_f32_e32 v146, 0xbfb8aa3b, v152
	v_mov_b32_e32 v148, v153
	v_exp_f32_e32 v156, v146
	v_pk_mul_f32 v[146:147], v[136:137], v[148:149]
	v_add_f32_e32 v149, 1.0, v156
	v_add_f32_e32 v147, v145, v147
	v_add_f32_e32 v148, v146, v147
	v_pk_mul_f32 v[146:147], v[140:141], v[154:155]
	v_rcp_f32_e32 v149, v149
	v_add_f32_e32 v147, v147, v148
	v_add_f32_e32 v146, v146, v147
	v_mul_f32_e32 v147, 0xbfb8aa3b, v146
	v_exp_f32_e32 v147, v147
	v_mul_f32_e32 v148, v151, v158
	v_mul_f32_e32 v149, v152, v149
	v_cndmask_b32_e64 v148, v148, v151, s[4:5]
	v_add_f32_e32 v147, 1.0, v147
	v_rcp_f32_e32 v147, v147
	v_cndmask_b32_e64 v149, v149, v152, s[4:5]
	v_mov_b32_e32 v156, v96
	v_mov_b32_e32 v154, v97
	v_mul_f32_e32 v147, v146, v147
	v_cndmask_b32_e64 v147, v147, v146, s[4:5]
	v_cvt_pk_bf16_f32 v146, v150, v148
	v_cvt_pk_bf16_f32 v147, v149, v147
	v_lshlrev_b64 v[148:149], v182, v[200:201]
	v_lshl_add_u64 v[224:225], v[148:149], 1, v[220:221]
	v_mov_b32_e32 v122, v146
	v_mov_b32_e32 v123, v147
	s_cbranch_vccnz .LBB0_417
	v_add_u32_e32 v147, 0xffffe020, v202
	v_ashrrev_i32_e32 v147, 2, v147
	v_lshl_add_u32 v147, v147, 1, v147
	v_mad_i64_i32 v[148:149], s[2:3], v147, s47, 0
	v_lshl_add_u64 v[148:149], v[148:149], 2, v[208:209]
	v_lshl_add_u64 v[150:151], v[148:149], 0, s[24:25]
	s_lshl_b32 s2, s27, 2
	s_mov_b32 s3, s25
	global_load_dwordx4 v[158:161], v[148:149], off
	s_nop 0
	global_load_dwordx4 v[150:153], v[150:151], off
	v_lshl_add_u64 v[148:149], v[148:149], 0, s[2:3]
	global_load_dwordx4 v[154:157], v[148:149], off
	v_mov_b32_e32 v164, 0
	v_mov_b32_e32 v165, 0
	v_mov_b32_e32 v146, 0
	v_mov_b32_dpp v164, v94 row_ror:1 row_mask:0xf bank_mask:0xf
	v_mov_b32_dpp v165, v94 row_ror:2 row_mask:0xf bank_mask:0xf
	v_mov_b32_dpp v146, v94 row_ror:3 row_mask:0xf bank_mask:0xf
	v_cmp_lt_i32_e32 vcc, 1, v205
	s_and_saveexec_b64 s[2:3], vcc
	s_xor_b64 s[2:3], exec, s[2:3]
	s_cbranch_execz .LBB0_380
	v_cmp_gt_i32_e32 vcc, 3, v205
	s_and_saveexec_b64 s[80:81], vcc
	s_cbranch_execz .LBB0_379
	s_waitcnt vmcnt(0)
	v_mov_b32_e32 v146, v154

; __device__ __forceinline__ unsigned cvt_pk_bf16(float lo, float hi) { unsigned r; asm("v_cvt_pk_bf16_f32 %0, %1, %2" : "=v"(r) : "v"(lo), "v"(hi)); return r; }
; __device__ __forceinline__ float siluf_(float x) { return x * sigmoidf_(x); }
; __device__ __forceinline__ float dpp_ror1(float v) { return __builtin_bit_cast(float, __builtin_amdgcn_update_dpp(0, __builtin_bit_cast(int, v), 0x121, 0xf, 0xf, false)); }
;     __device__ __forceinline__ void operator()(f32x4 (&acc)[2][2][4][2], const pg8::Unit& u, int wr, int wc, int fr, int fq) const {
;     ...
;                 for (int n = 0; n < 2; ++n) { const int ch = ch0 + bj * 128 + 4 * n;
;                     const f32x4 w0 = *(const f32x4*)(cw + ch), w1 = *(const f32x4*)(cw + CW + ch), w2 = *(const f32x4*)(cw + 2 * CW + ch), w3 = *(const f32x4*)(cw + 3 * CW + ch), bb = *(const f32x4*)(cb + ch);
; #pragma unroll
;                     for (int m = 0; m < 4; ++m) { const int row = row0 + ai * 128 + m * 16; const f32x4 g = acc[ai][bj][m][n]; f32x4 p1, p2, p3;
;                         if (prompt) { const f32x4 gp = (m == 0) ? hal[n] : acc[ai][bj][m > 0 ? m - 1 : 0][n];
; #pragma unroll
;                             for (int j = 0; j < 4; ++j) { p1[j] = dpp_ror1(fr == 15 ? gp[j] : g[j]); p2[j] = dpp_ror2(fr >= 14 ? gp[j] : g[j]); p3[j] = dpp_ror3(fr >= 13 ? gp[j] : g[j]); } }
;                         else { const int t = fr & 3; const float* sp = stp + (size_t)((row - MP) >> 2) * 3 * CW + ch;
;                             const f32x4 b0 = *(const f32x4*)sp, b1 = *(const f32x4*)(sp + CW), b2 = *(const f32x4*)(sp + 2 * CW);
; #pragma unroll
;                             for (int j = 0; j < 4; ++j) { const float r1 = dpp_ror1(g[j]), r2 = dpp_ror2(g[j]), r3 = dpp_ror3(g[j]);
;                                 p1[j] = t >= 1 ? r1 : b2[j]; p2[j] = t >= 2 ? r2 : (t == 1 ? b2[j] : b1[j]); p3[j] = t >= 3 ? r3 : (t == 2 ? b2[j] : (t == 1 ? b1[j] : b0[j])); } }
;                         float o[4];
; #pragma unroll
;                         for (int j = 0; j < 4; ++j) { const float y = bb[j] + w0[j] * p3[j] + w1[j] * p2[j] + w2[j] * p1[j] + w3[j] * g[j]; o[j] = is_rg ? y : siluf_(y); }
;                         u32x2 w; w.x = cvt_pk_bf16(o[0], o[1]); w.y = cvt_pk_bf16(o[2], o[3]);
;                         *(u32x2*)(dst + (size_t)row * ld + bj * 128 + 4 * n) = w; }
.LBB0_419:
	v_mov_b32_e32 v226, v150
	v_mov_b32_e32 v227, v146
	v_pk_mul_f32 v[226:227], v[166:167], v[226:227]
	v_mov_b32_e32 v173, v158
	v_add_f32_e32 v146, v142, v227
	v_add_f32_e32 v146, v226, v146
	v_pk_mul_f32 v[172:173], v[168:169], v[172:173]
	v_mov_b32_e32 v165, v159
	v_add_f32_e32 v146, v173, v146
	v_add_f32_e32 v150, v172, v146
	v_mul_f32_e32 v146, 0xbfb8aa3b, v150
	v_exp_f32_e32 v146, v146
	v_mov_b32_e32 v157, v160
	s_mov_b64 s[2:3], -1
	s_and_b64 vcc, exec, s[18:19]
	v_add_f32_e32 v146, 1.0, v146
	v_rcp_f32_e32 v155, v146
	v_mov_b32_e32 v146, v151
	v_pk_mul_f32 v[146:147], v[134:135], v[146:147]
	v_mov_b32_e32 v172, v78
	v_add_f32_e32 v147, v143, v147
	v_add_f32_e32 v151, v146, v147
	v_pk_mul_f32 v[146:147], v[138:139], v[164:165]
	v_mov_b32_e32 v164, v79
	v_add_f32_e32 v147, v147, v151
	v_add_f32_e32 v151, v146, v147
	v_mul_f32_e32 v146, 0xbfb8aa3b, v151
	v_exp_f32_e32 v146, v146
	v_mul_f32_e32 v147, v150, v155
	v_cndmask_b32_e64 v150, v147, v150, s[4:5]
	v_mov_b32_e32 v147, v148
	v_add_f32_e32 v146, 1.0, v146
	v_rcp_f32_e32 v158, v146
	v_mov_b32_e32 v146, v152
	v_pk_mul_f32 v[146:147], v[162:163], v[146:147]
	v_mov_b32_e32 v155, v161
	v_add_f32_e32 v147, v144, v147
	v_add_f32_e32 v148, v146, v147
	v_pk_mul_f32 v[146:147], v[170:171], v[156:157]
	s_nop 0
	v_add_f32_e32 v147, v147, v148
	v_add_f32_e32 v152, v146, v147
	v_mul_f32_e32 v146, 0xbfb8aa3b, v152
	v_mov_b32_e32 v148, v153
	v_exp_f32_e32 v156, v146
	v_pk_mul_f32 v[146:147], v[136:137], v[148:149]
	v_add_f32_e32 v149, 1.0, v156
	v_add_f32_e32 v147, v145, v147
	v_add_f32_e32 v148, v146, v147
	v_pk_mul_f32 v[146:147], v[140:141], v[154:155]
	v_rcp_f32_e32 v149, v149
	v_add_f32_e32 v147, v147, v148
	v_add_f32_e32 v146, v146, v147
	v_mul_f32_e32 v147, 0xbfb8aa3b, v146
	v_exp_f32_e32 v147, v147
	v_mul_f32_e32 v148, v151, v158
	v_mul_f32_e32 v149, v152, v149
	v_cndmask_b32_e64 v148, v148, v151, s[4:5]
	v_add_f32_e32 v147, 1.0, v147
	v_rcp_f32_e32 v147, v147
	v_cndmask_b32_e64 v149, v149, v152, s[4:5]
	v_mov_b32_e32 v156, v80
	v_mov_b32_e32 v154, v81
	v_mul_f32_e32 v147, v146, v147
	v_cndmask_b32_e64 v147, v147, v146, s[4:5]
	v_cvt_pk_bf16_f32 v146, v150, v148
	v_cvt_pk_bf16_f32 v147, v149, v147
	v_lshlrev_b64 v[148:149], v182, v[198:199]
	v_lshl_add_u64 v[226:227], v[148:149], 1, v[220:221]
	v_mov_b32_e32 v110, v146
	v_mov_b32_e32 v111, v147
	s_cbranch_vccnz .LBB0_461
	v_add_u32_e32 v147, 0xffffe030, v202
	v_ashrrev_i32_e32 v147, 2, v147
	v_lshl_add_u32 v147, v147, 1, v147
	v_mad_i64_i32 v[148:149], s[2:3], v147, s47, 0
	v_lshl_add_u64 v[148:149], v[148:149], 2, v[208:209]
	v_lshl_add_u64 v[150:151], v[148:149], 0, s[24:25]
	s_lshl_b32 s2, s27, 2
	s_mov_b32 s3, s25
	global_load_dwordx4 v[158:161], v[148:149], off
	s_nop 0
	global_load_dwordx4 v[150:153], v[150:151], off
	v_lshl_add_u64 v[148:149], v[148:149], 0, s[2:3]
	global_load_dwordx4 v[154:157], v[148:149], off
	v_mov_b32_e32 v164, 0
	v_mov_b32_e32 v165, 0
	v_mov_b32_e32 v146, 0
	v_mov_b32_dpp v164, v78 row_ror:1 row_mask:0xf bank_mask:0xf
	v_mov_b32_dpp v165, v78 row_ror:2 row_mask:0xf bank_mask:0xf
	v_mov_b32_dpp v146, v78 row_ror:3 row_mask:0xf bank_mask:0xf
	v_cmp_lt_i32_e32 vcc, 1, v205
	s_and_saveexec_b64 s[2:3], vcc
	s_xor_b64 s[2:3], exec, s[2:3]
	s_cbranch_execz .LBB0_424
	v_cmp_gt_i32_e32 vcc, 3, v205
	s_and_saveexec_b64 s[80:81], vcc
	s_cbranch_execz .LBB0_423
	s_waitcnt vmcnt(0)
	v_mov_b32_e32 v146, v154

; __device__ __forceinline__ unsigned cvt_pk_bf16(float lo, float hi) { unsigned r; asm("v_cvt_pk_bf16_f32 %0, %1, %2" : "=v"(r) : "v"(lo), "v"(hi)); return r; }
; __device__ __forceinline__ float siluf_(float x) { return x * sigmoidf_(x); }
; __device__ __forceinline__ float dpp_ror1(float v) { return __builtin_bit_cast(float, __builtin_amdgcn_update_dpp(0, __builtin_bit_cast(int, v), 0x121, 0xf, 0xf, false)); }
;     __device__ __forceinline__ void operator()(f32x4 (&acc)[2][2][4][2], const pg8::Unit& u, int wr, int wc, int fr, int fq) const {
;     ...
;                 for (int n = 0; n < 2; ++n) { const int ch = ch0 + bj * 128 + 4 * n;
;                     const f32x4 w0 = *(const f32x4*)(cw + ch), w1 = *(const f32x4*)(cw + CW + ch), w2 = *(const f32x4*)(cw + 2 * CW + ch), w3 = *(const f32x4*)(cw + 3 * CW + ch), bb = *(const f32x4*)(cb + ch);
; #pragma unroll
;                     for (int m = 0; m < 4; ++m) { const int row = row0 + ai * 128 + m * 16; const f32x4 g = acc[ai][bj][m][n]; f32x4 p1, p2, p3;
;                         if (prompt) { const f32x4 gp = (m == 0) ? hal[n] : acc[ai][bj][m > 0 ? m - 1 : 0][n];
; #pragma unroll
;                             for (int j = 0; j < 4; ++j) { p1[j] = dpp_ror1(fr == 15 ? gp[j] : g[j]); p2[j] = dpp_ror2(fr >= 14 ? gp[j] : g[j]); p3[j] = dpp_ror3(fr >= 13 ? gp[j] : g[j]); } }
;                         else { const int t = fr & 3; const float* sp = stp + (size_t)((row - MP) >> 2) * 3 * CW + ch;
;                             const f32x4 b0 = *(const f32x4*)sp, b1 = *(const f32x4*)(sp + CW), b2 = *(const f32x4*)(sp + 2 * CW);
; #pragma unroll
;                             for (int j = 0; j < 4; ++j) { const float r1 = dpp_ror1(g[j]), r2 = dpp_ror2(g[j]), r3 = dpp_ror3(g[j]);
;                                 p1[j] = t >= 1 ? r1 : b2[j]; p2[j] = t >= 2 ? r2 : (t == 1 ? b2[j] : b1[j]); p3[j] = t >= 3 ? r3 : (t == 2 ? b2[j] : (t == 1 ? b1[j] : b0[j])); } }
;                         float o[4];
; #pragma unroll
;                         for (int j = 0; j < 4; ++j) { const float y = bb[j] + w0[j] * p3[j] + w1[j] * p2[j] + w2[j] * p1[j] + w3[j] * g[j]; o[j] = is_rg ? y : siluf_(y); }
;                         u32x2 w; w.x = cvt_pk_bf16(o[0], o[1]); w.y = cvt_pk_bf16(o[2], o[3]);
;                         *(u32x2*)(dst + (size_t)row * ld + bj * 128 + 4 * n) = w; }
.LBB0_463:
	v_mov_b32_e32 v228, v150
	v_mov_b32_e32 v229, v146
	v_pk_mul_f32 v[166:167], v[166:167], v[228:229]
	v_mov_b32_e32 v173, v158
	v_add_f32_e32 v142, v142, v167
	v_add_f32_e32 v142, v166, v142
	v_pk_mul_f32 v[166:167], v[168:169], v[172:173]
	v_mov_b32_e32 v165, v159
	v_add_f32_e32 v142, v167, v142
	v_add_f32_e32 v142, v166, v142
	v_mul_f32_e32 v146, 0xbfb8aa3b, v142
	v_exp_f32_e32 v146, v146
	v_mov_b32_e32 v157, v160
	v_mov_b32_e32 v155, v161
	s_mov_b64 s[2:3], -1
	v_add_f32_e32 v146, 1.0, v146
	v_rcp_f32_e32 v150, v146
	v_mov_b32_e32 v146, v151
	v_pk_mul_f32 v[134:135], v[134:135], v[146:147]
	s_and_b64 vcc, exec, s[18:19]
	v_add_f32_e32 v135, v143, v135
	v_add_f32_e32 v143, v134, v135
	v_pk_mul_f32 v[134:135], v[138:139], v[164:165]
	v_mov_b32_e32 v234, v126
	v_add_f32_e32 v135, v135, v143
	v_add_f32_e32 v138, v134, v135
	v_mul_f32_e32 v134, 0xbfb8aa3b, v138
	v_exp_f32_e32 v134, v134
	v_mul_f32_e32 v135, v142, v150
	v_cndmask_b32_e64 v139, v135, v142, s[4:5]
	v_mov_b32_e32 v135, v148
	v_add_f32_e32 v134, 1.0, v134
	v_rcp_f32_e32 v142, v134
	v_mov_b32_e32 v134, v152
	v_pk_mul_f32 v[134:135], v[162:163], v[134:135]
	v_mov_b32_e32 v148, v153
	v_add_f32_e32 v135, v144, v135
	v_add_f32_e32 v143, v134, v135
	v_pk_mul_f32 v[134:135], v[170:171], v[156:157]
	v_mov_b32_e32 v232, v127
	v_add_f32_e32 v135, v135, v143
	v_add_f32_e32 v143, v134, v135
	v_mul_f32_e32 v134, 0xbfb8aa3b, v143
	v_exp_f32_e32 v144, v134
	v_pk_mul_f32 v[134:135], v[136:137], v[148:149]
	v_mov_b32_e32 v172, v128
	v_add_f32_e32 v135, v145, v135
	v_add_f32_e32 v136, v134, v135
	v_pk_mul_f32 v[134:135], v[140:141], v[154:155]
	v_add_f32_e32 v137, 1.0, v144
	v_add_f32_e32 v135, v135, v136
	v_add_f32_e32 v134, v134, v135
	v_mul_f32_e32 v135, 0xbfb8aa3b, v134
	v_exp_f32_e32 v135, v135
	v_rcp_f32_e32 v137, v137
	v_mul_f32_e32 v136, v138, v142
	v_cndmask_b32_e64 v136, v136, v138, s[4:5]
	v_add_f32_e32 v135, 1.0, v135
	v_rcp_f32_e32 v135, v135
	v_mul_f32_e32 v137, v143, v137
	v_cndmask_b32_e64 v137, v137, v143, s[4:5]
	v_mov_b32_e32 v170, v129
	v_mul_f32_e32 v135, v134, v135
	v_cndmask_b32_e64 v135, v135, v134, s[4:5]
	v_cvt_pk_bf16_f32 v134, v139, v136
	v_cvt_pk_bf16_f32 v135, v137, v135
	v_lshlrev_b64 v[136:137], v182, v[196:197]
	v_lshl_add_u64 v[228:229], v[136:137], 1, v[220:221]
	v_mov_b32_e32 v94, v134
	v_mov_b32_e32 v95, v135
	global_load_dwordx4 v[138:141], v[210:211], off offset:16
	global_load_dwordx4 v[150:153], v[212:213], off offset:16
	global_load_dwordx4 v[134:137], v[214:215], off offset:16
	global_load_dwordx4 v[146:149], v[216:217], off offset:16
	global_load_dwordx4 v[142:145], v[218:219], off offset:16
	s_cbranch_vccnz .LBB0_505
	v_add_u32_e32 v155, 0xffffe000, v202
	v_ashrrev_i32_e32 v155, 2, v155
	v_lshl_add_u32 v155, v155, 1, v155
	v_mad_i64_i32 v[156:157], s[2:3], v155, s47, 0
	v_lshl_add_u64 v[156:157], v[156:157], 2, v[208:209]
	v_lshl_add_u64 v[158:159], v[156:157], 0, s[24:25]
	s_lshl_b32 s2, s27, 2
	s_mov_b32 s3, s25
	global_load_dwordx4 v[166:169], v[156:157], off offset:16
	s_nop 0
	global_load_dwordx4 v[158:161], v[158:159], off offset:16
	v_lshl_add_u64 v[156:157], v[156:157], 0, s[2:3]
	global_load_dwordx4 v[162:165], v[156:157], off offset:16
	v_mov_b32_e32 v170, 0
	v_mov_b32_e32 v171, 0
	v_mov_b32_e32 v154, 0
	v_mov_b32_dpp v170, v126 row_ror:1 row_mask:0xf bank_mask:0xf
	v_mov_b32_dpp v171, v126 row_ror:2 row_mask:0xf bank_mask:0xf
	v_mov_b32_dpp v154, v126 row_ror:3 row_mask:0xf bank_mask:0xf
	v_cmp_lt_i32_e32 vcc, 1, v205
	s_and_saveexec_b64 s[2:3], vcc
	s_xor_b64 s[2:3], exec, s[2:3]
	s_cbranch_execz .LBB0_468
	v_cmp_gt_i32_e32 vcc, 3, v205
	s_and_saveexec_b64 s[80:81], vcc
	s_cbranch_execz .LBB0_467
	s_waitcnt vmcnt(0)
	v_mov_b32_e32 v154, v162

; __device__ __forceinline__ unsigned cvt_pk_bf16(float lo, float hi) { unsigned r; asm("v_cvt_pk_bf16_f32 %0, %1, %2" : "=v"(r) : "v"(lo), "v"(hi)); return r; }
; __device__ __forceinline__ float siluf_(float x) { return x * sigmoidf_(x); }
; __device__ __forceinline__ float dpp_ror1(float v) { return __builtin_bit_cast(float, __builtin_amdgcn_update_dpp(0, __builtin_bit_cast(int, v), 0x121, 0xf, 0xf, false)); }
;     __device__ __forceinline__ void operator()(f32x4 (&acc)[2][2][4][2], const pg8::Unit& u, int wr, int wc, int fr, int fq) const {
;     ...
;                 for (int n = 0; n < 2; ++n) { const int ch = ch0 + bj * 128 + 4 * n;
;                     const f32x4 w0 = *(const f32x4*)(cw + ch), w1 = *(const f32x4*)(cw + CW + ch), w2 = *(const f32x4*)(cw + 2 * CW + ch), w3 = *(const f32x4*)(cw + 3 * CW + ch), bb = *(const f32x4*)(cb + ch);
; #pragma unroll
;                     for (int m = 0; m < 4; ++m) { const int row = row0 + ai * 128 + m * 16; const f32x4 g = acc[ai][bj][m][n]; f32x4 p1, p2, p3;
;                         if (prompt) { const f32x4 gp = (m == 0) ? hal[n] : acc[ai][bj][m > 0 ? m - 1 : 0][n];
; #pragma unroll
;                             for (int j = 0; j < 4; ++j) { p1[j] = dpp_ror1(fr == 15 ? gp[j] : g[j]); p2[j] = dpp_ror2(fr >= 14 ? gp[j] : g[j]); p3[j] = dpp_ror3(fr >= 13 ? gp[j] : g[j]); } }
;                         else { const int t = fr & 3; const float* sp = stp + (size_t)((row - MP) >> 2) * 3 * CW + ch;
;                             const f32x4 b0 = *(const f32x4*)sp, b1 = *(const f32x4*)(sp + CW), b2 = *(const f32x4*)(sp + 2 * CW);
; #pragma unroll
;                             for (int j = 0; j < 4; ++j) { const float r1 = dpp_ror1(g[j]), r2 = dpp_ror2(g[j]), r3 = dpp_ror3(g[j]);
;                                 p1[j] = t >= 1 ? r1 : b2[j]; p2[j] = t >= 2 ? r2 : (t == 1 ? b2[j] : b1[j]); p3[j] = t >= 3 ? r3 : (t == 2 ? b2[j] : (t == 1 ? b1[j] : b0[j])); } }
;                         float o[4];
; #pragma unroll
;                         for (int j = 0; j < 4; ++j) { const float y = bb[j] + w0[j] * p3[j] + w1[j] * p2[j] + w2[j] * p1[j] + w3[j] * g[j]; o[j] = is_rg ? y : siluf_(y); }
;                         u32x2 w; w.x = cvt_pk_bf16(o[0], o[1]); w.y = cvt_pk_bf16(o[2], o[3]);
;                         *(u32x2*)(dst + (size_t)row * ld + bj * 128 + 4 * n) = w; }
.LBB0_551:
	v_mov_b32_e32 v170, v146
	v_mov_b32_e32 v171, v130
	v_pk_mul_f32 v[170:171], v[162:163], v[170:171]
	v_mov_b32_e32 v169, v154
	v_add_f32_e32 v130, v142, v171
	v_add_f32_e32 v130, v170, v130
	v_pk_mul_f32 v[168:169], v[164:165], v[168:169]
	v_mov_b32_e32 v161, v155
	v_add_f32_e32 v130, v169, v130
	v_add_f32_e32 v146, v168, v130
	v_mul_f32_e32 v130, 0xbfb8aa3b, v146
	v_exp_f32_e32 v130, v130
	v_mov_b32_e32 v153, v156
	s_mov_b64 s[2:3], -1
	s_and_b64 vcc, exec, s[18:19]
	v_add_f32_e32 v130, 1.0, v130
	v_rcp_f32_e32 v151, v130
	v_mov_b32_e32 v130, v147
	v_pk_mul_f32 v[130:131], v[138:139], v[130:131]
	v_mov_b32_e32 v168, v90
	v_add_f32_e32 v131, v143, v131
	v_add_f32_e32 v147, v130, v131
	v_pk_mul_f32 v[130:131], v[134:135], v[160:161]
	v_mov_b32_e32 v160, v91
	v_add_f32_e32 v131, v131, v147
	v_add_f32_e32 v147, v130, v131
	v_mul_f32_e32 v130, 0xbfb8aa3b, v147
	v_exp_f32_e32 v130, v130
	v_mul_f32_e32 v131, v146, v151
	v_cndmask_b32_e64 v146, v131, v146, s[4:5]
	v_mov_b32_e32 v131, v132
	v_add_f32_e32 v130, 1.0, v130
	v_rcp_f32_e32 v154, v130
	v_mov_b32_e32 v130, v148
	v_pk_mul_f32 v[130:131], v[158:159], v[130:131]
	v_mov_b32_e32 v151, v157
	v_add_f32_e32 v131, v144, v131
	v_add_f32_e32 v132, v130, v131
	v_pk_mul_f32 v[130:131], v[166:167], v[152:153]
	s_nop 0
	v_add_f32_e32 v131, v131, v132
	v_add_f32_e32 v148, v130, v131
	v_mul_f32_e32 v130, 0xbfb8aa3b, v148
	v_mov_b32_e32 v132, v149
	v_exp_f32_e32 v152, v130
	v_pk_mul_f32 v[130:131], v[140:141], v[132:133]
	v_add_f32_e32 v133, 1.0, v152
	v_add_f32_e32 v131, v145, v131
	v_add_f32_e32 v132, v130, v131
	v_pk_mul_f32 v[130:131], v[136:137], v[150:151]
	v_rcp_f32_e32 v133, v133
	v_add_f32_e32 v131, v131, v132
	v_add_f32_e32 v130, v130, v131
	v_mul_f32_e32 v131, 0xbfb8aa3b, v130
	v_exp_f32_e32 v131, v131
	v_mul_f32_e32 v132, v147, v154
	v_mul_f32_e32 v133, v148, v133
	v_cndmask_b32_e64 v132, v132, v147, s[4:5]
	v_add_f32_e32 v131, 1.0, v131
	v_rcp_f32_e32 v131, v131
	v_cndmask_b32_e64 v133, v133, v148, s[4:5]
	v_mov_b32_e32 v152, v92
	v_mov_b32_e32 v150, v93
	v_mul_f32_e32 v131, v130, v131
	v_cndmask_b32_e64 v131, v131, v130, s[4:5]
	v_cvt_pk_bf16_f32 v130, v146, v132
	v_cvt_pk_bf16_f32 v131, v133, v131
	v_mov_b32_e32 v124, v130
	v_mov_b32_e32 v125, v131
	flat_store_dwordx4 v[224:225], v[122:125]
	s_cbranch_vccnz .LBB0_593
	v_add_u32_e32 v131, 0xffffe020, v202
	v_ashrrev_i32_e32 v131, 2, v131
	v_lshl_add_u32 v131, v131, 1, v131
	v_mad_i64_i32 v[132:133], s[2:3], v131, s47, 0
	v_lshl_add_u64 v[132:133], v[132:133], 2, v[208:209]
	v_lshl_add_u64 v[146:147], v[132:133], 0, s[24:25]
	s_lshl_b32 s2, s27, 2
	s_mov_b32 s3, s25
	global_load_dwordx4 v[154:157], v[132:133], off offset:16
	s_nop 0
	global_load_dwordx4 v[146:149], v[146:147], off offset:16
	v_lshl_add_u64 v[132:133], v[132:133], 0, s[2:3]
	global_load_dwordx4 v[150:153], v[132:133], off offset:16
	v_mov_b32_e32 v160, 0
	v_mov_b32_e32 v161, 0
	v_mov_b32_e32 v130, 0
	v_mov_b32_dpp v160, v90 row_ror:1 row_mask:0xf bank_mask:0xf
	v_mov_b32_dpp v161, v90 row_ror:2 row_mask:0xf bank_mask:0xf
	v_mov_b32_dpp v130, v90 row_ror:3 row_mask:0xf bank_mask:0xf
	v_cmp_lt_i32_e32 vcc, 1, v205
	s_and_saveexec_b64 s[2:3], vcc
	s_xor_b64 s[2:3], exec, s[2:3]
	s_cbranch_execz .LBB0_556
	v_cmp_gt_i32_e32 vcc, 3, v205
	s_and_saveexec_b64 s[80:81], vcc
	s_cbranch_execz .LBB0_555
	s_waitcnt vmcnt(0)
	v_mov_b32_e32 v130, v150

; __device__ __forceinline__ unsigned cvt_pk_bf16(float lo, float hi) { unsigned r; asm("v_cvt_pk_bf16_f32 %0, %1, %2" : "=v"(r) : "v"(lo), "v"(hi)); return r; }
; __device__ __forceinline__ float siluf_(float x) { return x * sigmoidf_(x); }
; __device__ __forceinline__ float dpp_ror1(float v) { return __builtin_bit_cast(float, __builtin_amdgcn_update_dpp(0, __builtin_bit_cast(int, v), 0x121, 0xf, 0xf, false)); }
;     __device__ __forceinline__ void operator()(f32x4 (&acc)[2][2][4][2], const pg8::Unit& u, int wr, int wc, int fr, int fq) const {
;     ...
;                 for (int n = 0; n < 2; ++n) { const int ch = ch0 + bj * 128 + 4 * n;
;                     const f32x4 w0 = *(const f32x4*)(cw + ch), w1 = *(const f32x4*)(cw + CW + ch), w2 = *(const f32x4*)(cw + 2 * CW + ch), w3 = *(const f32x4*)(cw + 3 * CW + ch), bb = *(const f32x4*)(cb + ch);
; #pragma unroll
;                     for (int m = 0; m < 4; ++m) { const int row = row0 + ai * 128 + m * 16; const f32x4 g = acc[ai][bj][m][n]; f32x4 p1, p2, p3;
;                         if (prompt) { const f32x4 gp = (m == 0) ? hal[n] : acc[ai][bj][m > 0 ? m - 1 : 0][n];
; #pragma unroll
;                             for (int j = 0; j < 4; ++j) { p1[j] = dpp_ror1(fr == 15 ? gp[j] : g[j]); p2[j] = dpp_ror2(fr >= 14 ? gp[j] : g[j]); p3[j] = dpp_ror3(fr >= 13 ? gp[j] : g[j]); } }
;                         else { const int t = fr & 3; const float* sp = stp + (size_t)((row - MP) >> 2) * 3 * CW + ch;
;                             const f32x4 b0 = *(const f32x4*)sp, b1 = *(const f32x4*)(sp + CW), b2 = *(const f32x4*)(sp + 2 * CW);
; #pragma unroll
;                             for (int j = 0; j < 4; ++j) { const float r1 = dpp_ror1(g[j]), r2 = dpp_ror2(g[j]), r3 = dpp_ror3(g[j]);
;                                 p1[j] = t >= 1 ? r1 : b2[j]; p2[j] = t >= 2 ? r2 : (t == 1 ? b2[j] : b1[j]); p3[j] = t >= 3 ? r3 : (t == 2 ? b2[j] : (t == 1 ? b1[j] : b0[j])); } }
;                         float o[4];
; #pragma unroll
;                         for (int j = 0; j < 4; ++j) { const float y = bb[j] + w0[j] * p3[j] + w1[j] * p2[j] + w2[j] * p1[j] + w3[j] * g[j]; o[j] = is_rg ? y : siluf_(y); }
;                         u32x2 w; w.x = cvt_pk_bf16(o[0], o[1]); w.y = cvt_pk_bf16(o[2], o[3]);
;                         *(u32x2*)(dst + (size_t)row * ld + bj * 128 + 4 * n) = w; }
.LBB0_595:
	v_mov_b32_e32 v170, v146
	v_mov_b32_e32 v171, v130
	v_pk_mul_f32 v[170:171], v[162:163], v[170:171]
	v_mov_b32_e32 v169, v154
	v_add_f32_e32 v130, v142, v171
	v_add_f32_e32 v130, v170, v130
	v_pk_mul_f32 v[168:169], v[164:165], v[168:169]
	v_mov_b32_e32 v161, v155
	v_add_f32_e32 v130, v169, v130
	v_add_f32_e32 v146, v168, v130
	v_mul_f32_e32 v130, 0xbfb8aa3b, v146
	v_exp_f32_e32 v130, v130
	v_mov_b32_e32 v153, v156
	s_mov_b64 s[2:3], -1
	s_and_b64 vcc, exec, s[18:19]
	v_add_f32_e32 v130, 1.0, v130
	v_rcp_f32_e32 v151, v130
	v_mov_b32_e32 v130, v147
	v_pk_mul_f32 v[130:131], v[138:139], v[130:131]
	v_mov_b32_e32 v168, v74
	v_add_f32_e32 v131, v143, v131
	v_add_f32_e32 v147, v130, v131
	v_pk_mul_f32 v[130:131], v[134:135], v[160:161]
	v_mov_b32_e32 v160, v75
	v_add_f32_e32 v131, v131, v147
	v_add_f32_e32 v147, v130, v131
	v_mul_f32_e32 v130, 0xbfb8aa3b, v147
	v_exp_f32_e32 v130, v130
	v_mul_f32_e32 v131, v146, v151
	v_cndmask_b32_e64 v146, v131, v146, s[4:5]
	v_mov_b32_e32 v131, v132
	v_add_f32_e32 v130, 1.0, v130
	v_rcp_f32_e32 v154, v130
	v_mov_b32_e32 v130, v148
	v_pk_mul_f32 v[130:131], v[158:159], v[130:131]
	v_mov_b32_e32 v151, v157
	v_add_f32_e32 v131, v144, v131
	v_add_f32_e32 v132, v130, v131
	v_pk_mul_f32 v[130:131], v[166:167], v[152:153]
	s_nop 0
	v_add_f32_e32 v131, v131, v132
	v_add_f32_e32 v148, v130, v131
	v_mul_f32_e32 v130, 0xbfb8aa3b, v148
	v_mov_b32_e32 v132, v149
	v_exp_f32_e32 v152, v130
	v_pk_mul_f32 v[130:131], v[140:141], v[132:133]
	v_add_f32_e32 v133, 1.0, v152
	v_add_f32_e32 v131, v145, v131
	v_add_f32_e32 v132, v130, v131
	v_pk_mul_f32 v[130:131], v[136:137], v[150:151]
	v_rcp_f32_e32 v133, v133
	v_add_f32_e32 v131, v131, v132
	v_add_f32_e32 v130, v130, v131
	v_mul_f32_e32 v131, 0xbfb8aa3b, v130
	v_exp_f32_e32 v131, v131
	v_mul_f32_e32 v132, v147, v154
	v_mul_f32_e32 v133, v148, v133
	v_cndmask_b32_e64 v132, v132, v147, s[4:5]
	v_add_f32_e32 v131, 1.0, v131
	v_rcp_f32_e32 v131, v131
	v_cndmask_b32_e64 v133, v133, v148, s[4:5]
	v_mov_b32_e32 v152, v76
	v_mov_b32_e32 v150, v77
	v_mul_f32_e32 v131, v130, v131
	v_cndmask_b32_e64 v131, v131, v130, s[4:5]
	v_cvt_pk_bf16_f32 v130, v146, v132
	v_cvt_pk_bf16_f32 v131, v133, v131
	v_mov_b32_e32 v112, v130
	v_mov_b32_e32 v113, v131
	flat_store_dwordx4 v[226:227], v[110:113]
	s_cbranch_vccnz .LBB0_637
	v_add_u32_e32 v131, 0xffffe030, v202
	v_ashrrev_i32_e32 v131, 2, v131
	v_lshl_add_u32 v131, v131, 1, v131
	v_mad_i64_i32 v[132:133], s[2:3], v131, s47, 0
	v_lshl_add_u64 v[132:133], v[132:133], 2, v[208:209]
	v_lshl_add_u64 v[146:147], v[132:133], 0, s[24:25]
	s_lshl_b32 s2, s27, 2
	s_mov_b32 s3, s25
	global_load_dwordx4 v[154:157], v[132:133], off offset:16
	s_nop 0
	global_load_dwordx4 v[146:149], v[146:147], off offset:16
	v_lshl_add_u64 v[132:133], v[132:133], 0, s[2:3]
	global_load_dwordx4 v[150:153], v[132:133], off offset:16
	v_mov_b32_e32 v160, 0
	v_mov_b32_e32 v161, 0
	v_mov_b32_e32 v130, 0
	v_mov_b32_dpp v160, v74 row_ror:1 row_mask:0xf bank_mask:0xf
	v_mov_b32_dpp v161, v74 row_ror:2 row_mask:0xf bank_mask:0xf
	v_mov_b32_dpp v130, v74 row_ror:3 row_mask:0xf bank_mask:0xf
	v_cmp_lt_i32_e32 vcc, 1, v205
	s_and_saveexec_b64 s[2:3], vcc
	s_xor_b64 s[2:3], exec, s[2:3]
	s_cbranch_execz .LBB0_600
	v_cmp_gt_i32_e32 vcc, 3, v205
	s_and_saveexec_b64 s[80:81], vcc
	s_cbranch_execz .LBB0_599
	s_waitcnt vmcnt(0)
	v_mov_b32_e32 v130, v150

; __device__ __forceinline__ unsigned cvt_pk_bf16(float lo, float hi) { unsigned r; asm("v_cvt_pk_bf16_f32 %0, %1, %2" : "=v"(r) : "v"(lo), "v"(hi)); return r; }
; __device__ __forceinline__ float siluf_(float x) { return x * sigmoidf_(x); }
; __device__ __forceinline__ float dpp_ror1(float v) { return __builtin_bit_cast(float, __builtin_amdgcn_update_dpp(0, __builtin_bit_cast(int, v), 0x121, 0xf, 0xf, false)); }
;     __device__ __forceinline__ void operator()(f32x4 (&acc)[2][2][4][2], const pg8::Unit& u, int wr, int wc, int fr, int fq) const {
;     ...
;                 for (int n = 0; n < 2; ++n) { const int ch = ch0 + bj * 128 + 4 * n;
;                     const f32x4 w0 = *(const f32x4*)(cw + ch), w1 = *(const f32x4*)(cw + CW + ch), w2 = *(const f32x4*)(cw + 2 * CW + ch), w3 = *(const f32x4*)(cw + 3 * CW + ch), bb = *(const f32x4*)(cb + ch);
; #pragma unroll
;                     for (int m = 0; m < 4; ++m) { const int row = row0 + ai * 128 + m * 16; const f32x4 g = acc[ai][bj][m][n]; f32x4 p1, p2, p3;
;                         if (prompt) { const f32x4 gp = (m == 0) ? hal[n] : acc[ai][bj][m > 0 ? m - 1 : 0][n];
; #pragma unroll
;                             for (int j = 0; j < 4; ++j) { p1[j] = dpp_ror1(fr == 15 ? gp[j] : g[j]); p2[j] = dpp_ror2(fr >= 14 ? gp[j] : g[j]); p3[j] = dpp_ror3(fr >= 13 ? gp[j] : g[j]); } }
;                         else { const int t = fr & 3; const float* sp = stp + (size_t)((row - MP) >> 2) * 3 * CW + ch;
;                             const f32x4 b0 = *(const f32x4*)sp, b1 = *(const f32x4*)(sp + CW), b2 = *(const f32x4*)(sp + 2 * CW);
; #pragma unroll
;                             for (int j = 0; j < 4; ++j) { const float r1 = dpp_ror1(g[j]), r2 = dpp_ror2(g[j]), r3 = dpp_ror3(g[j]);
;                                 p1[j] = t >= 1 ? r1 : b2[j]; p2[j] = t >= 2 ? r2 : (t == 1 ? b2[j] : b1[j]); p3[j] = t >= 3 ? r3 : (t == 2 ? b2[j] : (t == 1 ? b1[j] : b0[j])); } }
;                         float o[4];
; #pragma unroll
;                         for (int j = 0; j < 4; ++j) { const float y = bb[j] + w0[j] * p3[j] + w1[j] * p2[j] + w2[j] * p1[j] + w3[j] * g[j]; o[j] = is_rg ? y : siluf_(y); }
;                         u32x2 w; w.x = cvt_pk_bf16(o[0], o[1]); w.y = cvt_pk_bf16(o[2], o[3]);
;                         *(u32x2*)(dst + (size_t)row * ld + bj * 128 + 4 * n) = w; }
.LBB0_639:
	v_mov_b32_e32 v170, v146
	v_mov_b32_e32 v171, v130
	v_pk_mul_f32 v[162:163], v[162:163], v[170:171]
	v_mov_b32_e32 v169, v154
	v_add_f32_e32 v130, v142, v163
	v_add_f32_e32 v130, v162, v130
	v_pk_mul_f32 v[162:163], v[164:165], v[168:169]
	v_mov_b32_e32 v161, v155
	v_add_f32_e32 v130, v163, v130
	v_add_f32_e32 v142, v162, v130
	v_mul_f32_e32 v130, 0xbfb8aa3b, v142
	v_exp_f32_e32 v130, v130
	v_mov_b32_e32 v153, v156
	v_mov_b32_e32 v151, v157
	s_and_b64 vcc, exec, s[20:21]
	v_add_f32_e32 v130, 1.0, v130
	v_rcp_f32_e32 v146, v130
	v_mov_b32_e32 v130, v147
	v_pk_mul_f32 v[130:131], v[138:139], v[130:131]
	v_mov_b32_e32 v147, 0
	v_add_f32_e32 v131, v143, v131
	v_add_f32_e32 v138, v130, v131
	v_pk_mul_f32 v[130:131], v[134:135], v[160:161]
	s_nop 0
	v_add_f32_e32 v131, v131, v138
	v_add_f32_e32 v134, v130, v131
	v_mul_f32_e32 v130, 0xbfb8aa3b, v134
	v_exp_f32_e32 v130, v130
	v_mul_f32_e32 v131, v142, v146
	v_cndmask_b32_e64 v135, v131, v142, s[4:5]
	v_mov_b32_e32 v131, v132
	v_add_f32_e32 v130, 1.0, v130
	v_rcp_f32_e32 v138, v130
	v_mov_b32_e32 v130, v148
	v_pk_mul_f32 v[130:131], v[158:159], v[130:131]
	v_mov_b32_e32 v146, 0
	v_add_f32_e32 v131, v144, v131
	v_add_f32_e32 v132, v130, v131
	v_pk_mul_f32 v[130:131], v[166:167], v[152:153]
	v_mov_b32_e32 v148, 0
	v_add_f32_e32 v131, v131, v132
	v_add_f32_e32 v139, v130, v131
	v_mul_f32_e32 v130, 0xbfb8aa3b, v139
	v_mov_b32_e32 v132, v149
	v_exp_f32_e32 v142, v130
	v_pk_mul_f32 v[130:131], v[140:141], v[132:133]
	v_mov_b32_e32 v149, 0
	v_add_f32_e32 v131, v145, v131
	v_add_f32_e32 v132, v130, v131
	v_pk_mul_f32 v[130:131], v[136:137], v[150:151]
	v_add_f32_e32 v133, 1.0, v142
	v_add_f32_e32 v131, v131, v132
	v_add_f32_e32 v130, v130, v131
	v_mul_f32_e32 v131, 0xbfb8aa3b, v130
	v_exp_f32_e32 v131, v131
	v_rcp_f32_e32 v133, v133
	v_mul_f32_e32 v132, v134, v138
	v_cndmask_b32_e64 v132, v132, v134, s[4:5]
	v_add_f32_e32 v131, 1.0, v131
	v_rcp_f32_e32 v131, v131
	v_mul_f32_e32 v133, v139, v133
	v_cndmask_b32_e64 v133, v133, v139, s[4:5]
	v_mul_f32_e32 v131, v130, v131
	v_cndmask_b32_e64 v131, v131, v130, s[4:5]
	v_cvt_pk_bf16_f32 v130, v135, v132
	v_cvt_pk_bf16_f32 v131, v133, v131
	v_mov_b32_e32 v96, v130
	v_mov_b32_e32 v97, v131
	flat_store_dwordx4 v[228:229], v[94:97]
	v_mov_b32_e32 v130, 0
	v_mov_b32_e32 v131, 0
	v_mov_b32_e32 v132, 0
	v_mov_b32_e32 v133, 0
	s_cbranch_vccnz .LBB0_663
	v_readlane_b32 s20, v255, 3
	v_readlane_b32 s21, v255, 4
	s_mov_b64 s[2:3], -1
	s_and_b64 vcc, exec, s[20:21]
	s_cbranch_vccz .LBB0_644
	v_mov_b32_e32 v149, 0
	v_mov_b32_e32 v148, 0
	v_mov_b32_e32 v147, 0
	v_mov_b32_e32 v146, 0
	v_mov_b32_e32 v133, 0
	v_mov_b32_e32 v132, 0
	v_mov_b32_e32 v131, 0
	v_mov_b32_e32 v130, 0
	s_and_saveexec_b64 s[2:3], s[6:7]
	s_cbranch_execz .LBB0_643
	v_readlane_b32 s20, v255, 19
	v_lshlrev_b32_e32 v131, 2, v206
	s_nop 0
	v_add_u32_e32 v130, s20, v236
	s_movk_i32 s20, 0xc200
	v_add3_u32 v130, v130, v131, s20
	ds_read_b128 v[146:149], v130
	ds_read_b128 v[130:133], v130 offset:16

; __device__ __forceinline__ unsigned cvt_pk_bf16(float lo, float hi) { unsigned r; asm("v_cvt_pk_bf16_f32 %0, %1, %2" : "=v"(r) : "v"(lo), "v"(hi)); return r; }
; __device__ __forceinline__ float siluf_(float x) { return x * sigmoidf_(x); }
; __device__ __forceinline__ float dpp_ror1(float v) { return __builtin_bit_cast(float, __builtin_amdgcn_update_dpp(0, __builtin_bit_cast(int, v), 0x121, 0xf, 0xf, false)); }
;     __device__ __forceinline__ void operator()(f32x4 (&acc)[2][2][4][2], const pg8::Unit& u, int wr, int wc, int fr, int fq) const {
;     ...
;                 for (int n = 0; n < 2; ++n) { const int ch = ch0 + bj * 128 + 4 * n;
;                     const f32x4 w0 = *(const f32x4*)(cw + ch), w1 = *(const f32x4*)(cw + CW + ch), w2 = *(const f32x4*)(cw + 2 * CW + ch), w3 = *(const f32x4*)(cw + 3 * CW + ch), bb = *(const f32x4*)(cb + ch);
; #pragma unroll
;                     for (int m = 0; m < 4; ++m) { const int row = row0 + ai * 128 + m * 16; const f32x4 g = acc[ai][bj][m][n]; f32x4 p1, p2, p3;
;                         if (prompt) { const f32x4 gp = (m == 0) ? hal[n] : acc[ai][bj][m > 0 ? m - 1 : 0][n];
; #pragma unroll
;                             for (int j = 0; j < 4; ++j) { p1[j] = dpp_ror1(fr == 15 ? gp[j] : g[j]); p2[j] = dpp_ror2(fr >= 14 ? gp[j] : g[j]); p3[j] = dpp_ror3(fr >= 13 ? gp[j] : g[j]); } }
;                         else { const int t = fr & 3; const float* sp = stp + (size_t)((row - MP) >> 2) * 3 * CW + ch;
;                             const f32x4 b0 = *(const f32x4*)sp, b1 = *(const f32x4*)(sp + CW), b2 = *(const f32x4*)(sp + 2 * CW);
; #pragma unroll
;                             for (int j = 0; j < 4; ++j) { const float r1 = dpp_ror1(g[j]), r2 = dpp_ror2(g[j]), r3 = dpp_ror3(g[j]);
;                                 p1[j] = t >= 1 ? r1 : b2[j]; p2[j] = t >= 2 ? r2 : (t == 1 ? b2[j] : b1[j]); p3[j] = t >= 3 ? r3 : (t == 2 ? b2[j] : (t == 1 ? b1[j] : b0[j])); } }
;                         float o[4];
; #pragma unroll
;                         for (int j = 0; j < 4; ++j) { const float y = bb[j] + w0[j] * p3[j] + w1[j] * p2[j] + w2[j] * p1[j] + w3[j] * g[j]; o[j] = is_rg ? y : siluf_(y); }
;                         u32x2 w; w.x = cvt_pk_bf16(o[0], o[1]); w.y = cvt_pk_bf16(o[2], o[3]);
;                         *(u32x2*)(dst + (size_t)row * ld + bj * 128 + 4 * n) = w; }
.LBB0_707:
	s_waitcnt vmcnt(0)
	v_mov_b32_e32 v166, v154
	v_mov_b32_e32 v167, v138
	s_waitcnt lgkmcnt(0)
	v_mov_b32_e32 v146, v162
	v_mov_b32_e32 v147, v158
	v_pk_mul_f32 v[146:147], v[166:167], v[146:147]
	v_mov_b32_e32 v168, v150
	v_add_f32_e32 v138, v142, v147
	v_mov_b32_e32 v169, v134
	v_mov_b32_e32 v237, v170
	v_add_f32_e32 v138, v146, v138
	v_pk_mul_f32 v[146:147], v[168:169], v[236:237]
	v_mov_b32_e32 v158, v163
	v_add_f32_e32 v134, v147, v138
	v_add_f32_e32 v148, v146, v134
	v_mul_f32_e32 v134, 0xbfb8aa3b, v148
	v_exp_f32_e32 v134, v134
	v_mov_b32_e32 v138, v155
	v_pk_mul_f32 v[146:147], v[138:139], v[158:159]
	v_mov_b32_e32 v235, v171
	v_add_f32_e32 v134, 1.0, v134
	v_rcp_f32_e32 v149, v134
	v_add_f32_e32 v134, v143, v147
	v_add_f32_e32 v150, v146, v134
	v_mov_b32_e32 v134, v151
	v_pk_mul_f32 v[146:147], v[134:135], v[234:235]
	v_mov_b32_e32 v162, v156
	v_add_f32_e32 v147, v147, v150
	v_add_f32_e32 v150, v146, v147
	v_mul_f32_e32 v146, 0xbfb8aa3b, v150
	v_exp_f32_e32 v146, v146
	v_mul_f32_e32 v147, v148, v149
	v_cndmask_b32_e64 v148, v147, v148, s[4:5]
	v_mov_b32_e32 v163, v140
	v_add_f32_e32 v146, 1.0, v146
	v_rcp_f32_e32 v149, v146
	v_mov_b32_e32 v146, v164
	v_mov_b32_e32 v147, v160
	v_pk_mul_f32 v[146:147], v[162:163], v[146:147]
	v_mov_b32_e32 v170, v152
	v_add_f32_e32 v140, v144, v147
	v_mov_b32_e32 v171, v136
	v_mov_b32_e32 v233, v172
	v_add_f32_e32 v140, v146, v140
	v_pk_mul_f32 v[146:147], v[170:171], v[232:233]
	v_mov_b32_e32 v160, v165
	v_add_f32_e32 v136, v147, v140
	v_add_f32_e32 v151, v146, v136
	v_mov_b32_e32 v140, v157
	v_mul_f32_e32 v136, 0xbfb8aa3b, v151
	v_pk_mul_f32 v[146:147], v[140:141], v[160:161]
	v_exp_f32_e32 v152, v136
	v_add_f32_e32 v136, v145, v147
	v_add_f32_e32 v154, v146, v136
	v_mov_b32_e32 v136, v153
	v_mov_b32_e32 v231, v173
	v_pk_mul_f32 v[146:147], v[136:137], v[230:231]
	v_add_f32_e32 v152, 1.0, v152
	v_add_f32_e32 v147, v147, v154
	v_add_f32_e32 v146, v146, v147
	v_mul_f32_e32 v147, 0xbfb8aa3b, v146
	v_exp_f32_e32 v147, v147
	v_rcp_f32_e32 v152, v152
	v_mul_f32_e32 v149, v150, v149
	v_cndmask_b32_e64 v149, v149, v150, s[4:5]
	v_add_f32_e32 v147, 1.0, v147
	v_rcp_f32_e32 v147, v147
	v_mul_f32_e32 v150, v151, v152
	v_cndmask_b32_e64 v150, v150, v151, s[4:5]
	s_mov_b64 s[0:1], -1
	v_mul_f32_e32 v147, v146, v147
	v_cndmask_b32_e64 v147, v147, v146, s[4:5]
	v_cvt_pk_bf16_f32 v146, v148, v149
	v_cvt_pk_bf16_f32 v147, v150, v147
	s_and_b64 vcc, exec, s[18:19]
	v_mov_b32_e32 v172, v102
	v_mov_b32_e32 v164, v103
	v_mov_b32_e32 v156, v104
	v_mov_b32_e32 v154, v105
	v_mov_b32_e32 v78, v146
	v_mov_b32_e32 v79, v147
	s_cbranch_vccnz .LBB0_749
	v_add_u32_e32 v147, 0xffffe010, v202
	v_ashrrev_i32_e32 v147, 2, v147
	v_lshl_add_u32 v147, v147, 1, v147
	v_mad_i64_i32 v[148:149], s[0:1], v147, s47, 0
	v_lshl_add_u64 v[148:149], v[148:149], 2, v[208:209]
	v_lshl_add_u64 v[150:151], v[148:149], 0, s[24:25]
	s_lshl_b32 s0, s27, 2
	s_mov_b32 s1, s25
	global_load_dwordx4 v[158:161], v[148:149], off offset:512
	s_nop 0
	global_load_dwordx4 v[150:153], v[150:151], off offset:512
	v_lshl_add_u64 v[148:149], v[148:149], 0, s[0:1]
	global_load_dwordx4 v[154:157], v[148:149], off offset:512
	v_mov_b32_e32 v164, 0
	v_mov_b32_e32 v165, 0
	v_mov_b32_e32 v146, 0
	v_mov_b32_dpp v164, v102 row_ror:1 row_mask:0xf bank_mask:0xf
	v_mov_b32_dpp v165, v102 row_ror:2 row_mask:0xf bank_mask:0xf
	v_mov_b32_dpp v146, v102 row_ror:3 row_mask:0xf bank_mask:0xf
	v_cmp_lt_i32_e32 vcc, 1, v205
	s_and_saveexec_b64 s[0:1], vcc
	s_xor_b64 s[0:1], exec, s[0:1]
	s_cbranch_execz .LBB0_712
	v_cmp_gt_i32_e32 vcc, 3, v205
	s_and_saveexec_b64 s[2:3], vcc
	s_cbranch_execz .LBB0_711
	s_waitcnt vmcnt(0)
	v_mov_b32_e32 v146, v154

; __device__ __forceinline__ unsigned cvt_pk_bf16(float lo, float hi) { unsigned r; asm("v_cvt_pk_bf16_f32 %0, %1, %2" : "=v"(r) : "v"(lo), "v"(hi)); return r; }
; __device__ __forceinline__ float siluf_(float x) { return x * sigmoidf_(x); }
; __device__ __forceinline__ float dpp_ror1(float v) { return __builtin_bit_cast(float, __builtin_amdgcn_update_dpp(0, __builtin_bit_cast(int, v), 0x121, 0xf, 0xf, false)); }
;     __device__ __forceinline__ void operator()(f32x4 (&acc)[2][2][4][2], const pg8::Unit& u, int wr, int wc, int fr, int fq) const {
;     ...
;                 for (int n = 0; n < 2; ++n) { const int ch = ch0 + bj * 128 + 4 * n;
;                     const f32x4 w0 = *(const f32x4*)(cw + ch), w1 = *(const f32x4*)(cw + CW + ch), w2 = *(const f32x4*)(cw + 2 * CW + ch), w3 = *(const f32x4*)(cw + 3 * CW + ch), bb = *(const f32x4*)(cb + ch);
; #pragma unroll
;                     for (int m = 0; m < 4; ++m) { const int row = row0 + ai * 128 + m * 16; const f32x4 g = acc[ai][bj][m][n]; f32x4 p1, p2, p3;
;                         if (prompt) { const f32x4 gp = (m == 0) ? hal[n] : acc[ai][bj][m > 0 ? m - 1 : 0][n];
; #pragma unroll
;                             for (int j = 0; j < 4; ++j) { p1[j] = dpp_ror1(fr == 15 ? gp[j] : g[j]); p2[j] = dpp_ror2(fr >= 14 ? gp[j] : g[j]); p3[j] = dpp_ror3(fr >= 13 ? gp[j] : g[j]); } }
;                         else { const int t = fr & 3; const float* sp = stp + (size_t)((row - MP) >> 2) * 3 * CW + ch;
;                             const f32x4 b0 = *(const f32x4*)sp, b1 = *(const f32x4*)(sp + CW), b2 = *(const f32x4*)(sp + 2 * CW);
; #pragma unroll
;                             for (int j = 0; j < 4; ++j) { const float r1 = dpp_ror1(g[j]), r2 = dpp_ror2(g[j]), r3 = dpp_ror3(g[j]);
;                                 p1[j] = t >= 1 ? r1 : b2[j]; p2[j] = t >= 2 ? r2 : (t == 1 ? b2[j] : b1[j]); p3[j] = t >= 3 ? r3 : (t == 2 ? b2[j] : (t == 1 ? b1[j] : b0[j])); } }
;                         float o[4];
; #pragma unroll
;                         for (int j = 0; j < 4; ++j) { const float y = bb[j] + w0[j] * p3[j] + w1[j] * p2[j] + w2[j] * p1[j] + w3[j] * g[j]; o[j] = is_rg ? y : siluf_(y); }
;                         u32x2 w; w.x = cvt_pk_bf16(o[0], o[1]); w.y = cvt_pk_bf16(o[2], o[3]);
;                         *(u32x2*)(dst + (size_t)row * ld + bj * 128 + 4 * n) = w; }
.LBB0_751:
	v_mov_b32_e32 v230, v150
	v_mov_b32_e32 v231, v146
	v_pk_mul_f32 v[230:231], v[166:167], v[230:231]
	v_mov_b32_e32 v173, v158
	v_add_f32_e32 v146, v142, v231
	v_add_f32_e32 v146, v230, v146
	v_pk_mul_f32 v[172:173], v[168:169], v[172:173]
	v_mov_b32_e32 v165, v159
	v_add_f32_e32 v146, v173, v146
	v_add_f32_e32 v150, v172, v146
	v_mul_f32_e32 v146, 0xbfb8aa3b, v150
	v_exp_f32_e32 v146, v146
	v_mov_b32_e32 v157, v160
	s_mov_b64 s[0:1], -1
	s_and_b64 vcc, exec, s[18:19]
	v_add_f32_e32 v146, 1.0, v146
	v_rcp_f32_e32 v155, v146
	v_mov_b32_e32 v146, v151
	v_pk_mul_f32 v[146:147], v[138:139], v[146:147]
	v_mov_b32_e32 v172, v86
	v_add_f32_e32 v147, v143, v147
	v_add_f32_e32 v151, v146, v147
	v_pk_mul_f32 v[146:147], v[134:135], v[164:165]
	v_mov_b32_e32 v164, v87
	v_add_f32_e32 v147, v147, v151
	v_add_f32_e32 v151, v146, v147
	v_mul_f32_e32 v146, 0xbfb8aa3b, v151
	v_exp_f32_e32 v146, v146
	v_mul_f32_e32 v147, v150, v155
	v_cndmask_b32_e64 v150, v147, v150, s[4:5]
	v_mov_b32_e32 v147, v148
	v_add_f32_e32 v146, 1.0, v146
	v_rcp_f32_e32 v158, v146
	v_mov_b32_e32 v146, v152
	v_pk_mul_f32 v[146:147], v[162:163], v[146:147]
	v_mov_b32_e32 v155, v161
	v_add_f32_e32 v147, v144, v147
	v_add_f32_e32 v148, v146, v147
	v_pk_mul_f32 v[146:147], v[170:171], v[156:157]
	s_nop 0
	v_add_f32_e32 v147, v147, v148
	v_add_f32_e32 v152, v146, v147
	v_mul_f32_e32 v146, 0xbfb8aa3b, v152
	v_mov_b32_e32 v148, v153
	v_exp_f32_e32 v156, v146
	v_pk_mul_f32 v[146:147], v[140:141], v[148:149]
	v_add_f32_e32 v149, 1.0, v156
	v_add_f32_e32 v147, v145, v147
	v_add_f32_e32 v148, v146, v147
	v_pk_mul_f32 v[146:147], v[136:137], v[154:155]
	v_rcp_f32_e32 v149, v149
	v_add_f32_e32 v147, v147, v148
	v_add_f32_e32 v146, v146, v147
	v_mul_f32_e32 v147, 0xbfb8aa3b, v146
	v_exp_f32_e32 v147, v147
	v_mul_f32_e32 v148, v151, v158
	v_mul_f32_e32 v149, v152, v149
	v_cndmask_b32_e64 v148, v148, v151, s[4:5]
	v_add_f32_e32 v147, 1.0, v147
	v_rcp_f32_e32 v147, v147
	v_cndmask_b32_e64 v149, v149, v152, s[4:5]
	v_mov_b32_e32 v156, v88
	v_mov_b32_e32 v154, v89
	v_mul_f32_e32 v147, v146, v147
	v_cndmask_b32_e64 v147, v147, v146, s[4:5]
	v_cvt_pk_bf16_f32 v146, v150, v148
	v_cvt_pk_bf16_f32 v147, v149, v147
	v_mov_b32_e32 v118, v146
	v_mov_b32_e32 v119, v147
	s_cbranch_vccnz .LBB0_793
	v_add_u32_e32 v147, 0xffffe020, v202
	v_ashrrev_i32_e32 v147, 2, v147
	v_lshl_add_u32 v147, v147, 1, v147
	v_mad_i64_i32 v[148:149], s[0:1], v147, s47, 0
	v_lshl_add_u64 v[148:149], v[148:149], 2, v[208:209]
	v_lshl_add_u64 v[150:151], v[148:149], 0, s[24:25]
	s_lshl_b32 s0, s27, 2
	s_mov_b32 s1, s25
	global_load_dwordx4 v[158:161], v[148:149], off offset:512
	s_nop 0
	global_load_dwordx4 v[150:153], v[150:151], off offset:512
	v_lshl_add_u64 v[148:149], v[148:149], 0, s[0:1]
	global_load_dwordx4 v[154:157], v[148:149], off offset:512
	v_mov_b32_e32 v164, 0
	v_mov_b32_e32 v165, 0
	v_mov_b32_e32 v146, 0
	v_mov_b32_dpp v164, v86 row_ror:1 row_mask:0xf bank_mask:0xf
	v_mov_b32_dpp v165, v86 row_ror:2 row_mask:0xf bank_mask:0xf
	v_mov_b32_dpp v146, v86 row_ror:3 row_mask:0xf bank_mask:0xf
	v_cmp_lt_i32_e32 vcc, 1, v205
	s_and_saveexec_b64 s[0:1], vcc
	s_xor_b64 s[0:1], exec, s[0:1]
	s_cbranch_execz .LBB0_756
	v_cmp_gt_i32_e32 vcc, 3, v205
	s_and_saveexec_b64 s[2:3], vcc
	s_cbranch_execz .LBB0_755
	s_waitcnt vmcnt(0)
	v_mov_b32_e32 v146, v154

; __device__ __forceinline__ unsigned cvt_pk_bf16(float lo, float hi) { unsigned r; asm("v_cvt_pk_bf16_f32 %0, %1, %2" : "=v"(r) : "v"(lo), "v"(hi)); return r; }
; __device__ __forceinline__ float siluf_(float x) { return x * sigmoidf_(x); }
; __device__ __forceinline__ float dpp_ror1(float v) { return __builtin_bit_cast(float, __builtin_amdgcn_update_dpp(0, __builtin_bit_cast(int, v), 0x121, 0xf, 0xf, false)); }
;     __device__ __forceinline__ void operator()(f32x4 (&acc)[2][2][4][2], const pg8::Unit& u, int wr, int wc, int fr, int fq) const {
;     ...
;                 for (int n = 0; n < 2; ++n) { const int ch = ch0 + bj * 128 + 4 * n;
;                     const f32x4 w0 = *(const f32x4*)(cw + ch), w1 = *(const f32x4*)(cw + CW + ch), w2 = *(const f32x4*)(cw + 2 * CW + ch), w3 = *(const f32x4*)(cw + 3 * CW + ch), bb = *(const f32x4*)(cb + ch);
; #pragma unroll
;                     for (int m = 0; m < 4; ++m) { const int row = row0 + ai * 128 + m * 16; const f32x4 g = acc[ai][bj][m][n]; f32x4 p1, p2, p3;
;                         if (prompt) { const f32x4 gp = (m == 0) ? hal[n] : acc[ai][bj][m > 0 ? m - 1 : 0][n];
; #pragma unroll
;                             for (int j = 0; j < 4; ++j) { p1[j] = dpp_ror1(fr == 15 ? gp[j] : g[j]); p2[j] = dpp_ror2(fr >= 14 ? gp[j] : g[j]); p3[j] = dpp_ror3(fr >= 13 ? gp[j] : g[j]); } }
;                         else { const int t = fr & 3; const float* sp = stp + (size_t)((row - MP) >> 2) * 3 * CW + ch;
;                             const f32x4 b0 = *(const f32x4*)sp, b1 = *(const f32x4*)(sp + CW), b2 = *(const f32x4*)(sp + 2 * CW);
; #pragma unroll
;                             for (int j = 0; j < 4; ++j) { const float r1 = dpp_ror1(g[j]), r2 = dpp_ror2(g[j]), r3 = dpp_ror3(g[j]);
;                                 p1[j] = t >= 1 ? r1 : b2[j]; p2[j] = t >= 2 ? r2 : (t == 1 ? b2[j] : b1[j]); p3[j] = t >= 3 ? r3 : (t == 2 ? b2[j] : (t == 1 ? b1[j] : b0[j])); } }
;                         float o[4];
; #pragma unroll
;                         for (int j = 0; j < 4; ++j) { const float y = bb[j] + w0[j] * p3[j] + w1[j] * p2[j] + w2[j] * p1[j] + w3[j] * g[j]; o[j] = is_rg ? y : siluf_(y); }
;                         u32x2 w; w.x = cvt_pk_bf16(o[0], o[1]); w.y = cvt_pk_bf16(o[2], o[3]);
;                         *(u32x2*)(dst + (size_t)row * ld + bj * 128 + 4 * n) = w; }
.LBB0_795:
	v_mov_b32_e32 v230, v150
	v_mov_b32_e32 v231, v146
	v_pk_mul_f32 v[230:231], v[166:167], v[230:231]
	v_mov_b32_e32 v173, v158
	v_add_f32_e32 v146, v142, v231
	v_add_f32_e32 v146, v230, v146
	v_pk_mul_f32 v[172:173], v[168:169], v[172:173]
	v_mov_b32_e32 v165, v159
	v_add_f32_e32 v146, v173, v146
	v_add_f32_e32 v150, v172, v146
	v_mul_f32_e32 v146, 0xbfb8aa3b, v150
	v_exp_f32_e32 v146, v146
	v_mov_b32_e32 v157, v160
	s_mov_b64 s[0:1], -1
	s_and_b64 vcc, exec, s[18:19]
	v_add_f32_e32 v146, 1.0, v146
	v_rcp_f32_e32 v155, v146
	v_mov_b32_e32 v146, v151
	v_pk_mul_f32 v[146:147], v[138:139], v[146:147]
	v_mov_b32_e32 v172, v70
	v_add_f32_e32 v147, v143, v147
	v_add_f32_e32 v151, v146, v147
	v_pk_mul_f32 v[146:147], v[134:135], v[164:165]
	v_mov_b32_e32 v164, v71
	v_add_f32_e32 v147, v147, v151
	v_add_f32_e32 v151, v146, v147
	v_mul_f32_e32 v146, 0xbfb8aa3b, v151
	v_exp_f32_e32 v146, v146
	v_mul_f32_e32 v147, v150, v155
	v_cndmask_b32_e64 v150, v147, v150, s[4:5]
	v_mov_b32_e32 v147, v148
	v_add_f32_e32 v146, 1.0, v146
	v_rcp_f32_e32 v158, v146
	v_mov_b32_e32 v146, v152
	v_pk_mul_f32 v[146:147], v[162:163], v[146:147]
	v_mov_b32_e32 v155, v161
	v_add_f32_e32 v147, v144, v147
	v_add_f32_e32 v148, v146, v147
	v_pk_mul_f32 v[146:147], v[170:171], v[156:157]
	s_nop 0
	v_add_f32_e32 v147, v147, v148
	v_add_f32_e32 v152, v146, v147
	v_mul_f32_e32 v146, 0xbfb8aa3b, v152
	v_mov_b32_e32 v148, v153
	v_exp_f32_e32 v156, v146
	v_pk_mul_f32 v[146:147], v[140:141], v[148:149]
	v_add_f32_e32 v149, 1.0, v156
	v_add_f32_e32 v147, v145, v147
	v_add_f32_e32 v148, v146, v147
	v_pk_mul_f32 v[146:147], v[136:137], v[154:155]
	v_rcp_f32_e32 v149, v149
	v_add_f32_e32 v147, v147, v148
	v_add_f32_e32 v146, v146, v147
	v_mul_f32_e32 v147, 0xbfb8aa3b, v146
	v_exp_f32_e32 v147, v147
	v_mul_f32_e32 v148, v151, v158
	v_mul_f32_e32 v149, v152, v149
	v_cndmask_b32_e64 v148, v148, v151, s[4:5]
	v_add_f32_e32 v147, 1.0, v147
	v_rcp_f32_e32 v147, v147
	v_cndmask_b32_e64 v149, v149, v152, s[4:5]
	v_mov_b32_e32 v156, v72
	v_mov_b32_e32 v154, v73
	v_mul_f32_e32 v147, v146, v147
	v_cndmask_b32_e64 v147, v147, v146, s[4:5]
	v_cvt_pk_bf16_f32 v146, v150, v148
	v_cvt_pk_bf16_f32 v147, v149, v147
	v_mov_b32_e32 v102, v146
	v_mov_b32_e32 v103, v147
	s_cbranch_vccnz .LBB0_837
	v_add_u32_e32 v147, 0xffffe030, v202
	v_ashrrev_i32_e32 v147, 2, v147
	v_lshl_add_u32 v147, v147, 1, v147
	v_mad_i64_i32 v[148:149], s[0:1], v147, s47, 0
	v_lshl_add_u64 v[148:149], v[148:149], 2, v[208:209]
	v_lshl_add_u64 v[150:151], v[148:149], 0, s[24:25]
	s_lshl_b32 s0, s27, 2
	s_mov_b32 s1, s25
	global_load_dwordx4 v[158:161], v[148:149], off offset:512
	s_nop 0
	global_load_dwordx4 v[150:153], v[150:151], off offset:512
	v_lshl_add_u64 v[148:149], v[148:149], 0, s[0:1]
	global_load_dwordx4 v[154:157], v[148:149], off offset:512
	v_mov_b32_e32 v164, 0
	v_mov_b32_e32 v165, 0
	v_mov_b32_e32 v146, 0
	v_mov_b32_dpp v164, v70 row_ror:1 row_mask:0xf bank_mask:0xf
	v_mov_b32_dpp v165, v70 row_ror:2 row_mask:0xf bank_mask:0xf
	v_mov_b32_dpp v146, v70 row_ror:3 row_mask:0xf bank_mask:0xf
	v_cmp_lt_i32_e32 vcc, 1, v205
	s_and_saveexec_b64 s[0:1], vcc
	s_xor_b64 s[0:1], exec, s[0:1]
	s_cbranch_execz .LBB0_800
	v_cmp_gt_i32_e32 vcc, 3, v205
	s_and_saveexec_b64 s[2:3], vcc
	s_cbranch_execz .LBB0_799
	s_waitcnt vmcnt(0)
	v_mov_b32_e32 v146, v154

; __device__ __forceinline__ unsigned cvt_pk_bf16(float lo, float hi) { unsigned r; asm("v_cvt_pk_bf16_f32 %0, %1, %2" : "=v"(r) : "v"(lo), "v"(hi)); return r; }
; __device__ __forceinline__ float siluf_(float x) { return x * sigmoidf_(x); }
; __device__ __forceinline__ float dpp_ror1(float v) { return __builtin_bit_cast(float, __builtin_amdgcn_update_dpp(0, __builtin_bit_cast(int, v), 0x121, 0xf, 0xf, false)); }
;     __device__ __forceinline__ void operator()(f32x4 (&acc)[2][2][4][2], const pg8::Unit& u, int wr, int wc, int fr, int fq) const {
;     ...
;                 for (int n = 0; n < 2; ++n) { const int ch = ch0 + bj * 128 + 4 * n;
;                     const f32x4 w0 = *(const f32x4*)(cw + ch), w1 = *(const f32x4*)(cw + CW + ch), w2 = *(const f32x4*)(cw + 2 * CW + ch), w3 = *(const f32x4*)(cw + 3 * CW + ch), bb = *(const f32x4*)(cb + ch);
; #pragma unroll
;                     for (int m = 0; m < 4; ++m) { const int row = row0 + ai * 128 + m * 16; const f32x4 g = acc[ai][bj][m][n]; f32x4 p1, p2, p3;
;                         if (prompt) { const f32x4 gp = (m == 0) ? hal[n] : acc[ai][bj][m > 0 ? m - 1 : 0][n];
; #pragma unroll
;                             for (int j = 0; j < 4; ++j) { p1[j] = dpp_ror1(fr == 15 ? gp[j] : g[j]); p2[j] = dpp_ror2(fr >= 14 ? gp[j] : g[j]); p3[j] = dpp_ror3(fr >= 13 ? gp[j] : g[j]); } }
;                         else { const int t = fr & 3; const float* sp = stp + (size_t)((row - MP) >> 2) * 3 * CW + ch;
;                             const f32x4 b0 = *(const f32x4*)sp, b1 = *(const f32x4*)(sp + CW), b2 = *(const f32x4*)(sp + 2 * CW);
; #pragma unroll
;                             for (int j = 0; j < 4; ++j) { const float r1 = dpp_ror1(g[j]), r2 = dpp_ror2(g[j]), r3 = dpp_ror3(g[j]);
;                                 p1[j] = t >= 1 ? r1 : b2[j]; p2[j] = t >= 2 ? r2 : (t == 1 ? b2[j] : b1[j]); p3[j] = t >= 3 ? r3 : (t == 2 ? b2[j] : (t == 1 ? b1[j] : b0[j])); } }
;                         float o[4];
; #pragma unroll
;                         for (int j = 0; j < 4; ++j) { const float y = bb[j] + w0[j] * p3[j] + w1[j] * p2[j] + w2[j] * p1[j] + w3[j] * g[j]; o[j] = is_rg ? y : siluf_(y); }
;                         u32x2 w; w.x = cvt_pk_bf16(o[0], o[1]); w.y = cvt_pk_bf16(o[2], o[3]);
;                         *(u32x2*)(dst + (size_t)row * ld + bj * 128 + 4 * n) = w; }
.LBB0_839:
	v_mov_b32_e32 v230, v150
	v_mov_b32_e32 v231, v146
	v_pk_mul_f32 v[166:167], v[166:167], v[230:231]
	v_mov_b32_e32 v173, v158
	v_add_f32_e32 v142, v142, v167
	v_add_f32_e32 v142, v166, v142
	v_pk_mul_f32 v[166:167], v[168:169], v[172:173]
	v_mov_b32_e32 v165, v159
	v_add_f32_e32 v142, v167, v142
	v_add_f32_e32 v142, v166, v142
	v_mul_f32_e32 v146, 0xbfb8aa3b, v142
	v_exp_f32_e32 v146, v146
	v_pk_mul_f32 v[134:135], v[134:135], v[164:165]
	v_mov_b32_e32 v157, v160
	v_mov_b32_e32 v155, v161
	v_add_f32_e32 v146, 1.0, v146
	v_rcp_f32_e32 v150, v146
	v_mov_b32_e32 v146, v151
	v_pk_mul_f32 v[138:139], v[138:139], v[146:147]
	s_mov_b64 s[0:1], -1
	v_add_f32_e32 v139, v143, v139
	v_add_f32_e32 v138, v138, v139
	v_add_f32_e32 v135, v135, v138
	v_add_f32_e32 v138, v134, v135
	v_mul_f32_e32 v134, 0xbfb8aa3b, v138
	v_exp_f32_e32 v134, v134
	v_mul_f32_e32 v135, v142, v150
	v_cndmask_b32_e64 v139, v135, v142, s[4:5]
	v_mov_b32_e32 v135, v148
	v_add_f32_e32 v134, 1.0, v134
	v_rcp_f32_e32 v142, v134
	v_mov_b32_e32 v134, v152
	v_pk_mul_f32 v[134:135], v[162:163], v[134:135]
	v_mov_b32_e32 v148, v153
	v_add_f32_e32 v135, v144, v135
	v_add_f32_e32 v143, v134, v135
	v_pk_mul_f32 v[134:135], v[170:171], v[156:157]
	s_and_b64 vcc, exec, s[18:19]
	v_add_f32_e32 v135, v135, v143
	v_add_f32_e32 v143, v134, v135
	v_mul_f32_e32 v134, 0xbfb8aa3b, v143
	v_exp_f32_e32 v144, v134
	v_pk_mul_f32 v[134:135], v[140:141], v[148:149]
	v_mov_b32_e32 v232, v114
	v_add_f32_e32 v135, v145, v135
	v_add_f32_e32 v140, v134, v135
	v_pk_mul_f32 v[134:135], v[136:137], v[154:155]
	v_add_f32_e32 v137, 1.0, v144
	v_add_f32_e32 v135, v135, v140
	v_add_f32_e32 v134, v134, v135
	v_mul_f32_e32 v135, 0xbfb8aa3b, v134
	v_exp_f32_e32 v135, v135
	v_rcp_f32_e32 v137, v137
	v_mul_f32_e32 v136, v138, v142
	v_cndmask_b32_e64 v136, v136, v138, s[4:5]
	v_add_f32_e32 v135, 1.0, v135
	v_rcp_f32_e32 v135, v135
	v_mul_f32_e32 v137, v143, v137
	v_cndmask_b32_e64 v137, v137, v143, s[4:5]
	v_mov_b32_e32 v230, v115
	v_mul_f32_e32 v135, v134, v135
	v_cndmask_b32_e64 v135, v135, v134, s[4:5]
	v_cvt_pk_bf16_f32 v134, v139, v136
	v_cvt_pk_bf16_f32 v135, v137, v135
	v_mov_b32_e32 v86, v134
	v_mov_b32_e32 v87, v135
	global_load_dwordx4 v[138:141], v[210:211], off offset:528
	global_load_dwordx4 v[150:153], v[212:213], off offset:528
	global_load_dwordx4 v[134:137], v[214:215], off offset:528
	global_load_dwordx4 v[146:149], v[216:217], off offset:528
	global_load_dwordx4 v[142:145], v[218:219], off offset:528
	v_mov_b32_e32 v172, v116
	v_mov_b32_e32 v170, v117
	s_cbranch_vccnz .LBB0_881
	v_add_u32_e32 v155, 0xffffe000, v202
	v_ashrrev_i32_e32 v155, 2, v155
	v_lshl_add_u32 v155, v155, 1, v155
	v_mad_i64_i32 v[156:157], s[0:1], v155, s47, 0
	v_lshl_add_u64 v[156:157], v[156:157], 2, v[208:209]
	v_lshl_add_u64 v[158:159], v[156:157], 0, s[24:25]
	s_lshl_b32 s0, s27, 2
	s_mov_b32 s1, s25
	global_load_dwordx4 v[166:169], v[156:157], off offset:528
	s_nop 0
	global_load_dwordx4 v[158:161], v[158:159], off offset:528
	v_lshl_add_u64 v[156:157], v[156:157], 0, s[0:1]
	global_load_dwordx4 v[162:165], v[156:157], off offset:528
	v_mov_b32_e32 v170, 0
	v_mov_b32_e32 v171, 0
	v_mov_b32_e32 v154, 0
	v_mov_b32_dpp v170, v114 row_ror:1 row_mask:0xf bank_mask:0xf
	v_mov_b32_dpp v171, v114 row_ror:2 row_mask:0xf bank_mask:0xf
	v_mov_b32_dpp v154, v114 row_ror:3 row_mask:0xf bank_mask:0xf
	v_cmp_lt_i32_e32 vcc, 1, v205
	s_and_saveexec_b64 s[0:1], vcc
	s_xor_b64 s[0:1], exec, s[0:1]
	s_cbranch_execz .LBB0_844
	v_cmp_gt_i32_e32 vcc, 3, v205
	s_and_saveexec_b64 s[2:3], vcc
	s_cbranch_execz .LBB0_843
	s_waitcnt vmcnt(0)
	v_mov_b32_e32 v154, v162

; __device__ __forceinline__ unsigned cvt_pk_bf16(float lo, float hi) { unsigned r; asm("v_cvt_pk_bf16_f32 %0, %1, %2" : "=v"(r) : "v"(lo), "v"(hi)); return r; }
; __device__ __forceinline__ float siluf_(float x) { return x * sigmoidf_(x); }
; __device__ __forceinline__ float dpp_ror1(float v) { return __builtin_bit_cast(float, __builtin_amdgcn_update_dpp(0, __builtin_bit_cast(int, v), 0x121, 0xf, 0xf, false)); }
;     __device__ __forceinline__ void operator()(f32x4 (&acc)[2][2][4][2], const pg8::Unit& u, int wr, int wc, int fr, int fq) const {
;     ...
;                 for (int n = 0; n < 2; ++n) { const int ch = ch0 + bj * 128 + 4 * n;
;                     const f32x4 w0 = *(const f32x4*)(cw + ch), w1 = *(const f32x4*)(cw + CW + ch), w2 = *(const f32x4*)(cw + 2 * CW + ch), w3 = *(const f32x4*)(cw + 3 * CW + ch), bb = *(const f32x4*)(cb + ch);
; #pragma unroll
;                     for (int m = 0; m < 4; ++m) { const int row = row0 + ai * 128 + m * 16; const f32x4 g = acc[ai][bj][m][n]; f32x4 p1, p2, p3;
;                         if (prompt) { const f32x4 gp = (m == 0) ? hal[n] : acc[ai][bj][m > 0 ? m - 1 : 0][n];
; #pragma unroll
;                             for (int j = 0; j < 4; ++j) { p1[j] = dpp_ror1(fr == 15 ? gp[j] : g[j]); p2[j] = dpp_ror2(fr >= 14 ? gp[j] : g[j]); p3[j] = dpp_ror3(fr >= 13 ? gp[j] : g[j]); } }
;                         else { const int t = fr & 3; const float* sp = stp + (size_t)((row - MP) >> 2) * 3 * CW + ch;
;                             const f32x4 b0 = *(const f32x4*)sp, b1 = *(const f32x4*)(sp + CW), b2 = *(const f32x4*)(sp + 2 * CW);
; #pragma unroll
;                             for (int j = 0; j < 4; ++j) { const float r1 = dpp_ror1(g[j]), r2 = dpp_ror2(g[j]), r3 = dpp_ror3(g[j]);
;                                 p1[j] = t >= 1 ? r1 : b2[j]; p2[j] = t >= 2 ? r2 : (t == 1 ? b2[j] : b1[j]); p3[j] = t >= 3 ? r3 : (t == 2 ? b2[j] : (t == 1 ? b1[j] : b0[j])); } }
;                         float o[4];
; #pragma unroll
;                         for (int j = 0; j < 4; ++j) { const float y = bb[j] + w0[j] * p3[j] + w1[j] * p2[j] + w2[j] * p1[j] + w3[j] * g[j]; o[j] = is_rg ? y : siluf_(y); }
;                         u32x2 w; w.x = cvt_pk_bf16(o[0], o[1]); w.y = cvt_pk_bf16(o[2], o[3]);
;                         *(u32x2*)(dst + (size_t)row * ld + bj * 128 + 4 * n) = w; }
.LBB0_883:
	s_waitcnt vmcnt(0)
	v_mov_b32_e32 v162, v150
	v_mov_b32_e32 v163, v138
	v_mov_b32_e32 v130, v158
	v_mov_b32_e32 v131, v154
	v_pk_mul_f32 v[130:131], v[162:163], v[130:131]
	v_mov_b32_e32 v164, v146
	v_add_f32_e32 v131, v142, v131
	v_mov_b32_e32 v165, v134
	v_mov_b32_e32 v233, v166
	v_add_f32_e32 v132, v130, v131
	v_pk_mul_f32 v[130:131], v[164:165], v[232:233]
	v_mov_b32_e32 v138, v151
	v_add_f32_e32 v131, v131, v132
	v_add_f32_e32 v132, v130, v131
	v_mul_f32_e32 v130, 0xbfb8aa3b, v132
	v_exp_f32_e32 v130, v130
	v_mov_b32_e32 v154, v159
	v_mov_b32_e32 v134, v147
	v_mov_b32_e32 v231, v167
	v_add_f32_e32 v130, 1.0, v130
	v_rcp_f32_e32 v133, v130
	v_pk_mul_f32 v[130:131], v[138:139], v[154:155]
	v_mov_b32_e32 v158, v152
	v_add_f32_e32 v131, v143, v131
	v_add_f32_e32 v146, v130, v131
	v_pk_mul_f32 v[130:131], v[134:135], v[230:231]
	v_mov_b32_e32 v159, v140
	v_add_f32_e32 v131, v131, v146
	v_add_f32_e32 v146, v130, v131
	v_mul_f32_e32 v130, 0xbfb8aa3b, v146
	v_exp_f32_e32 v130, v130
	v_mul_f32_e32 v131, v132, v133
	v_cndmask_b32_e64 v132, v131, v132, s[4:5]
	v_mov_b32_e32 v131, v156
	v_add_f32_e32 v130, 1.0, v130
	v_rcp_f32_e32 v133, v130
	v_mov_b32_e32 v130, v160
	v_pk_mul_f32 v[130:131], v[158:159], v[130:131]
	v_mov_b32_e32 v166, v148
	v_add_f32_e32 v131, v144, v131
	v_mov_b32_e32 v167, v136
	v_mov_b32_e32 v173, v168
	v_add_f32_e32 v140, v130, v131
	v_pk_mul_f32 v[130:131], v[166:167], v[172:173]
	v_mov_b32_e32 v156, v161
	v_add_f32_e32 v131, v131, v140
	v_add_f32_e32 v147, v130, v131
	v_mul_f32_e32 v130, 0xbfb8aa3b, v147
	v_mov_b32_e32 v140, v153
	v_exp_f32_e32 v148, v130
	v_pk_mul_f32 v[130:131], v[140:141], v[156:157]
	v_mov_b32_e32 v136, v149
	v_add_f32_e32 v131, v145, v131
	v_mov_b32_e32 v171, v169
	v_add_f32_e32 v150, v130, v131
	v_pk_mul_f32 v[130:131], v[136:137], v[170:171]
	v_add_f32_e32 v148, 1.0, v148
	v_add_f32_e32 v131, v131, v150
	v_add_f32_e32 v130, v130, v131
	v_mul_f32_e32 v131, 0xbfb8aa3b, v130
	v_exp_f32_e32 v131, v131
	v_rcp_f32_e32 v148, v148
	v_mul_f32_e32 v133, v146, v133
	v_cndmask_b32_e64 v133, v133, v146, s[4:5]
	v_add_f32_e32 v131, 1.0, v131
	v_rcp_f32_e32 v131, v131
	v_mul_f32_e32 v146, v147, v148
	v_cndmask_b32_e64 v146, v146, v147, s[4:5]
	s_mov_b64 s[0:1], -1
	v_mul_f32_e32 v131, v130, v131
	v_cndmask_b32_e64 v131, v131, v130, s[4:5]
	v_cvt_pk_bf16_f32 v130, v132, v133
	v_cvt_pk_bf16_f32 v131, v146, v131
	s_and_b64 vcc, exec, s[18:19]
	v_mov_b32_e32 v168, v98
	v_mov_b32_e32 v160, v99
	v_mov_b32_e32 v152, v100
	v_mov_b32_e32 v150, v101
	v_mov_b32_e32 v80, v130
	v_mov_b32_e32 v81, v131
	flat_store_dwordx4 v[222:223], v[78:81] offset:256
	s_cbranch_vccnz .LBB0_925
	v_add_u32_e32 v131, 0xffffe010, v202
	v_ashrrev_i32_e32 v131, 2, v131
	v_lshl_add_u32 v131, v131, 1, v131
	v_mad_i64_i32 v[132:133], s[0:1], v131, s47, 0
	v_lshl_add_u64 v[132:133], v[132:133], 2, v[208:209]
	v_lshl_add_u64 v[146:147], v[132:133], 0, s[24:25]
	s_lshl_b32 s0, s27, 2
	s_mov_b32 s1, s25
	global_load_dwordx4 v[154:157], v[132:133], off offset:528
	s_nop 0
	global_load_dwordx4 v[146:149], v[146:147], off offset:528
	v_lshl_add_u64 v[132:133], v[132:133], 0, s[0:1]
	global_load_dwordx4 v[150:153], v[132:133], off offset:528
	v_mov_b32_e32 v160, 0
	v_mov_b32_e32 v161, 0
	v_mov_b32_e32 v130, 0
	v_mov_b32_dpp v160, v98 row_ror:1 row_mask:0xf bank_mask:0xf
	v_mov_b32_dpp v161, v98 row_ror:2 row_mask:0xf bank_mask:0xf
	v_mov_b32_dpp v130, v98 row_ror:3 row_mask:0xf bank_mask:0xf
	v_cmp_lt_i32_e32 vcc, 1, v205
	s_and_saveexec_b64 s[0:1], vcc
	s_xor_b64 s[0:1], exec, s[0:1]
	s_cbranch_execz .LBB0_888
	v_cmp_gt_i32_e32 vcc, 3, v205
	s_and_saveexec_b64 s[2:3], vcc
	s_cbranch_execz .LBB0_887
	s_waitcnt vmcnt(0)
	v_mov_b32_e32 v130, v150

; __device__ __forceinline__ unsigned cvt_pk_bf16(float lo, float hi) { unsigned r; asm("v_cvt_pk_bf16_f32 %0, %1, %2" : "=v"(r) : "v"(lo), "v"(hi)); return r; }
; __device__ __forceinline__ float siluf_(float x) { return x * sigmoidf_(x); }
; __device__ __forceinline__ float dpp_ror1(float v) { return __builtin_bit_cast(float, __builtin_amdgcn_update_dpp(0, __builtin_bit_cast(int, v), 0x121, 0xf, 0xf, false)); }
;     __device__ __forceinline__ void operator()(f32x4 (&acc)[2][2][4][2], const pg8::Unit& u, int wr, int wc, int fr, int fq) const {
;     ...
;                 for (int n = 0; n < 2; ++n) { const int ch = ch0 + bj * 128 + 4 * n;
;                     const f32x4 w0 = *(const f32x4*)(cw + ch), w1 = *(const f32x4*)(cw + CW + ch), w2 = *(const f32x4*)(cw + 2 * CW + ch), w3 = *(const f32x4*)(cw + 3 * CW + ch), bb = *(const f32x4*)(cb + ch);
; #pragma unroll
;                     for (int m = 0; m < 4; ++m) { const int row = row0 + ai * 128 + m * 16; const f32x4 g = acc[ai][bj][m][n]; f32x4 p1, p2, p3;
;                         if (prompt) { const f32x4 gp = (m == 0) ? hal[n] : acc[ai][bj][m > 0 ? m - 1 : 0][n];
; #pragma unroll
;                             for (int j = 0; j < 4; ++j) { p1[j] = dpp_ror1(fr == 15 ? gp[j] : g[j]); p2[j] = dpp_ror2(fr >= 14 ? gp[j] : g[j]); p3[j] = dpp_ror3(fr >= 13 ? gp[j] : g[j]); } }
;                         else { const int t = fr & 3; const float* sp = stp + (size_t)((row - MP) >> 2) * 3 * CW + ch;
;                             const f32x4 b0 = *(const f32x4*)sp, b1 = *(const f32x4*)(sp + CW), b2 = *(const f32x4*)(sp + 2 * CW);
; #pragma unroll
;                             for (int j = 0; j < 4; ++j) { const float r1 = dpp_ror1(g[j]), r2 = dpp_ror2(g[j]), r3 = dpp_ror3(g[j]);
;                                 p1[j] = t >= 1 ? r1 : b2[j]; p2[j] = t >= 2 ? r2 : (t == 1 ? b2[j] : b1[j]); p3[j] = t >= 3 ? r3 : (t == 2 ? b2[j] : (t == 1 ? b1[j] : b0[j])); } }
;                         float o[4];
; #pragma unroll
;                         for (int j = 0; j < 4; ++j) { const float y = bb[j] + w0[j] * p3[j] + w1[j] * p2[j] + w2[j] * p1[j] + w3[j] * g[j]; o[j] = is_rg ? y : siluf_(y); }
;                         u32x2 w; w.x = cvt_pk_bf16(o[0], o[1]); w.y = cvt_pk_bf16(o[2], o[3]);
;                         *(u32x2*)(dst + (size_t)row * ld + bj * 128 + 4 * n) = w; }
.LBB0_927:
	v_mov_b32_e32 v170, v146
	v_mov_b32_e32 v171, v130
	v_pk_mul_f32 v[170:171], v[162:163], v[170:171]
	v_mov_b32_e32 v169, v154
	v_add_f32_e32 v130, v142, v171
	v_add_f32_e32 v130, v170, v130
	v_pk_mul_f32 v[168:169], v[164:165], v[168:169]
	v_mov_b32_e32 v161, v155
	v_add_f32_e32 v130, v169, v130
	v_add_f32_e32 v146, v168, v130
	v_mul_f32_e32 v130, 0xbfb8aa3b, v146
	v_exp_f32_e32 v130, v130
	v_mov_b32_e32 v153, v156
	s_mov_b64 s[0:1], -1
	s_and_b64 vcc, exec, s[18:19]
	v_add_f32_e32 v130, 1.0, v130
	v_rcp_f32_e32 v151, v130
	v_mov_b32_e32 v130, v147
	v_pk_mul_f32 v[130:131], v[138:139], v[130:131]
	v_mov_b32_e32 v168, v82
	v_add_f32_e32 v131, v143, v131
	v_add_f32_e32 v147, v130, v131
	v_pk_mul_f32 v[130:131], v[134:135], v[160:161]
	v_mov_b32_e32 v160, v83
	v_add_f32_e32 v131, v131, v147
	v_add_f32_e32 v147, v130, v131
	v_mul_f32_e32 v130, 0xbfb8aa3b, v147
	v_exp_f32_e32 v130, v130
	v_mul_f32_e32 v131, v146, v151
	v_cndmask_b32_e64 v146, v131, v146, s[4:5]
	v_mov_b32_e32 v131, v132
	v_add_f32_e32 v130, 1.0, v130
	v_rcp_f32_e32 v154, v130
	v_mov_b32_e32 v130, v148
	v_pk_mul_f32 v[130:131], v[158:159], v[130:131]
	v_mov_b32_e32 v151, v157
	v_add_f32_e32 v131, v144, v131
	v_add_f32_e32 v132, v130, v131
	v_pk_mul_f32 v[130:131], v[166:167], v[152:153]
	s_nop 0
	v_add_f32_e32 v131, v131, v132
	v_add_f32_e32 v148, v130, v131
	v_mul_f32_e32 v130, 0xbfb8aa3b, v148
	v_mov_b32_e32 v132, v149
	v_exp_f32_e32 v152, v130
	v_pk_mul_f32 v[130:131], v[140:141], v[132:133]
	v_add_f32_e32 v133, 1.0, v152
	v_add_f32_e32 v131, v145, v131
	v_add_f32_e32 v132, v130, v131
	v_pk_mul_f32 v[130:131], v[136:137], v[150:151]
	v_rcp_f32_e32 v133, v133
	v_add_f32_e32 v131, v131, v132
	v_add_f32_e32 v130, v130, v131
	v_mul_f32_e32 v131, 0xbfb8aa3b, v130
	v_exp_f32_e32 v131, v131
	v_mul_f32_e32 v132, v147, v154
	v_mul_f32_e32 v133, v148, v133
	v_cndmask_b32_e64 v132, v132, v147, s[4:5]
	v_add_f32_e32 v131, 1.0, v131
	v_rcp_f32_e32 v131, v131
	v_cndmask_b32_e64 v133, v133, v148, s[4:5]
	v_mov_b32_e32 v152, v84
	v_mov_b32_e32 v150, v85
	v_mul_f32_e32 v131, v130, v131
	v_cndmask_b32_e64 v131, v131, v130, s[4:5]
	v_cvt_pk_bf16_f32 v130, v146, v132
	v_cvt_pk_bf16_f32 v131, v133, v131
	v_mov_b32_e32 v120, v130
	v_mov_b32_e32 v121, v131
	flat_store_dwordx4 v[224:225], v[118:121] offset:256
	s_cbranch_vccnz .LBB0_969
	v_add_u32_e32 v131, 0xffffe020, v202
	v_ashrrev_i32_e32 v131, 2, v131
	v_lshl_add_u32 v131, v131, 1, v131
	v_mad_i64_i32 v[132:133], s[0:1], v131, s47, 0
	v_lshl_add_u64 v[132:133], v[132:133], 2, v[208:209]
	v_lshl_add_u64 v[146:147], v[132:133], 0, s[24:25]
	s_lshl_b32 s0, s27, 2
	s_mov_b32 s1, s25
	global_load_dwordx4 v[154:157], v[132:133], off offset:528
	s_nop 0
	global_load_dwordx4 v[146:149], v[146:147], off offset:528
	v_lshl_add_u64 v[132:133], v[132:133], 0, s[0:1]
	global_load_dwordx4 v[150:153], v[132:133], off offset:528
	v_mov_b32_e32 v160, 0
	v_mov_b32_e32 v161, 0
	v_mov_b32_e32 v130, 0
	v_mov_b32_dpp v160, v82 row_ror:1 row_mask:0xf bank_mask:0xf
	v_mov_b32_dpp v161, v82 row_ror:2 row_mask:0xf bank_mask:0xf
	v_mov_b32_dpp v130, v82 row_ror:3 row_mask:0xf bank_mask:0xf
	v_cmp_lt_i32_e32 vcc, 1, v205
	s_and_saveexec_b64 s[0:1], vcc
	s_xor_b64 s[0:1], exec, s[0:1]
	s_cbranch_execz .LBB0_932
	v_cmp_gt_i32_e32 vcc, 3, v205
	s_and_saveexec_b64 s[2:3], vcc
	s_cbranch_execz .LBB0_931
	s_waitcnt vmcnt(0)
	v_mov_b32_e32 v130, v150

; __device__ __forceinline__ unsigned cvt_pk_bf16(float lo, float hi) { unsigned r; asm("v_cvt_pk_bf16_f32 %0, %1, %2" : "=v"(r) : "v"(lo), "v"(hi)); return r; }
; __device__ __forceinline__ float siluf_(float x) { return x * sigmoidf_(x); }
; __device__ __forceinline__ float dpp_ror1(float v) { return __builtin_bit_cast(float, __builtin_amdgcn_update_dpp(0, __builtin_bit_cast(int, v), 0x121, 0xf, 0xf, false)); }
;     __device__ __forceinline__ void operator()(f32x4 (&acc)[2][2][4][2], const pg8::Unit& u, int wr, int wc, int fr, int fq) const {
;     ...
;                 for (int n = 0; n < 2; ++n) { const int ch = ch0 + bj * 128 + 4 * n;
;                     const f32x4 w0 = *(const f32x4*)(cw + ch), w1 = *(const f32x4*)(cw + CW + ch), w2 = *(const f32x4*)(cw + 2 * CW + ch), w3 = *(const f32x4*)(cw + 3 * CW + ch), bb = *(const f32x4*)(cb + ch);
; #pragma unroll
;                     for (int m = 0; m < 4; ++m) { const int row = row0 + ai * 128 + m * 16; const f32x4 g = acc[ai][bj][m][n]; f32x4 p1, p2, p3;
;                         if (prompt) { const f32x4 gp = (m == 0) ? hal[n] : acc[ai][bj][m > 0 ? m - 1 : 0][n];
; #pragma unroll
;                             for (int j = 0; j < 4; ++j) { p1[j] = dpp_ror1(fr == 15 ? gp[j] : g[j]); p2[j] = dpp_ror2(fr >= 14 ? gp[j] : g[j]); p3[j] = dpp_ror3(fr >= 13 ? gp[j] : g[j]); } }
;                         else { const int t = fr & 3; const float* sp = stp + (size_t)((row - MP) >> 2) * 3 * CW + ch;
;                             const f32x4 b0 = *(const f32x4*)sp, b1 = *(const f32x4*)(sp + CW), b2 = *(const f32x4*)(sp + 2 * CW);
; #pragma unroll
;                             for (int j = 0; j < 4; ++j) { const float r1 = dpp_ror1(g[j]), r2 = dpp_ror2(g[j]), r3 = dpp_ror3(g[j]);
;                                 p1[j] = t >= 1 ? r1 : b2[j]; p2[j] = t >= 2 ? r2 : (t == 1 ? b2[j] : b1[j]); p3[j] = t >= 3 ? r3 : (t == 2 ? b2[j] : (t == 1 ? b1[j] : b0[j])); } }
;                         float o[4];
; #pragma unroll
;                         for (int j = 0; j < 4; ++j) { const float y = bb[j] + w0[j] * p3[j] + w1[j] * p2[j] + w2[j] * p1[j] + w3[j] * g[j]; o[j] = is_rg ? y : siluf_(y); }
;                         u32x2 w; w.x = cvt_pk_bf16(o[0], o[1]); w.y = cvt_pk_bf16(o[2], o[3]);
;                         *(u32x2*)(dst + (size_t)row * ld + bj * 128 + 4 * n) = w; }
.LBB0_971:
	v_mov_b32_e32 v170, v146
	v_mov_b32_e32 v171, v130
	v_pk_mul_f32 v[170:171], v[162:163], v[170:171]
	v_mov_b32_e32 v169, v154
	v_add_f32_e32 v130, v142, v171
	v_add_f32_e32 v130, v170, v130
	v_pk_mul_f32 v[168:169], v[164:165], v[168:169]
	v_mov_b32_e32 v161, v155
	v_add_f32_e32 v130, v169, v130
	v_add_f32_e32 v146, v168, v130
	v_mul_f32_e32 v130, 0xbfb8aa3b, v146
	v_exp_f32_e32 v130, v130
	v_mov_b32_e32 v153, v156
	s_mov_b64 s[0:1], -1
	s_and_b64 vcc, exec, s[18:19]
	v_add_f32_e32 v130, 1.0, v130
	v_rcp_f32_e32 v151, v130
	v_mov_b32_e32 v130, v147
	v_pk_mul_f32 v[130:131], v[138:139], v[130:131]
	v_mov_b32_e32 v168, v66
	v_add_f32_e32 v131, v143, v131
	v_add_f32_e32 v147, v130, v131
	v_pk_mul_f32 v[130:131], v[134:135], v[160:161]
	v_mov_b32_e32 v160, v67
	v_add_f32_e32 v131, v131, v147
	v_add_f32_e32 v147, v130, v131
	v_mul_f32_e32 v130, 0xbfb8aa3b, v147
	v_exp_f32_e32 v130, v130
	v_mul_f32_e32 v131, v146, v151
	v_cndmask_b32_e64 v146, v131, v146, s[4:5]
	v_mov_b32_e32 v131, v132
	v_add_f32_e32 v130, 1.0, v130
	v_rcp_f32_e32 v154, v130
	v_mov_b32_e32 v130, v148
	v_pk_mul_f32 v[130:131], v[158:159], v[130:131]
	v_mov_b32_e32 v151, v157
	v_add_f32_e32 v131, v144, v131
	v_add_f32_e32 v132, v130, v131
	v_pk_mul_f32 v[130:131], v[166:167], v[152:153]
	s_nop 0
	v_add_f32_e32 v131, v131, v132
	v_add_f32_e32 v148, v130, v131
	v_mul_f32_e32 v130, 0xbfb8aa3b, v148
	v_mov_b32_e32 v132, v149
	v_exp_f32_e32 v152, v130
	v_pk_mul_f32 v[130:131], v[140:141], v[132:133]
	v_add_f32_e32 v133, 1.0, v152
	v_add_f32_e32 v131, v145, v131
	v_add_f32_e32 v132, v130, v131
	v_pk_mul_f32 v[130:131], v[136:137], v[150:151]
	v_rcp_f32_e32 v133, v133
	v_add_f32_e32 v131, v131, v132
	v_add_f32_e32 v130, v130, v131
	v_mul_f32_e32 v131, 0xbfb8aa3b, v130
	v_exp_f32_e32 v131, v131
	v_mul_f32_e32 v132, v147, v154
	v_mul_f32_e32 v133, v148, v133
	v_cndmask_b32_e64 v132, v132, v147, s[4:5]
	v_add_f32_e32 v131, 1.0, v131
	v_rcp_f32_e32 v131, v131
	v_cndmask_b32_e64 v133, v133, v148, s[4:5]
	v_mov_b32_e32 v152, v68
	v_mov_b32_e32 v150, v69
	v_mul_f32_e32 v131, v130, v131
	v_cndmask_b32_e64 v131, v131, v130, s[4:5]
	v_cvt_pk_bf16_f32 v130, v146, v132
	v_cvt_pk_bf16_f32 v131, v133, v131
	v_mov_b32_e32 v104, v130
	v_mov_b32_e32 v105, v131
	flat_store_dwordx4 v[226:227], v[102:105] offset:256
	s_cbranch_vccnz .LBB0_1013
	v_add_u32_e32 v131, 0xffffe030, v202
	v_ashrrev_i32_e32 v131, 2, v131
	v_lshl_add_u32 v131, v131, 1, v131
	v_mad_i64_i32 v[132:133], s[0:1], v131, s47, 0
	v_lshl_add_u64 v[132:133], v[132:133], 2, v[208:209]
	v_lshl_add_u64 v[146:147], v[132:133], 0, s[24:25]
	s_lshl_b32 s0, s27, 2
	s_mov_b32 s1, s25
	global_load_dwordx4 v[154:157], v[132:133], off offset:528
	s_nop 0
	global_load_dwordx4 v[146:149], v[146:147], off offset:528
	v_lshl_add_u64 v[132:133], v[132:133], 0, s[0:1]
	global_load_dwordx4 v[150:153], v[132:133], off offset:528
	v_mov_b32_e32 v160, 0
	v_mov_b32_e32 v161, 0
	v_mov_b32_e32 v130, 0
	v_mov_b32_dpp v160, v66 row_ror:1 row_mask:0xf bank_mask:0xf
	v_mov_b32_dpp v161, v66 row_ror:2 row_mask:0xf bank_mask:0xf
	v_mov_b32_dpp v130, v66 row_ror:3 row_mask:0xf bank_mask:0xf
	v_cmp_lt_i32_e32 vcc, 1, v205
	s_and_saveexec_b64 s[0:1], vcc
	s_xor_b64 s[0:1], exec, s[0:1]
	s_cbranch_execz .LBB0_976
	v_cmp_gt_i32_e32 vcc, 3, v205
	s_and_saveexec_b64 s[2:3], vcc
	s_cbranch_execz .LBB0_975
	s_waitcnt vmcnt(0)
	v_mov_b32_e32 v130, v150

; __device__ __forceinline__ unsigned cvt_pk_bf16(float lo, float hi) { unsigned r; asm("v_cvt_pk_bf16_f32 %0, %1, %2" : "=v"(r) : "v"(lo), "v"(hi)); return r; }
; __device__ __forceinline__ float siluf_(float x) { return x * sigmoidf_(x); }
; __device__ __forceinline__ float dpp_ror1(float v) { return __builtin_bit_cast(float, __builtin_amdgcn_update_dpp(0, __builtin_bit_cast(int, v), 0x121, 0xf, 0xf, false)); }
;     __device__ __forceinline__ void operator()(f32x4 (&acc)[2][2][4][2], const pg8::Unit& u, int wr, int wc, int fr, int fq) const {
;     ...
;                 for (int n = 0; n < 2; ++n) { const int ch = ch0 + bj * 128 + 4 * n;
;                     const f32x4 w0 = *(const f32x4*)(cw + ch), w1 = *(const f32x4*)(cw + CW + ch), w2 = *(const f32x4*)(cw + 2 * CW + ch), w3 = *(const f32x4*)(cw + 3 * CW + ch), bb = *(const f32x4*)(cb + ch);
; #pragma unroll
;                     for (int m = 0; m < 4; ++m) { const int row = row0 + ai * 128 + m * 16; const f32x4 g = acc[ai][bj][m][n]; f32x4 p1, p2, p3;
;                         if (prompt) { const f32x4 gp = (m == 0) ? hal[n] : acc[ai][bj][m > 0 ? m - 1 : 0][n];
; #pragma unroll
;                             for (int j = 0; j < 4; ++j) { p1[j] = dpp_ror1(fr == 15 ? gp[j] : g[j]); p2[j] = dpp_ror2(fr >= 14 ? gp[j] : g[j]); p3[j] = dpp_ror3(fr >= 13 ? gp[j] : g[j]); } }
;                         else { const int t = fr & 3; const float* sp = stp + (size_t)((row - MP) >> 2) * 3 * CW + ch;
;                             const f32x4 b0 = *(const f32x4*)sp, b1 = *(const f32x4*)(sp + CW), b2 = *(const f32x4*)(sp + 2 * CW);
; #pragma unroll
;                             for (int j = 0; j < 4; ++j) { const float r1 = dpp_ror1(g[j]), r2 = dpp_ror2(g[j]), r3 = dpp_ror3(g[j]);
;                                 p1[j] = t >= 1 ? r1 : b2[j]; p2[j] = t >= 2 ? r2 : (t == 1 ? b2[j] : b1[j]); p3[j] = t >= 3 ? r3 : (t == 2 ? b2[j] : (t == 1 ? b1[j] : b0[j])); } }
;                         float o[4];
; #pragma unroll
;                         for (int j = 0; j < 4; ++j) { const float y = bb[j] + w0[j] * p3[j] + w1[j] * p2[j] + w2[j] * p1[j] + w3[j] * g[j]; o[j] = is_rg ? y : siluf_(y); }
;                         u32x2 w; w.x = cvt_pk_bf16(o[0], o[1]); w.y = cvt_pk_bf16(o[2], o[3]);
;                         *(u32x2*)(dst + (size_t)row * ld + bj * 128 + 4 * n) = w; }
.LBB0_1015:
	v_mov_b32_e32 v170, v146
	v_mov_b32_e32 v171, v130
	v_pk_mul_f32 v[162:163], v[162:163], v[170:171]
	v_mov_b32_e32 v169, v154
	v_add_f32_e32 v130, v142, v163
	v_add_f32_e32 v130, v162, v130
	v_pk_mul_f32 v[162:163], v[164:165], v[168:169]
	v_mov_b32_e32 v161, v155
	v_add_f32_e32 v130, v163, v130
	v_add_f32_e32 v142, v162, v130
	v_mul_f32_e32 v130, 0xbfb8aa3b, v142
	v_exp_f32_e32 v130, v130
	v_mov_b32_e32 v153, v156
	v_mov_b32_e32 v151, v157
	v_readlane_b32 s0, v255, 7
	v_add_f32_e32 v130, 1.0, v130
	v_rcp_f32_e32 v146, v130
	v_mov_b32_e32 v130, v147
	v_pk_mul_f32 v[130:131], v[138:139], v[130:131]
	v_readlane_b32 s2, v255, 19
	v_add_f32_e32 v131, v143, v131
	v_add_f32_e32 v138, v130, v131
	v_pk_mul_f32 v[130:131], v[134:135], v[160:161]
	v_mov_b32_e32 v160, 0
	v_add_f32_e32 v131, v131, v138
	v_add_f32_e32 v134, v130, v131
	v_mul_f32_e32 v130, 0xbfb8aa3b, v134
	v_exp_f32_e32 v130, v130
	v_mul_f32_e32 v131, v142, v146
	v_cndmask_b32_e64 v135, v131, v142, s[4:5]
	v_mov_b32_e32 v131, v132
	v_add_f32_e32 v130, 1.0, v130
	v_rcp_f32_e32 v138, v130
	v_mov_b32_e32 v130, v148
	v_pk_mul_f32 v[130:131], v[158:159], v[130:131]
	v_mov_b32_e32 v158, 0
	v_add_f32_e32 v131, v144, v131
	v_add_f32_e32 v132, v130, v131
	v_pk_mul_f32 v[130:131], v[166:167], v[152:153]
	v_mov_b32_e32 v159, 0
	v_add_f32_e32 v131, v131, v132
	v_add_f32_e32 v139, v130, v131
	v_mul_f32_e32 v130, 0xbfb8aa3b, v139
	v_mov_b32_e32 v132, v149
	v_exp_f32_e32 v142, v130
	v_pk_mul_f32 v[130:131], v[140:141], v[132:133]
	v_mov_b32_e32 v161, 0
	v_add_f32_e32 v131, v145, v131
	v_add_f32_e32 v132, v130, v131
	v_pk_mul_f32 v[130:131], v[136:137], v[150:151]
	v_add_f32_e32 v133, 1.0, v142
	v_add_f32_e32 v131, v131, v132
	v_add_f32_e32 v130, v130, v131
	v_mul_f32_e32 v131, 0xbfb8aa3b, v130
	v_exp_f32_e32 v131, v131
	v_rcp_f32_e32 v133, v133
	v_mul_f32_e32 v132, v134, v138
	v_cndmask_b32_e64 v132, v132, v134, s[4:5]
	v_add_f32_e32 v131, 1.0, v131
	v_rcp_f32_e32 v131, v131
	v_mul_f32_e32 v133, v139, v133
	v_cndmask_b32_e64 v133, v133, v139, s[4:5]
	v_mul_f32_e32 v131, v130, v131
	v_cndmask_b32_e64 v131, v131, v130, s[4:5]
	v_cvt_pk_bf16_f32 v130, v135, v132
	v_cvt_pk_bf16_f32 v131, v133, v131
	v_mov_b32_e32 v88, v130
	v_mov_b32_e32 v89, v131
	flat_store_dwordx4 v[228:229], v[86:89] offset:256
	v_add_lshl_u32 v131, v207, s0, 10
	s_and_b64 s[0:1], s[76:77], s[6:7]
	v_mov_b32_e32 v130, 0
	v_lshlrev_b32_e32 v207, 2, v206
	v_add_u32_e32 v232, s2, v131
	v_mov_b32_e32 v131, 0
	v_mov_b32_e32 v132, 0
	v_mov_b32_e32 v133, 0
	s_and_saveexec_b64 s[2:3], s[0:1]
	s_cbranch_execz .LBB0_1017
	s_movk_i32 s20, 0xc000
	v_add3_u32 v130, v232, v207, s20
	ds_read_b128 v[158:161], v130
	ds_read_b128 v[130:133], v130 offset:16

; __device__ __forceinline__ unsigned cvt_pk_bf16(float lo, float hi) { unsigned r; asm("v_cvt_pk_bf16_f32 %0, %1, %2" : "=v"(r) : "v"(lo), "v"(hi)); return r; }
; __device__ __forceinline__ float siluf_(float x) { return x * sigmoidf_(x); }
; __device__ __forceinline__ float dpp_ror1(float v) { return __builtin_bit_cast(float, __builtin_amdgcn_update_dpp(0, __builtin_bit_cast(int, v), 0x121, 0xf, 0xf, false)); }
; __device__ __forceinline__ float dpp_ror2(float v) { return __builtin_bit_cast(float, __builtin_amdgcn_update_dpp(0, __builtin_bit_cast(int, v), 0x122, 0xf, 0xf, false)); }
; __device__ __forceinline__ float dpp_ror3(float v) { return __builtin_bit_cast(float, __builtin_amdgcn_update_dpp(0, __builtin_bit_cast(int, v), 0x123, 0xf, 0xf, false)); }
;     __device__ __forceinline__ void operator()(f32x4 (&acc)[2][2][4][2], const pg8::Unit& u, int wr, int wc, int fr, int fq) const {
;     ...
;                     for (int m = 0; m < 4; ++m) { const int row = row0 + ai * 128 + m * 16; const f32x4 g = acc[ai][bj][m][n]; f32x4 p1, p2, p3;
;                         if (prompt) { const f32x4 gp = (m == 0) ? hal[n] : acc[ai][bj][m > 0 ? m - 1 : 0][n];
; #pragma unroll
;                             for (int j = 0; j < 4; ++j) { p1[j] = dpp_ror1(fr == 15 ? gp[j] : g[j]); p2[j] = dpp_ror2(fr >= 14 ? gp[j] : g[j]); p3[j] = dpp_ror3(fr >= 13 ? gp[j] : g[j]); } }
;                         else { const int t = fr & 3; const float* sp = stp + (size_t)((row - MP) >> 2) * 3 * CW + ch;
;                             const f32x4 b0 = *(const f32x4*)sp, b1 = *(const f32x4*)(sp + CW), b2 = *(const f32x4*)(sp + 2 * CW);
; #pragma unroll
;                             for (int j = 0; j < 4; ++j) { const float r1 = dpp_ror1(g[j]), r2 = dpp_ror2(g[j]), r3 = dpp_ror3(g[j]);
;                                 p1[j] = t >= 1 ? r1 : b2[j]; p2[j] = t >= 2 ? r2 : (t == 1 ? b2[j] : b1[j]); p3[j] = t >= 3 ? r3 : (t == 2 ? b2[j] : (t == 1 ? b1[j] : b0[j])); } }
;                         float o[4];
; #pragma unroll
;                         for (int j = 0; j < 4; ++j) { const float y = bb[j] + w0[j] * p3[j] + w1[j] * p2[j] + w2[j] * p1[j] + w3[j] * g[j]; o[j] = is_rg ? y : siluf_(y); }
;                         u32x2 w; w.x = cvt_pk_bf16(o[0], o[1]); w.y = cvt_pk_bf16(o[2], o[3]);
;                         *(u32x2*)(dst + (size_t)row * ld + bj * 128 + 4 * n) = w; }
.LBB0_1061:
	s_waitcnt vmcnt(0)
	v_mov_b32_e32 v166, v150
	v_mov_b32_e32 v167, v138
	s_waitcnt lgkmcnt(0)
	v_mov_b32_e32 v158, v162
	v_mov_b32_e32 v159, v154
	v_pk_mul_f32 v[158:159], v[166:167], v[158:159]
	v_mov_b32_e32 v168, v146
	v_add_f32_e32 v138, v142, v159
	v_mov_b32_e32 v169, v134
	v_mov_b32_e32 v229, v170
	v_add_f32_e32 v138, v158, v138
	v_pk_mul_f32 v[158:159], v[168:169], v[228:229]
	v_mov_b32_e32 v154, v163
	v_add_f32_e32 v134, v159, v138
	v_add_f32_e32 v158, v158, v134
	v_mul_f32_e32 v134, 0xbfb8aa3b, v158
	v_exp_f32_e32 v134, v134
	v_mov_b32_e32 v138, v151
	v_pk_mul_f32 v[150:151], v[138:139], v[154:155]
	v_mov_b32_e32 v227, v171
	v_add_f32_e32 v134, 1.0, v134
	v_rcp_f32_e32 v159, v134
	v_add_f32_e32 v134, v143, v151
	v_add_f32_e32 v150, v150, v134
	v_mov_b32_e32 v134, v147
	v_pk_mul_f32 v[146:147], v[134:135], v[226:227]
	v_mov_b32_e32 v162, v152
	v_add_f32_e32 v147, v147, v150
	v_add_f32_e32 v150, v146, v147
	v_mul_f32_e32 v146, 0xbfb8aa3b, v150
	v_exp_f32_e32 v146, v146
	v_mul_f32_e32 v147, v158, v159
	v_cndmask_b32_e64 v151, v147, v158, s[4:5]
	v_mov_b32_e32 v163, v140
	v_add_f32_e32 v146, 1.0, v146
	v_rcp_f32_e32 v154, v146
	v_mov_b32_e32 v146, v164
	v_mov_b32_e32 v147, v156
	v_pk_mul_f32 v[146:147], v[162:163], v[146:147]
	v_mov_b32_e32 v170, v148
	v_add_f32_e32 v140, v144, v147
	v_mov_b32_e32 v171, v136
	v_mov_b32_e32 v225, v172
	v_add_f32_e32 v140, v146, v140
	v_pk_mul_f32 v[146:147], v[170:171], v[224:225]
	v_mov_b32_e32 v156, v165
	v_add_f32_e32 v136, v147, v140
	v_add_f32_e32 v148, v146, v136
	v_mov_b32_e32 v140, v153
	v_mul_f32_e32 v136, 0xbfb8aa3b, v148
	v_pk_mul_f32 v[146:147], v[140:141], v[156:157]
	v_exp_f32_e32 v152, v136
	v_add_f32_e32 v136, v145, v147
	v_add_f32_e32 v153, v146, v136
	v_mov_b32_e32 v136, v149
	v_mov_b32_e32 v223, v173
	v_pk_mul_f32 v[146:147], v[136:137], v[222:223]
	v_add_f32_e32 v152, 1.0, v152
	v_add_f32_e32 v147, v147, v153
	v_add_f32_e32 v146, v146, v147
	v_mul_f32_e32 v147, 0xbfb8aa3b, v146
	v_exp_f32_e32 v147, v147
	v_rcp_f32_e32 v152, v152
	v_mul_f32_e32 v149, v150, v154
	v_cndmask_b32_e64 v149, v149, v150, s[4:5]
	v_add_f32_e32 v147, 1.0, v147
	v_rcp_f32_e32 v147, v147
	v_mul_f32_e32 v150, v148, v152
	v_cndmask_b32_e64 v148, v150, v148, s[4:5]
	s_mov_b64 s[2:3], -1
	v_mul_f32_e32 v147, v146, v147
	v_cndmask_b32_e64 v147, v147, v146, s[4:5]
	v_cvt_pk_bf16_f32 v146, v151, v149
	v_cvt_pk_bf16_f32 v147, v148, v147
	v_lshlrev_b64 v[148:149], v182, v[194:195]
	v_lshl_add_u64 v[222:223], v[148:149], 1, v[220:221]
	s_and_b64 vcc, exec, s[18:19]
	v_mov_b32_e32 v172, v46
	v_mov_b32_e32 v164, v47
	v_mov_b32_e32 v156, v48
	v_mov_b32_e32 v154, v49
	v_mov_b32_e32 v70, v146
	v_mov_b32_e32 v71, v147
	s_cbranch_vccnz .LBB0_1103
	v_add_u32_e32 v147, 0xffffe090, v202
	v_ashrrev_i32_e32 v147, 2, v147
	v_lshl_add_u32 v147, v147, 1, v147
	v_mad_i64_i32 v[148:149], s[2:3], v147, s47, 0
	v_lshl_add_u64 v[148:149], v[148:149], 2, v[208:209]
	v_lshl_add_u64 v[150:151], v[148:149], 0, s[24:25]
	s_lshl_b32 s2, s27, 2
	s_mov_b32 s3, s25
	global_load_dwordx4 v[158:161], v[148:149], off
	s_nop 0
	global_load_dwordx4 v[150:153], v[150:151], off
	v_lshl_add_u64 v[148:149], v[148:149], 0, s[2:3]
	global_load_dwordx4 v[154:157], v[148:149], off
	v_mov_b32_e32 v164, 0
	v_mov_b32_e32 v165, 0
	v_mov_b32_e32 v146, 0
	v_mov_b32_dpp v164, v46 row_ror:1 row_mask:0xf bank_mask:0xf
	v_mov_b32_dpp v165, v46 row_ror:2 row_mask:0xf bank_mask:0xf
	v_mov_b32_dpp v146, v46 row_ror:3 row_mask:0xf bank_mask:0xf
	v_cmp_lt_i32_e32 vcc, 1, v205
	s_and_saveexec_b64 s[2:3], vcc
	s_xor_b64 s[2:3], exec, s[2:3]
	s_cbranch_execz .LBB0_1066
	v_cmp_gt_i32_e32 vcc, 3, v205
	s_and_saveexec_b64 s[20:21], vcc
	s_cbranch_execz .LBB0_1065
	s_waitcnt vmcnt(0)
	v_mov_b32_e32 v146, v154

; __device__ __forceinline__ unsigned cvt_pk_bf16(float lo, float hi) { unsigned r; asm("v_cvt_pk_bf16_f32 %0, %1, %2" : "=v"(r) : "v"(lo), "v"(hi)); return r; }
; __device__ __forceinline__ float siluf_(float x) { return x * sigmoidf_(x); }
; __device__ __forceinline__ float dpp_ror1(float v) { return __builtin_bit_cast(float, __builtin_amdgcn_update_dpp(0, __builtin_bit_cast(int, v), 0x121, 0xf, 0xf, false)); }
; __device__ __forceinline__ float dpp_ror2(float v) { return __builtin_bit_cast(float, __builtin_amdgcn_update_dpp(0, __builtin_bit_cast(int, v), 0x122, 0xf, 0xf, false)); }
; __device__ __forceinline__ float dpp_ror3(float v) { return __builtin_bit_cast(float, __builtin_amdgcn_update_dpp(0, __builtin_bit_cast(int, v), 0x123, 0xf, 0xf, false)); }
;     __device__ __forceinline__ void operator()(f32x4 (&acc)[2][2][4][2], const pg8::Unit& u, int wr, int wc, int fr, int fq) const {
;     ...
;                     for (int m = 0; m < 4; ++m) { const int row = row0 + ai * 128 + m * 16; const f32x4 g = acc[ai][bj][m][n]; f32x4 p1, p2, p3;
;                         if (prompt) { const f32x4 gp = (m == 0) ? hal[n] : acc[ai][bj][m > 0 ? m - 1 : 0][n];
; #pragma unroll
;                             for (int j = 0; j < 4; ++j) { p1[j] = dpp_ror1(fr == 15 ? gp[j] : g[j]); p2[j] = dpp_ror2(fr >= 14 ? gp[j] : g[j]); p3[j] = dpp_ror3(fr >= 13 ? gp[j] : g[j]); } }
;                         else { const int t = fr & 3; const float* sp = stp + (size_t)((row - MP) >> 2) * 3 * CW + ch;
;                             const f32x4 b0 = *(const f32x4*)sp, b1 = *(const f32x4*)(sp + CW), b2 = *(const f32x4*)(sp + 2 * CW);
; #pragma unroll
;                             for (int j = 0; j < 4; ++j) { const float r1 = dpp_ror1(g[j]), r2 = dpp_ror2(g[j]), r3 = dpp_ror3(g[j]);
;                                 p1[j] = t >= 1 ? r1 : b2[j]; p2[j] = t >= 2 ? r2 : (t == 1 ? b2[j] : b1[j]); p3[j] = t >= 3 ? r3 : (t == 2 ? b2[j] : (t == 1 ? b1[j] : b0[j])); } }
;                         float o[4];
; #pragma unroll
;                         for (int j = 0; j < 4; ++j) { const float y = bb[j] + w0[j] * p3[j] + w1[j] * p2[j] + w2[j] * p1[j] + w3[j] * g[j]; o[j] = is_rg ? y : siluf_(y); }
;                         u32x2 w; w.x = cvt_pk_bf16(o[0], o[1]); w.y = cvt_pk_bf16(o[2], o[3]);
;                         *(u32x2*)(dst + (size_t)row * ld + bj * 128 + 4 * n) = w; }
.LBB0_1105:
	v_mov_b32_e32 v224, v150
	v_mov_b32_e32 v225, v146
	v_pk_mul_f32 v[224:225], v[166:167], v[224:225]
	v_mov_b32_e32 v173, v158
	v_add_f32_e32 v146, v142, v225
	v_add_f32_e32 v146, v224, v146
	v_pk_mul_f32 v[172:173], v[168:169], v[172:173]
	v_mov_b32_e32 v165, v159
	v_add_f32_e32 v146, v173, v146
	v_add_f32_e32 v150, v172, v146
	v_mul_f32_e32 v146, 0xbfb8aa3b, v150
	v_exp_f32_e32 v146, v146
	v_mov_b32_e32 v157, v160
	s_mov_b64 s[2:3], -1
	s_and_b64 vcc, exec, s[18:19]
	v_add_f32_e32 v146, 1.0, v146
	v_rcp_f32_e32 v155, v146
	v_mov_b32_e32 v146, v151
	v_pk_mul_f32 v[146:147], v[138:139], v[146:147]
	v_mov_b32_e32 v172, v26
	v_add_f32_e32 v147, v143, v147
	v_add_f32_e32 v151, v146, v147
	v_pk_mul_f32 v[146:147], v[134:135], v[164:165]
	v_mov_b32_e32 v164, v27
	v_add_f32_e32 v147, v147, v151
	v_add_f32_e32 v151, v146, v147
	v_mul_f32_e32 v146, 0xbfb8aa3b, v151
	v_exp_f32_e32 v146, v146
	v_mul_f32_e32 v147, v150, v155
	v_cndmask_b32_e64 v150, v147, v150, s[4:5]
	v_mov_b32_e32 v147, v148
	v_add_f32_e32 v146, 1.0, v146
	v_rcp_f32_e32 v158, v146
	v_mov_b32_e32 v146, v152
	v_pk_mul_f32 v[146:147], v[162:163], v[146:147]
	v_mov_b32_e32 v155, v161
	v_add_f32_e32 v147, v144, v147
	v_add_f32_e32 v148, v146, v147
	v_pk_mul_f32 v[146:147], v[170:171], v[156:157]
	s_nop 0
	v_add_f32_e32 v147, v147, v148
	v_add_f32_e32 v152, v146, v147
	v_mul_f32_e32 v146, 0xbfb8aa3b, v152
	v_mov_b32_e32 v148, v153
	v_exp_f32_e32 v156, v146
	v_pk_mul_f32 v[146:147], v[140:141], v[148:149]
	v_add_f32_e32 v149, 1.0, v156
	v_add_f32_e32 v147, v145, v147
	v_add_f32_e32 v148, v146, v147
	v_pk_mul_f32 v[146:147], v[136:137], v[154:155]
	v_rcp_f32_e32 v149, v149
	v_add_f32_e32 v147, v147, v148
	v_add_f32_e32 v146, v146, v147
	v_mul_f32_e32 v147, 0xbfb8aa3b, v146
	v_exp_f32_e32 v147, v147
	v_mul_f32_e32 v148, v151, v158
	v_mul_f32_e32 v149, v152, v149
	v_cndmask_b32_e64 v148, v148, v151, s[4:5]
	v_add_f32_e32 v147, 1.0, v147
	v_rcp_f32_e32 v147, v147
	v_cndmask_b32_e64 v149, v149, v152, s[4:5]
	v_mov_b32_e32 v156, v28
	v_mov_b32_e32 v154, v29
	v_mul_f32_e32 v147, v146, v147
	v_cndmask_b32_e64 v147, v147, v146, s[4:5]
	v_cvt_pk_bf16_f32 v146, v150, v148
	v_cvt_pk_bf16_f32 v147, v149, v147
	v_lshlrev_b64 v[148:149], v182, v[192:193]
	v_lshl_add_u64 v[224:225], v[148:149], 1, v[220:221]
	v_mov_b32_e32 v62, v146
	v_mov_b32_e32 v63, v147
	s_cbranch_vccnz .LBB0_1147
	v_add_u32_e32 v147, 0xffffe0a0, v202
	v_ashrrev_i32_e32 v147, 2, v147
	v_lshl_add_u32 v147, v147, 1, v147
	v_mad_i64_i32 v[148:149], s[2:3], v147, s47, 0
	v_lshl_add_u64 v[148:149], v[148:149], 2, v[208:209]
	v_lshl_add_u64 v[150:151], v[148:149], 0, s[24:25]
	s_lshl_b32 s2, s27, 2
	s_mov_b32 s3, s25
	global_load_dwordx4 v[158:161], v[148:149], off
	s_nop 0
	global_load_dwordx4 v[150:153], v[150:151], off
	v_lshl_add_u64 v[148:149], v[148:149], 0, s[2:3]
	global_load_dwordx4 v[154:157], v[148:149], off
	v_mov_b32_e32 v164, 0
	v_mov_b32_e32 v165, 0
	v_mov_b32_e32 v146, 0
	v_mov_b32_dpp v164, v26 row_ror:1 row_mask:0xf bank_mask:0xf
	v_mov_b32_dpp v165, v26 row_ror:2 row_mask:0xf bank_mask:0xf
	v_mov_b32_dpp v146, v26 row_ror:3 row_mask:0xf bank_mask:0xf
	v_cmp_lt_i32_e32 vcc, 1, v205
	s_and_saveexec_b64 s[2:3], vcc
	s_xor_b64 s[2:3], exec, s[2:3]
	s_cbranch_execz .LBB0_1110
	v_cmp_gt_i32_e32 vcc, 3, v205
	s_and_saveexec_b64 s[20:21], vcc
	s_cbranch_execz .LBB0_1109
	s_waitcnt vmcnt(0)
	v_mov_b32_e32 v146, v154

; __device__ __forceinline__ unsigned cvt_pk_bf16(float lo, float hi) { unsigned r; asm("v_cvt_pk_bf16_f32 %0, %1, %2" : "=v"(r) : "v"(lo), "v"(hi)); return r; }
; __device__ __forceinline__ float siluf_(float x) { return x * sigmoidf_(x); }
; __device__ __forceinline__ float dpp_ror1(float v) { return __builtin_bit_cast(float, __builtin_amdgcn_update_dpp(0, __builtin_bit_cast(int, v), 0x121, 0xf, 0xf, false)); }
; __device__ __forceinline__ float dpp_ror2(float v) { return __builtin_bit_cast(float, __builtin_amdgcn_update_dpp(0, __builtin_bit_cast(int, v), 0x122, 0xf, 0xf, false)); }
; __device__ __forceinline__ float dpp_ror3(float v) { return __builtin_bit_cast(float, __builtin_amdgcn_update_dpp(0, __builtin_bit_cast(int, v), 0x123, 0xf, 0xf, false)); }
;     __device__ __forceinline__ void operator()(f32x4 (&acc)[2][2][4][2], const pg8::Unit& u, int wr, int wc, int fr, int fq) const {
;     ...
;                     for (int m = 0; m < 4; ++m) { const int row = row0 + ai * 128 + m * 16; const f32x4 g = acc[ai][bj][m][n]; f32x4 p1, p2, p3;
;                         if (prompt) { const f32x4 gp = (m == 0) ? hal[n] : acc[ai][bj][m > 0 ? m - 1 : 0][n];
; #pragma unroll
;                             for (int j = 0; j < 4; ++j) { p1[j] = dpp_ror1(fr == 15 ? gp[j] : g[j]); p2[j] = dpp_ror2(fr >= 14 ? gp[j] : g[j]); p3[j] = dpp_ror3(fr >= 13 ? gp[j] : g[j]); } }
;                         else { const int t = fr & 3; const float* sp = stp + (size_t)((row - MP) >> 2) * 3 * CW + ch;
;                             const f32x4 b0 = *(const f32x4*)sp, b1 = *(const f32x4*)(sp + CW), b2 = *(const f32x4*)(sp + 2 * CW);
; #pragma unroll
;                             for (int j = 0; j < 4; ++j) { const float r1 = dpp_ror1(g[j]), r2 = dpp_ror2(g[j]), r3 = dpp_ror3(g[j]);
;                                 p1[j] = t >= 1 ? r1 : b2[j]; p2[j] = t >= 2 ? r2 : (t == 1 ? b2[j] : b1[j]); p3[j] = t >= 3 ? r3 : (t == 2 ? b2[j] : (t == 1 ? b1[j] : b0[j])); } }
;                         float o[4];
; #pragma unroll
;                         for (int j = 0; j < 4; ++j) { const float y = bb[j] + w0[j] * p3[j] + w1[j] * p2[j] + w2[j] * p1[j] + w3[j] * g[j]; o[j] = is_rg ? y : siluf_(y); }
;                         u32x2 w; w.x = cvt_pk_bf16(o[0], o[1]); w.y = cvt_pk_bf16(o[2], o[3]);
;                         *(u32x2*)(dst + (size_t)row * ld + bj * 128 + 4 * n) = w; }
.LBB0_1149:
	v_mov_b32_e32 v226, v150
	v_mov_b32_e32 v227, v146
	v_pk_mul_f32 v[226:227], v[166:167], v[226:227]
	v_mov_b32_e32 v173, v158
	v_add_f32_e32 v146, v142, v227
	v_add_f32_e32 v146, v226, v146
	v_pk_mul_f32 v[172:173], v[168:169], v[172:173]
	v_mov_b32_e32 v165, v159
	v_add_f32_e32 v146, v173, v146
	v_add_f32_e32 v150, v172, v146
	v_mul_f32_e32 v146, 0xbfb8aa3b, v150
	v_exp_f32_e32 v146, v146
	v_mov_b32_e32 v157, v160
	s_mov_b64 s[2:3], -1
	s_and_b64 vcc, exec, s[18:19]
	v_add_f32_e32 v146, 1.0, v146
	v_rcp_f32_e32 v155, v146
	v_mov_b32_e32 v146, v151
	v_pk_mul_f32 v[146:147], v[138:139], v[146:147]
	v_mov_b32_e32 v172, v14
	v_add_f32_e32 v147, v143, v147
	v_add_f32_e32 v151, v146, v147
	v_pk_mul_f32 v[146:147], v[134:135], v[164:165]
	v_mov_b32_e32 v164, v15
	v_add_f32_e32 v147, v147, v151
	v_add_f32_e32 v151, v146, v147
	v_mul_f32_e32 v146, 0xbfb8aa3b, v151
	v_exp_f32_e32 v146, v146
	v_mul_f32_e32 v147, v150, v155
	v_cndmask_b32_e64 v150, v147, v150, s[4:5]
	v_mov_b32_e32 v147, v148
	v_add_f32_e32 v146, 1.0, v146
	v_rcp_f32_e32 v158, v146
	v_mov_b32_e32 v146, v152
	v_pk_mul_f32 v[146:147], v[162:163], v[146:147]
	v_mov_b32_e32 v155, v161
	v_add_f32_e32 v147, v144, v147
	v_add_f32_e32 v148, v146, v147
	v_pk_mul_f32 v[146:147], v[170:171], v[156:157]
	s_nop 0
	v_add_f32_e32 v147, v147, v148
	v_add_f32_e32 v152, v146, v147
	v_mul_f32_e32 v146, 0xbfb8aa3b, v152
	v_mov_b32_e32 v148, v153
	v_exp_f32_e32 v156, v146
	v_pk_mul_f32 v[146:147], v[140:141], v[148:149]
	v_add_f32_e32 v149, 1.0, v156
	v_add_f32_e32 v147, v145, v147
	v_add_f32_e32 v148, v146, v147
	v_pk_mul_f32 v[146:147], v[136:137], v[154:155]
	v_rcp_f32_e32 v149, v149
	v_add_f32_e32 v147, v147, v148
	v_add_f32_e32 v146, v146, v147
	v_mul_f32_e32 v147, 0xbfb8aa3b, v146
	v_exp_f32_e32 v147, v147
	v_mul_f32_e32 v148, v151, v158
	v_mul_f32_e32 v149, v152, v149
	v_cndmask_b32_e64 v148, v148, v151, s[4:5]
	v_add_f32_e32 v147, 1.0, v147
	v_rcp_f32_e32 v147, v147
	v_cndmask_b32_e64 v149, v149, v152, s[4:5]
	v_mov_b32_e32 v156, v16
	v_mov_b32_e32 v154, v17
	v_mul_f32_e32 v147, v146, v147
	v_cndmask_b32_e64 v147, v147, v146, s[4:5]
	v_cvt_pk_bf16_f32 v146, v150, v148
	v_cvt_pk_bf16_f32 v147, v149, v147
	v_lshlrev_b64 v[148:149], v182, v[190:191]
	v_lshl_add_u64 v[226:227], v[148:149], 1, v[220:221]
	v_mov_b32_e32 v46, v146
	v_mov_b32_e32 v47, v147
	s_cbranch_vccnz .LBB0_1191
	v_add_u32_e32 v147, 0xffffe0b0, v202
	v_ashrrev_i32_e32 v147, 2, v147
	v_lshl_add_u32 v147, v147, 1, v147
	v_mad_i64_i32 v[148:149], s[2:3], v147, s47, 0
	v_lshl_add_u64 v[148:149], v[148:149], 2, v[208:209]
	v_lshl_add_u64 v[150:151], v[148:149], 0, s[24:25]
	s_lshl_b32 s2, s27, 2
	s_mov_b32 s3, s25
	global_load_dwordx4 v[158:161], v[148:149], off
	s_nop 0
	global_load_dwordx4 v[150:153], v[150:151], off
	v_lshl_add_u64 v[148:149], v[148:149], 0, s[2:3]
	global_load_dwordx4 v[154:157], v[148:149], off
	v_mov_b32_e32 v164, 0
	v_mov_b32_e32 v165, 0
	v_mov_b32_e32 v146, 0
	v_mov_b32_dpp v164, v14 row_ror:1 row_mask:0xf bank_mask:0xf
	v_mov_b32_dpp v165, v14 row_ror:2 row_mask:0xf bank_mask:0xf
	v_mov_b32_dpp v146, v14 row_ror:3 row_mask:0xf bank_mask:0xf
	v_cmp_lt_i32_e32 vcc, 1, v205
	s_and_saveexec_b64 s[2:3], vcc
	s_xor_b64 s[2:3], exec, s[2:3]
	s_cbranch_execz .LBB0_1154
	v_cmp_gt_i32_e32 vcc, 3, v205
	s_and_saveexec_b64 s[20:21], vcc
	s_cbranch_execz .LBB0_1153
	s_waitcnt vmcnt(0)
	v_mov_b32_e32 v146, v154

; __device__ __forceinline__ unsigned cvt_pk_bf16(float lo, float hi) { unsigned r; asm("v_cvt_pk_bf16_f32 %0, %1, %2" : "=v"(r) : "v"(lo), "v"(hi)); return r; }
; __device__ __forceinline__ float siluf_(float x) { return x * sigmoidf_(x); }
; __device__ __forceinline__ float dpp_ror1(float v) { return __builtin_bit_cast(float, __builtin_amdgcn_update_dpp(0, __builtin_bit_cast(int, v), 0x121, 0xf, 0xf, false)); }
;     __device__ __forceinline__ void operator()(f32x4 (&acc)[2][2][4][2], const pg8::Unit& u, int wr, int wc, int fr, int fq) const {
;     ...
;                     const f32x4 w0 = *(const f32x4*)(cw + ch), w1 = *(const f32x4*)(cw + CW + ch), w2 = *(const f32x4*)(cw + 2 * CW + ch), w3 = *(const f32x4*)(cw + 3 * CW + ch), bb = *(const f32x4*)(cb + ch);
; #pragma unroll
;                     for (int m = 0; m < 4; ++m) { const int row = row0 + ai * 128 + m * 16; const f32x4 g = acc[ai][bj][m][n]; f32x4 p1, p2, p3;
;                         if (prompt) { const f32x4 gp = (m == 0) ? hal[n] : acc[ai][bj][m > 0 ? m - 1 : 0][n];
; #pragma unroll
;                             for (int j = 0; j < 4; ++j) { p1[j] = dpp_ror1(fr == 15 ? gp[j] : g[j]); p2[j] = dpp_ror2(fr >= 14 ? gp[j] : g[j]); p3[j] = dpp_ror3(fr >= 13 ? gp[j] : g[j]); } }
;                         else { const int t = fr & 3; const float* sp = stp + (size_t)((row - MP) >> 2) * 3 * CW + ch;
;                             const f32x4 b0 = *(const f32x4*)sp, b1 = *(const f32x4*)(sp + CW), b2 = *(const f32x4*)(sp + 2 * CW);
; #pragma unroll
;                             for (int j = 0; j < 4; ++j) { const float r1 = dpp_ror1(g[j]), r2 = dpp_ror2(g[j]), r3 = dpp_ror3(g[j]);
;                                 p1[j] = t >= 1 ? r1 : b2[j]; p2[j] = t >= 2 ? r2 : (t == 1 ? b2[j] : b1[j]); p3[j] = t >= 3 ? r3 : (t == 2 ? b2[j] : (t == 1 ? b1[j] : b0[j])); } }
;                         float o[4];
; #pragma unroll
;                         for (int j = 0; j < 4; ++j) { const float y = bb[j] + w0[j] * p3[j] + w1[j] * p2[j] + w2[j] * p1[j] + w3[j] * g[j]; o[j] = is_rg ? y : siluf_(y); }
;                         u32x2 w; w.x = cvt_pk_bf16(o[0], o[1]); w.y = cvt_pk_bf16(o[2], o[3]);
;                         *(u32x2*)(dst + (size_t)row * ld + bj * 128 + 4 * n) = w; }
.LBB0_1193:
	v_mov_b32_e32 v228, v150
	v_mov_b32_e32 v229, v146
	v_pk_mul_f32 v[166:167], v[166:167], v[228:229]
	v_mov_b32_e32 v173, v158
	v_add_f32_e32 v142, v142, v167
	v_add_f32_e32 v142, v166, v142
	v_pk_mul_f32 v[166:167], v[168:169], v[172:173]
	v_mov_b32_e32 v165, v159
	v_add_f32_e32 v142, v167, v142
	v_add_f32_e32 v142, v166, v142
	v_mul_f32_e32 v146, 0xbfb8aa3b, v142
	v_exp_f32_e32 v146, v146
	v_pk_mul_f32 v[134:135], v[134:135], v[164:165]
	v_mov_b32_e32 v157, v160
	v_mov_b32_e32 v155, v161
	v_add_f32_e32 v146, 1.0, v146
	v_rcp_f32_e32 v150, v146
	v_mov_b32_e32 v146, v151
	v_pk_mul_f32 v[138:139], v[138:139], v[146:147]
	s_mov_b64 s[2:3], -1
	v_add_f32_e32 v139, v143, v139
	v_add_f32_e32 v138, v138, v139
	v_add_f32_e32 v135, v135, v138
	v_add_f32_e32 v138, v134, v135
	v_mul_f32_e32 v134, 0xbfb8aa3b, v138
	v_exp_f32_e32 v134, v134
	v_mul_f32_e32 v135, v142, v150
	v_cndmask_b32_e64 v139, v135, v142, s[4:5]
	v_mov_b32_e32 v135, v148
	v_add_f32_e32 v134, 1.0, v134
	v_rcp_f32_e32 v142, v134
	v_mov_b32_e32 v134, v152
	v_pk_mul_f32 v[134:135], v[162:163], v[134:135]
	v_mov_b32_e32 v148, v153
	v_add_f32_e32 v135, v144, v135
	v_add_f32_e32 v143, v134, v135
	v_pk_mul_f32 v[134:135], v[170:171], v[156:157]
	s_and_b64 vcc, exec, s[18:19]
	v_add_f32_e32 v135, v135, v143
	v_add_f32_e32 v143, v134, v135
	v_mul_f32_e32 v134, 0xbfb8aa3b, v143
	v_exp_f32_e32 v144, v134
	v_pk_mul_f32 v[134:135], v[140:141], v[148:149]
	v_mov_b32_e32 v230, v58
	v_add_f32_e32 v135, v145, v135
	v_add_f32_e32 v140, v134, v135
	v_pk_mul_f32 v[134:135], v[136:137], v[154:155]
	v_add_f32_e32 v137, 1.0, v144
	v_add_f32_e32 v135, v135, v140
	v_add_f32_e32 v134, v134, v135
	v_mul_f32_e32 v135, 0xbfb8aa3b, v134
	v_exp_f32_e32 v135, v135
	v_rcp_f32_e32 v137, v137
	v_mul_f32_e32 v136, v138, v142
	v_cndmask_b32_e64 v136, v136, v138, s[4:5]
	v_add_f32_e32 v135, 1.0, v135
	v_rcp_f32_e32 v135, v135
	v_mul_f32_e32 v137, v143, v137
	v_cndmask_b32_e64 v137, v137, v143, s[4:5]
	v_mov_b32_e32 v228, v59
	v_mul_f32_e32 v135, v134, v135
	v_cndmask_b32_e64 v135, v135, v134, s[4:5]
	v_cvt_pk_bf16_f32 v134, v139, v136
	v_cvt_pk_bf16_f32 v135, v137, v135
	v_lshlrev_b64 v[136:137], v182, v[188:189]
	v_lshl_add_u64 v[220:221], v[136:137], 1, v[220:221]
	v_mov_b32_e32 v26, v134
	v_mov_b32_e32 v27, v135
	global_load_dwordx4 v[138:141], v[210:211], off offset:16
	global_load_dwordx4 v[150:153], v[212:213], off offset:16
	global_load_dwordx4 v[134:137], v[214:215], off offset:16
	global_load_dwordx4 v[146:149], v[216:217], off offset:16
	global_load_dwordx4 v[142:145], v[218:219], off offset:16
	v_mov_b32_e32 v172, v60
	v_mov_b32_e32 v170, v61
	s_cbranch_vccnz .LBB0_1235
	v_add_u32_e32 v155, 0xffffe080, v202
	v_ashrrev_i32_e32 v155, 2, v155
	v_lshl_add_u32 v155, v155, 1, v155
	v_mad_i64_i32 v[156:157], s[2:3], v155, s47, 0
	v_lshl_add_u64 v[156:157], v[156:157], 2, v[208:209]
	v_lshl_add_u64 v[158:159], v[156:157], 0, s[24:25]
	s_lshl_b32 s2, s27, 2
	s_mov_b32 s3, s25
	global_load_dwordx4 v[166:169], v[156:157], off offset:16
	s_nop 0
	global_load_dwordx4 v[158:161], v[158:159], off offset:16
	v_lshl_add_u64 v[156:157], v[156:157], 0, s[2:3]
	global_load_dwordx4 v[162:165], v[156:157], off offset:16
	v_mov_b32_e32 v170, 0
	v_mov_b32_e32 v171, 0
	v_mov_b32_e32 v154, 0
	v_mov_b32_dpp v170, v58 row_ror:1 row_mask:0xf bank_mask:0xf
	v_mov_b32_dpp v171, v58 row_ror:2 row_mask:0xf bank_mask:0xf
	v_mov_b32_dpp v154, v58 row_ror:3 row_mask:0xf bank_mask:0xf
	v_cmp_lt_i32_e32 vcc, 1, v205
	s_and_saveexec_b64 s[2:3], vcc
	s_xor_b64 s[2:3], exec, s[2:3]
	s_cbranch_execz .LBB0_1198
	v_cmp_gt_i32_e32 vcc, 3, v205
	s_and_saveexec_b64 s[20:21], vcc
	s_cbranch_execz .LBB0_1197
	s_waitcnt vmcnt(0)
	v_mov_b32_e32 v154, v162

; __device__ __forceinline__ unsigned cvt_pk_bf16(float lo, float hi) { unsigned r; asm("v_cvt_pk_bf16_f32 %0, %1, %2" : "=v"(r) : "v"(lo), "v"(hi)); return r; }
; __device__ __forceinline__ float siluf_(float x) { return x * sigmoidf_(x); }
; __device__ __forceinline__ float dpp_ror1(float v) { return __builtin_bit_cast(float, __builtin_amdgcn_update_dpp(0, __builtin_bit_cast(int, v), 0x121, 0xf, 0xf, false)); }
; __device__ __forceinline__ float dpp_ror2(float v) { return __builtin_bit_cast(float, __builtin_amdgcn_update_dpp(0, __builtin_bit_cast(int, v), 0x122, 0xf, 0xf, false)); }
; __device__ __forceinline__ float dpp_ror3(float v) { return __builtin_bit_cast(float, __builtin_amdgcn_update_dpp(0, __builtin_bit_cast(int, v), 0x123, 0xf, 0xf, false)); }
;     __device__ __forceinline__ void operator()(f32x4 (&acc)[2][2][4][2], const pg8::Unit& u, int wr, int wc, int fr, int fq) const {
;     ...
;                     for (int m = 0; m < 4; ++m) { const int row = row0 + ai * 128 + m * 16; const f32x4 g = acc[ai][bj][m][n]; f32x4 p1, p2, p3;
;                         if (prompt) { const f32x4 gp = (m == 0) ? hal[n] : acc[ai][bj][m > 0 ? m - 1 : 0][n];
; #pragma unroll
;                             for (int j = 0; j < 4; ++j) { p1[j] = dpp_ror1(fr == 15 ? gp[j] : g[j]); p2[j] = dpp_ror2(fr >= 14 ? gp[j] : g[j]); p3[j] = dpp_ror3(fr >= 13 ? gp[j] : g[j]); } }
;                         else { const int t = fr & 3; const float* sp = stp + (size_t)((row - MP) >> 2) * 3 * CW + ch;
;                             const f32x4 b0 = *(const f32x4*)sp, b1 = *(const f32x4*)(sp + CW), b2 = *(const f32x4*)(sp + 2 * CW);
; #pragma unroll
;                             for (int j = 0; j < 4; ++j) { const float r1 = dpp_ror1(g[j]), r2 = dpp_ror2(g[j]), r3 = dpp_ror3(g[j]);
;                                 p1[j] = t >= 1 ? r1 : b2[j]; p2[j] = t >= 2 ? r2 : (t == 1 ? b2[j] : b1[j]); p3[j] = t >= 3 ? r3 : (t == 2 ? b2[j] : (t == 1 ? b1[j] : b0[j])); } }
;                         float o[4];
; #pragma unroll
;                         for (int j = 0; j < 4; ++j) { const float y = bb[j] + w0[j] * p3[j] + w1[j] * p2[j] + w2[j] * p1[j] + w3[j] * g[j]; o[j] = is_rg ? y : siluf_(y); }
;                         u32x2 w; w.x = cvt_pk_bf16(o[0], o[1]); w.y = cvt_pk_bf16(o[2], o[3]);
;                         *(u32x2*)(dst + (size_t)row * ld + bj * 128 + 4 * n) = w; }
.LBB0_1237:
	s_waitcnt vmcnt(0)
	v_mov_b32_e32 v162, v150
	v_mov_b32_e32 v163, v138
	v_mov_b32_e32 v130, v158
	v_mov_b32_e32 v131, v154
	v_pk_mul_f32 v[130:131], v[162:163], v[130:131]
	v_mov_b32_e32 v164, v146
	v_add_f32_e32 v131, v142, v131
	v_mov_b32_e32 v165, v134
	v_mov_b32_e32 v231, v166
	v_add_f32_e32 v132, v130, v131
	v_pk_mul_f32 v[130:131], v[164:165], v[230:231]
	v_mov_b32_e32 v138, v151
	v_add_f32_e32 v131, v131, v132
	v_add_f32_e32 v132, v130, v131
	v_mul_f32_e32 v130, 0xbfb8aa3b, v132
	v_exp_f32_e32 v130, v130
	v_mov_b32_e32 v154, v159
	v_mov_b32_e32 v134, v147
	v_mov_b32_e32 v229, v167
	v_add_f32_e32 v130, 1.0, v130
	v_rcp_f32_e32 v133, v130
	v_pk_mul_f32 v[130:131], v[138:139], v[154:155]
	v_mov_b32_e32 v158, v152
	v_add_f32_e32 v131, v143, v131
	v_add_f32_e32 v146, v130, v131
	v_pk_mul_f32 v[130:131], v[134:135], v[228:229]
	v_mov_b32_e32 v159, v140
	v_add_f32_e32 v131, v131, v146
	v_add_f32_e32 v146, v130, v131
	v_mul_f32_e32 v130, 0xbfb8aa3b, v146
	v_exp_f32_e32 v130, v130
	v_mul_f32_e32 v131, v132, v133
	v_cndmask_b32_e64 v132, v131, v132, s[4:5]
	v_mov_b32_e32 v131, v156
	v_add_f32_e32 v130, 1.0, v130
	v_rcp_f32_e32 v133, v130
	v_mov_b32_e32 v130, v160
	v_pk_mul_f32 v[130:131], v[158:159], v[130:131]
	v_mov_b32_e32 v166, v148
	v_add_f32_e32 v131, v144, v131
	v_mov_b32_e32 v167, v136
	v_mov_b32_e32 v173, v168
	v_add_f32_e32 v140, v130, v131
	v_pk_mul_f32 v[130:131], v[166:167], v[172:173]
	v_mov_b32_e32 v156, v161
	v_add_f32_e32 v131, v131, v140
	v_add_f32_e32 v147, v130, v131
	v_mul_f32_e32 v130, 0xbfb8aa3b, v147
	v_mov_b32_e32 v140, v153
	v_exp_f32_e32 v148, v130
	v_pk_mul_f32 v[130:131], v[140:141], v[156:157]
	v_mov_b32_e32 v136, v149
	v_add_f32_e32 v131, v145, v131
	v_mov_b32_e32 v171, v169
	v_add_f32_e32 v150, v130, v131
	v_pk_mul_f32 v[130:131], v[136:137], v[170:171]
	v_add_f32_e32 v148, 1.0, v148
	v_add_f32_e32 v131, v131, v150
	v_add_f32_e32 v130, v130, v131
	v_mul_f32_e32 v131, 0xbfb8aa3b, v130
	v_exp_f32_e32 v131, v131
	v_rcp_f32_e32 v148, v148
	v_mul_f32_e32 v133, v146, v133
	v_cndmask_b32_e64 v133, v133, v146, s[4:5]
	v_add_f32_e32 v131, 1.0, v131
	v_rcp_f32_e32 v131, v131
	v_mul_f32_e32 v146, v147, v148
	v_cndmask_b32_e64 v146, v146, v147, s[4:5]
	s_mov_b64 s[2:3], -1
	v_mul_f32_e32 v131, v130, v131
	v_cndmask_b32_e64 v131, v131, v130, s[4:5]
	v_cvt_pk_bf16_f32 v130, v132, v133
	v_cvt_pk_bf16_f32 v131, v146, v131
	s_and_b64 vcc, exec, s[18:19]
	v_mov_b32_e32 v168, v42
	v_mov_b32_e32 v160, v43
	v_mov_b32_e32 v152, v44
	v_mov_b32_e32 v150, v45
	v_mov_b32_e32 v72, v130
	v_mov_b32_e32 v73, v131
	flat_store_dwordx4 v[222:223], v[70:73]
	s_cbranch_vccnz .LBB0_1279
	v_add_u32_e32 v131, 0xffffe090, v202
	v_ashrrev_i32_e32 v131, 2, v131
	v_lshl_add_u32 v131, v131, 1, v131
	v_mad_i64_i32 v[132:133], s[2:3], v131, s47, 0
	v_lshl_add_u64 v[132:133], v[132:133], 2, v[208:209]
	v_lshl_add_u64 v[146:147], v[132:133], 0, s[24:25]
	s_lshl_b32 s2, s27, 2
	s_mov_b32 s3, s25
	global_load_dwordx4 v[154:157], v[132:133], off offset:16
	s_nop 0
	global_load_dwordx4 v[146:149], v[146:147], off offset:16
	v_lshl_add_u64 v[132:133], v[132:133], 0, s[2:3]
	global_load_dwordx4 v[150:153], v[132:133], off offset:16
	v_mov_b32_e32 v160, 0
	v_mov_b32_e32 v161, 0
	v_mov_b32_e32 v130, 0
	v_mov_b32_dpp v160, v42 row_ror:1 row_mask:0xf bank_mask:0xf
	v_mov_b32_dpp v161, v42 row_ror:2 row_mask:0xf bank_mask:0xf
	v_mov_b32_dpp v130, v42 row_ror:3 row_mask:0xf bank_mask:0xf
	v_cmp_lt_i32_e32 vcc, 1, v205
	s_and_saveexec_b64 s[2:3], vcc
	s_xor_b64 s[2:3], exec, s[2:3]
	s_cbranch_execz .LBB0_1242
	v_cmp_gt_i32_e32 vcc, 3, v205
	s_and_saveexec_b64 s[20:21], vcc
	s_cbranch_execz .LBB0_1241
	s_waitcnt vmcnt(0)
	v_mov_b32_e32 v130, v150

; __device__ __forceinline__ unsigned cvt_pk_bf16(float lo, float hi) { unsigned r; asm("v_cvt_pk_bf16_f32 %0, %1, %2" : "=v"(r) : "v"(lo), "v"(hi)); return r; }
; __device__ __forceinline__ float siluf_(float x) { return x * sigmoidf_(x); }
; __device__ __forceinline__ float dpp_ror1(float v) { return __builtin_bit_cast(float, __builtin_amdgcn_update_dpp(0, __builtin_bit_cast(int, v), 0x121, 0xf, 0xf, false)); }
; __device__ __forceinline__ float dpp_ror2(float v) { return __builtin_bit_cast(float, __builtin_amdgcn_update_dpp(0, __builtin_bit_cast(int, v), 0x122, 0xf, 0xf, false)); }
; __device__ __forceinline__ float dpp_ror3(float v) { return __builtin_bit_cast(float, __builtin_amdgcn_update_dpp(0, __builtin_bit_cast(int, v), 0x123, 0xf, 0xf, false)); }
;     __device__ __forceinline__ void operator()(f32x4 (&acc)[2][2][4][2], const pg8::Unit& u, int wr, int wc, int fr, int fq) const {
;     ...
;                     for (int m = 0; m < 4; ++m) { const int row = row0 + ai * 128 + m * 16; const f32x4 g = acc[ai][bj][m][n]; f32x4 p1, p2, p3;
;                         if (prompt) { const f32x4 gp = (m == 0) ? hal[n] : acc[ai][bj][m > 0 ? m - 1 : 0][n];
; #pragma unroll
;                             for (int j = 0; j < 4; ++j) { p1[j] = dpp_ror1(fr == 15 ? gp[j] : g[j]); p2[j] = dpp_ror2(fr >= 14 ? gp[j] : g[j]); p3[j] = dpp_ror3(fr >= 13 ? gp[j] : g[j]); } }
;                         else { const int t = fr & 3; const float* sp = stp + (size_t)((row - MP) >> 2) * 3 * CW + ch;
;                             const f32x4 b0 = *(const f32x4*)sp, b1 = *(const f32x4*)(sp + CW), b2 = *(const f32x4*)(sp + 2 * CW);
; #pragma unroll
;                             for (int j = 0; j < 4; ++j) { const float r1 = dpp_ror1(g[j]), r2 = dpp_ror2(g[j]), r3 = dpp_ror3(g[j]);
;                                 p1[j] = t >= 1 ? r1 : b2[j]; p2[j] = t >= 2 ? r2 : (t == 1 ? b2[j] : b1[j]); p3[j] = t >= 3 ? r3 : (t == 2 ? b2[j] : (t == 1 ? b1[j] : b0[j])); } }
;                         float o[4];
; #pragma unroll
;                         for (int j = 0; j < 4; ++j) { const float y = bb[j] + w0[j] * p3[j] + w1[j] * p2[j] + w2[j] * p1[j] + w3[j] * g[j]; o[j] = is_rg ? y : siluf_(y); }
;                         u32x2 w; w.x = cvt_pk_bf16(o[0], o[1]); w.y = cvt_pk_bf16(o[2], o[3]);
;                         *(u32x2*)(dst + (size_t)row * ld + bj * 128 + 4 * n) = w; }
.LBB0_1281:
	v_mov_b32_e32 v170, v146
	v_mov_b32_e32 v171, v130
	v_pk_mul_f32 v[170:171], v[162:163], v[170:171]
	v_mov_b32_e32 v169, v154
	v_add_f32_e32 v130, v142, v171
	v_add_f32_e32 v130, v170, v130
	v_pk_mul_f32 v[168:169], v[164:165], v[168:169]
	v_mov_b32_e32 v161, v155
	v_add_f32_e32 v130, v169, v130
	v_add_f32_e32 v146, v168, v130
	v_mul_f32_e32 v130, 0xbfb8aa3b, v146
	v_exp_f32_e32 v130, v130
	v_mov_b32_e32 v153, v156
	s_mov_b64 s[2:3], -1
	s_and_b64 vcc, exec, s[18:19]
	v_add_f32_e32 v130, 1.0, v130
	v_rcp_f32_e32 v151, v130
	v_mov_b32_e32 v130, v147
	v_pk_mul_f32 v[130:131], v[138:139], v[130:131]
	v_mov_b32_e32 v168, v30
	v_add_f32_e32 v131, v143, v131
	v_add_f32_e32 v147, v130, v131
	v_pk_mul_f32 v[130:131], v[134:135], v[160:161]
	v_mov_b32_e32 v160, v31
	v_add_f32_e32 v131, v131, v147
	v_add_f32_e32 v147, v130, v131
	v_mul_f32_e32 v130, 0xbfb8aa3b, v147
	v_exp_f32_e32 v130, v130
	v_mul_f32_e32 v131, v146, v151
	v_cndmask_b32_e64 v146, v131, v146, s[4:5]
	v_mov_b32_e32 v131, v132
	v_add_f32_e32 v130, 1.0, v130
	v_rcp_f32_e32 v154, v130
	v_mov_b32_e32 v130, v148
	v_pk_mul_f32 v[130:131], v[158:159], v[130:131]
	v_mov_b32_e32 v151, v157
	v_add_f32_e32 v131, v144, v131
	v_add_f32_e32 v132, v130, v131
	v_pk_mul_f32 v[130:131], v[166:167], v[152:153]
	s_nop 0
	v_add_f32_e32 v131, v131, v132
	v_add_f32_e32 v148, v130, v131
	v_mul_f32_e32 v130, 0xbfb8aa3b, v148
	v_mov_b32_e32 v132, v149
	v_exp_f32_e32 v152, v130
	v_pk_mul_f32 v[130:131], v[140:141], v[132:133]
	v_add_f32_e32 v133, 1.0, v152
	v_add_f32_e32 v131, v145, v131
	v_add_f32_e32 v132, v130, v131
	v_pk_mul_f32 v[130:131], v[136:137], v[150:151]
	v_rcp_f32_e32 v133, v133
	v_add_f32_e32 v131, v131, v132
	v_add_f32_e32 v130, v130, v131
	v_mul_f32_e32 v131, 0xbfb8aa3b, v130
	v_exp_f32_e32 v131, v131
	v_mul_f32_e32 v132, v147, v154
	v_mul_f32_e32 v133, v148, v133
	v_cndmask_b32_e64 v132, v132, v147, s[4:5]
	v_add_f32_e32 v131, 1.0, v131
	v_rcp_f32_e32 v131, v131
	v_cndmask_b32_e64 v133, v133, v148, s[4:5]
	v_mov_b32_e32 v152, v32
	v_mov_b32_e32 v150, v33
	v_mul_f32_e32 v131, v130, v131
	v_cndmask_b32_e64 v131, v131, v130, s[4:5]
	v_cvt_pk_bf16_f32 v130, v146, v132
	v_cvt_pk_bf16_f32 v131, v133, v131
	v_mov_b32_e32 v64, v130
	v_mov_b32_e32 v65, v131
	flat_store_dwordx4 v[224:225], v[62:65]
	s_cbranch_vccnz .LBB0_1323
	v_add_u32_e32 v131, 0xffffe0a0, v202
	v_ashrrev_i32_e32 v131, 2, v131
	v_lshl_add_u32 v131, v131, 1, v131
	v_mad_i64_i32 v[132:133], s[2:3], v131, s47, 0
	v_lshl_add_u64 v[132:133], v[132:133], 2, v[208:209]
	v_lshl_add_u64 v[146:147], v[132:133], 0, s[24:25]
	s_lshl_b32 s2, s27, 2
	s_mov_b32 s3, s25
	global_load_dwordx4 v[154:157], v[132:133], off offset:16
	s_nop 0
	global_load_dwordx4 v[146:149], v[146:147], off offset:16
	v_lshl_add_u64 v[132:133], v[132:133], 0, s[2:3]
	global_load_dwordx4 v[150:153], v[132:133], off offset:16
	v_mov_b32_e32 v160, 0
	v_mov_b32_e32 v161, 0
	v_mov_b32_e32 v130, 0
	v_mov_b32_dpp v160, v30 row_ror:1 row_mask:0xf bank_mask:0xf
	v_mov_b32_dpp v161, v30 row_ror:2 row_mask:0xf bank_mask:0xf
	v_mov_b32_dpp v130, v30 row_ror:3 row_mask:0xf bank_mask:0xf
	v_cmp_lt_i32_e32 vcc, 1, v205
	s_and_saveexec_b64 s[2:3], vcc
	s_xor_b64 s[2:3], exec, s[2:3]
	s_cbranch_execz .LBB0_1286
	v_cmp_gt_i32_e32 vcc, 3, v205
	s_and_saveexec_b64 s[20:21], vcc
	s_cbranch_execz .LBB0_1285
	s_waitcnt vmcnt(0)
	v_mov_b32_e32 v130, v150

; __device__ __forceinline__ unsigned cvt_pk_bf16(float lo, float hi) { unsigned r; asm("v_cvt_pk_bf16_f32 %0, %1, %2" : "=v"(r) : "v"(lo), "v"(hi)); return r; }
; __device__ __forceinline__ float siluf_(float x) { return x * sigmoidf_(x); }
; __device__ __forceinline__ float dpp_ror1(float v) { return __builtin_bit_cast(float, __builtin_amdgcn_update_dpp(0, __builtin_bit_cast(int, v), 0x121, 0xf, 0xf, false)); }
; __device__ __forceinline__ float dpp_ror2(float v) { return __builtin_bit_cast(float, __builtin_amdgcn_update_dpp(0, __builtin_bit_cast(int, v), 0x122, 0xf, 0xf, false)); }
; __device__ __forceinline__ float dpp_ror3(float v) { return __builtin_bit_cast(float, __builtin_amdgcn_update_dpp(0, __builtin_bit_cast(int, v), 0x123, 0xf, 0xf, false)); }
;     __device__ __forceinline__ void operator()(f32x4 (&acc)[2][2][4][2], const pg8::Unit& u, int wr, int wc, int fr, int fq) const {
;     ...
;                     for (int m = 0; m < 4; ++m) { const int row = row0 + ai * 128 + m * 16; const f32x4 g = acc[ai][bj][m][n]; f32x4 p1, p2, p3;
;                         if (prompt) { const f32x4 gp = (m == 0) ? hal[n] : acc[ai][bj][m > 0 ? m - 1 : 0][n];
; #pragma unroll
;                             for (int j = 0; j < 4; ++j) { p1[j] = dpp_ror1(fr == 15 ? gp[j] : g[j]); p2[j] = dpp_ror2(fr >= 14 ? gp[j] : g[j]); p3[j] = dpp_ror3(fr >= 13 ? gp[j] : g[j]); } }
;                         else { const int t = fr & 3; const float* sp = stp + (size_t)((row - MP) >> 2) * 3 * CW + ch;
;                             const f32x4 b0 = *(const f32x4*)sp, b1 = *(const f32x4*)(sp + CW), b2 = *(const f32x4*)(sp + 2 * CW);
; #pragma unroll
;                             for (int j = 0; j < 4; ++j) { const float r1 = dpp_ror1(g[j]), r2 = dpp_ror2(g[j]), r3 = dpp_ror3(g[j]);
;                                 p1[j] = t >= 1 ? r1 : b2[j]; p2[j] = t >= 2 ? r2 : (t == 1 ? b2[j] : b1[j]); p3[j] = t >= 3 ? r3 : (t == 2 ? b2[j] : (t == 1 ? b1[j] : b0[j])); } }
;                         float o[4];
; #pragma unroll
;                         for (int j = 0; j < 4; ++j) { const float y = bb[j] + w0[j] * p3[j] + w1[j] * p2[j] + w2[j] * p1[j] + w3[j] * g[j]; o[j] = is_rg ? y : siluf_(y); }
;                         u32x2 w; w.x = cvt_pk_bf16(o[0], o[1]); w.y = cvt_pk_bf16(o[2], o[3]);
;                         *(u32x2*)(dst + (size_t)row * ld + bj * 128 + 4 * n) = w; }
.LBB0_1325:
	v_mov_b32_e32 v170, v146
	v_mov_b32_e32 v171, v130
	v_pk_mul_f32 v[170:171], v[162:163], v[170:171]
	v_mov_b32_e32 v169, v154
	v_add_f32_e32 v130, v142, v171
	v_add_f32_e32 v130, v170, v130
	v_pk_mul_f32 v[168:169], v[164:165], v[168:169]
	v_mov_b32_e32 v161, v155
	v_add_f32_e32 v130, v169, v130
	v_add_f32_e32 v146, v168, v130
	v_mul_f32_e32 v130, 0xbfb8aa3b, v146
	v_exp_f32_e32 v130, v130
	v_mov_b32_e32 v153, v156
	s_mov_b64 s[2:3], -1
	s_and_b64 vcc, exec, s[18:19]
	v_add_f32_e32 v130, 1.0, v130
	v_rcp_f32_e32 v151, v130
	v_mov_b32_e32 v130, v147
	v_pk_mul_f32 v[130:131], v[138:139], v[130:131]
	v_mov_b32_e32 v168, v10
	v_add_f32_e32 v131, v143, v131
	v_add_f32_e32 v147, v130, v131
	v_pk_mul_f32 v[130:131], v[134:135], v[160:161]
	v_mov_b32_e32 v160, v11
	v_add_f32_e32 v131, v131, v147
	v_add_f32_e32 v147, v130, v131
	v_mul_f32_e32 v130, 0xbfb8aa3b, v147
	v_exp_f32_e32 v130, v130
	v_mul_f32_e32 v131, v146, v151
	v_cndmask_b32_e64 v146, v131, v146, s[4:5]
	v_mov_b32_e32 v131, v132
	v_add_f32_e32 v130, 1.0, v130
	v_rcp_f32_e32 v154, v130
	v_mov_b32_e32 v130, v148
	v_pk_mul_f32 v[130:131], v[158:159], v[130:131]
	v_mov_b32_e32 v151, v157
	v_add_f32_e32 v131, v144, v131
	v_add_f32_e32 v132, v130, v131
	v_pk_mul_f32 v[130:131], v[166:167], v[152:153]
	s_nop 0
	v_add_f32_e32 v131, v131, v132
	v_add_f32_e32 v148, v130, v131
	v_mul_f32_e32 v130, 0xbfb8aa3b, v148
	v_mov_b32_e32 v132, v149
	v_exp_f32_e32 v152, v130
	v_pk_mul_f32 v[130:131], v[140:141], v[132:133]
	v_add_f32_e32 v133, 1.0, v152
	v_add_f32_e32 v131, v145, v131
	v_add_f32_e32 v132, v130, v131
	v_pk_mul_f32 v[130:131], v[136:137], v[150:151]
	v_rcp_f32_e32 v133, v133
	v_add_f32_e32 v131, v131, v132
	v_add_f32_e32 v130, v130, v131
	v_mul_f32_e32 v131, 0xbfb8aa3b, v130
	v_exp_f32_e32 v131, v131
	v_mul_f32_e32 v132, v147, v154
	v_mul_f32_e32 v133, v148, v133
	v_cndmask_b32_e64 v132, v132, v147, s[4:5]
	v_add_f32_e32 v131, 1.0, v131
	v_rcp_f32_e32 v131, v131
	v_cndmask_b32_e64 v133, v133, v148, s[4:5]
	v_mov_b32_e32 v152, v12
	v_mov_b32_e32 v150, v13
	v_mul_f32_e32 v131, v130, v131
	v_cndmask_b32_e64 v131, v131, v130, s[4:5]
	v_cvt_pk_bf16_f32 v130, v146, v132
	v_cvt_pk_bf16_f32 v131, v133, v131
	v_mov_b32_e32 v48, v130
	v_mov_b32_e32 v49, v131
	flat_store_dwordx4 v[226:227], v[46:49]
	s_cbranch_vccnz .LBB0_1367
	v_add_u32_e32 v131, 0xffffe0b0, v202
	v_ashrrev_i32_e32 v131, 2, v131
	v_lshl_add_u32 v131, v131, 1, v131
	v_mad_i64_i32 v[132:133], s[2:3], v131, s47, 0
	v_lshl_add_u64 v[132:133], v[132:133], 2, v[208:209]
	v_lshl_add_u64 v[146:147], v[132:133], 0, s[24:25]
	s_lshl_b32 s2, s27, 2
	s_mov_b32 s3, s25
	global_load_dwordx4 v[154:157], v[132:133], off offset:16
	s_nop 0
	global_load_dwordx4 v[146:149], v[146:147], off offset:16
	v_lshl_add_u64 v[132:133], v[132:133], 0, s[2:3]
	global_load_dwordx4 v[150:153], v[132:133], off offset:16
	v_mov_b32_e32 v160, 0
	v_mov_b32_e32 v161, 0
	v_mov_b32_e32 v130, 0
	v_mov_b32_dpp v160, v10 row_ror:1 row_mask:0xf bank_mask:0xf
	v_mov_b32_dpp v161, v10 row_ror:2 row_mask:0xf bank_mask:0xf
	v_mov_b32_dpp v130, v10 row_ror:3 row_mask:0xf bank_mask:0xf
	v_cmp_lt_i32_e32 vcc, 1, v205
	s_and_saveexec_b64 s[2:3], vcc
	s_xor_b64 s[2:3], exec, s[2:3]
	s_cbranch_execz .LBB0_1330
	v_cmp_gt_i32_e32 vcc, 3, v205
	s_and_saveexec_b64 s[20:21], vcc
	s_cbranch_execz .LBB0_1329
	s_waitcnt vmcnt(0)
	v_mov_b32_e32 v130, v150

; #define LAS __attribute__((address_space(3)))
; __device__ __forceinline__ unsigned cvt_pk_bf16(float lo, float hi) { unsigned r; asm("v_cvt_pk_bf16_f32 %0, %1, %2" : "=v"(r) : "v"(lo), "v"(hi)); return r; }
; __device__ __forceinline__ float siluf_(float x) { return x * sigmoidf_(x); }
;     __device__ __forceinline__ void operator()(f32x4 (&acc)[2][2][4][2], const pg8::Unit& u, int wr, int wc, int fr, int fq) const {
;     ...
;                 f32x4 hal[2];
;                 hal[0] = hal[1] = (f32x4){0.f, 0.f, 0.f, 0.f};
;                 if (prompt) { const int b = 2 * ai + wr;
;                     if (b >= 1) { if (fr >= 13) {
; #pragma unroll
;                             for (int n = 0; n < 2; ++n) hal[n] = *(const LAS f32x4*)(H + ((b - 1) * 3 + (fr - 13)) * 256 + bj * 128 + cl0 + 4 * n); } }
;     ...
;                         float o[4];
; #pragma unroll
;                         for (int j = 0; j < 4; ++j) { const float y = bb[j] + w0[j] * p3[j] + w1[j] * p2[j] + w2[j] * p1[j] + w3[j] * g[j]; o[j] = is_rg ? y : siluf_(y); }
;                         u32x2 w; w.x = cvt_pk_bf16(o[0], o[1]); w.y = cvt_pk_bf16(o[2], o[3]);
;                         *(u32x2*)(dst + (size_t)row * ld + bj * 128 + 4 * n) = w; }
.LBB0_1369:
	v_mov_b32_e32 v170, v146
	v_mov_b32_e32 v171, v130
	v_pk_mul_f32 v[162:163], v[162:163], v[170:171]
	v_mov_b32_e32 v169, v154
	v_add_f32_e32 v130, v142, v163
	v_add_f32_e32 v130, v162, v130
	v_pk_mul_f32 v[162:163], v[164:165], v[168:169]
	v_mov_b32_e32 v161, v155
	v_add_f32_e32 v130, v163, v130
	v_add_f32_e32 v142, v162, v130
	v_mul_f32_e32 v130, 0xbfb8aa3b, v142
	v_exp_f32_e32 v130, v130
	v_mov_b32_e32 v153, v156
	v_mov_b32_e32 v151, v157
	v_add_f32_e32 v130, 1.0, v130
	v_rcp_f32_e32 v146, v130
	v_mov_b32_e32 v130, v147
	v_pk_mul_f32 v[130:131], v[138:139], v[130:131]
	s_nop 0
	v_add_f32_e32 v131, v143, v131
	v_add_f32_e32 v138, v130, v131
	v_pk_mul_f32 v[130:131], v[134:135], v[160:161]
	v_mov_b32_e32 v160, 0
	v_add_f32_e32 v131, v131, v138
	v_add_f32_e32 v134, v130, v131
	v_mul_f32_e32 v130, 0xbfb8aa3b, v134
	v_exp_f32_e32 v130, v130
	v_mul_f32_e32 v131, v142, v146
	v_cndmask_b32_e64 v135, v131, v142, s[4:5]
	v_mov_b32_e32 v131, v132
	v_add_f32_e32 v130, 1.0, v130
	v_rcp_f32_e32 v138, v130
	v_mov_b32_e32 v130, v148
	v_pk_mul_f32 v[130:131], v[158:159], v[130:131]
	v_mov_b32_e32 v158, 0
	v_add_f32_e32 v131, v144, v131
	v_add_f32_e32 v132, v130, v131
	v_pk_mul_f32 v[130:131], v[166:167], v[152:153]
	v_mov_b32_e32 v159, 0
	v_add_f32_e32 v131, v131, v132
	v_add_f32_e32 v139, v130, v131
	v_mul_f32_e32 v130, 0xbfb8aa3b, v139
	v_mov_b32_e32 v132, v149
	v_exp_f32_e32 v142, v130
	v_pk_mul_f32 v[130:131], v[140:141], v[132:133]
	v_mov_b32_e32 v161, 0
	v_add_f32_e32 v131, v145, v131
	v_add_f32_e32 v132, v130, v131
	v_pk_mul_f32 v[130:131], v[136:137], v[150:151]
	v_add_f32_e32 v133, 1.0, v142
	v_add_f32_e32 v131, v131, v132
	v_add_f32_e32 v130, v130, v131
	v_mul_f32_e32 v131, 0xbfb8aa3b, v130
	v_exp_f32_e32 v131, v131
	v_rcp_f32_e32 v133, v133
	v_mul_f32_e32 v132, v134, v138
	v_cndmask_b32_e64 v132, v132, v134, s[4:5]
	v_add_f32_e32 v131, 1.0, v131
	v_rcp_f32_e32 v131, v131
	v_mul_f32_e32 v133, v139, v133
	v_cndmask_b32_e64 v133, v133, v139, s[4:5]
	v_mul_f32_e32 v131, v130, v131
	v_cndmask_b32_e64 v131, v131, v130, s[4:5]
	v_cvt_pk_bf16_f32 v130, v135, v132
	v_cvt_pk_bf16_f32 v131, v133, v131
	v_mov_b32_e32 v28, v130
	v_mov_b32_e32 v29, v131
	flat_store_dwordx4 v[220:221], v[26:29]
	v_mov_b32_e32 v130, 0
	v_mov_b32_e32 v131, 0
	v_mov_b32_e32 v132, 0
	v_mov_b32_e32 v133, 0
	s_and_saveexec_b64 s[2:3], s[0:1]
	s_cbranch_execz .LBB0_1371
	s_movk_i32 s0, 0xc200
	v_add3_u32 v130, v232, v207, s0
	ds_read_b128 v[158:161], v130
	ds_read_b128 v[130:133], v130 offset:16

; __device__ __forceinline__ unsigned cvt_pk_bf16(float lo, float hi) { unsigned r; asm("v_cvt_pk_bf16_f32 %0, %1, %2" : "=v"(r) : "v"(lo), "v"(hi)); return r; }
; __device__ __forceinline__ float siluf_(float x) { return x * sigmoidf_(x); }
; __device__ __forceinline__ float dpp_ror1(float v) { return __builtin_bit_cast(float, __builtin_amdgcn_update_dpp(0, __builtin_bit_cast(int, v), 0x121, 0xf, 0xf, false)); }
; __device__ __forceinline__ float dpp_ror2(float v) { return __builtin_bit_cast(float, __builtin_amdgcn_update_dpp(0, __builtin_bit_cast(int, v), 0x122, 0xf, 0xf, false)); }
; __device__ __forceinline__ float dpp_ror3(float v) { return __builtin_bit_cast(float, __builtin_amdgcn_update_dpp(0, __builtin_bit_cast(int, v), 0x123, 0xf, 0xf, false)); }
;     __device__ __forceinline__ void operator()(f32x4 (&acc)[2][2][4][2], const pg8::Unit& u, int wr, int wc, int fr, int fq) const {
;     ...
;                     for (int m = 0; m < 4; ++m) { const int row = row0 + ai * 128 + m * 16; const f32x4 g = acc[ai][bj][m][n]; f32x4 p1, p2, p3;
;                         if (prompt) { const f32x4 gp = (m == 0) ? hal[n] : acc[ai][bj][m > 0 ? m - 1 : 0][n];
; #pragma unroll
;                             for (int j = 0; j < 4; ++j) { p1[j] = dpp_ror1(fr == 15 ? gp[j] : g[j]); p2[j] = dpp_ror2(fr >= 14 ? gp[j] : g[j]); p3[j] = dpp_ror3(fr >= 13 ? gp[j] : g[j]); } }
;                         else { const int t = fr & 3; const float* sp = stp + (size_t)((row - MP) >> 2) * 3 * CW + ch;
;                             const f32x4 b0 = *(const f32x4*)sp, b1 = *(const f32x4*)(sp + CW), b2 = *(const f32x4*)(sp + 2 * CW);
; #pragma unroll
;                             for (int j = 0; j < 4; ++j) { const float r1 = dpp_ror1(g[j]), r2 = dpp_ror2(g[j]), r3 = dpp_ror3(g[j]);
;                                 p1[j] = t >= 1 ? r1 : b2[j]; p2[j] = t >= 2 ? r2 : (t == 1 ? b2[j] : b1[j]); p3[j] = t >= 3 ? r3 : (t == 2 ? b2[j] : (t == 1 ? b1[j] : b0[j])); } }
;                         float o[4];
; #pragma unroll
;                         for (int j = 0; j < 4; ++j) { const float y = bb[j] + w0[j] * p3[j] + w1[j] * p2[j] + w2[j] * p1[j] + w3[j] * g[j]; o[j] = is_rg ? y : siluf_(y); }
;                         u32x2 w; w.x = cvt_pk_bf16(o[0], o[1]); w.y = cvt_pk_bf16(o[2], o[3]);
;                         *(u32x2*)(dst + (size_t)row * ld + bj * 128 + 4 * n) = w; }
.LBB0_1415:
	s_waitcnt vmcnt(0)
	v_mov_b32_e32 v166, v150
	v_mov_b32_e32 v167, v138
	s_waitcnt lgkmcnt(0)
	v_mov_b32_e32 v158, v162
	v_mov_b32_e32 v159, v154
	v_pk_mul_f32 v[158:159], v[166:167], v[158:159]
	v_mov_b32_e32 v168, v146
	v_add_f32_e32 v138, v142, v159
	v_mov_b32_e32 v169, v134
	v_mov_b32_e32 v235, v170
	v_add_f32_e32 v138, v158, v138
	v_pk_mul_f32 v[158:159], v[168:169], v[234:235]
	v_mov_b32_e32 v154, v163
	v_add_f32_e32 v134, v159, v138
	v_add_f32_e32 v158, v158, v134
	v_mul_f32_e32 v134, 0xbfb8aa3b, v158
	v_exp_f32_e32 v134, v134
	v_mov_b32_e32 v138, v151
	v_pk_mul_f32 v[150:151], v[138:139], v[154:155]
	v_mov_b32_e32 v233, v171
	v_add_f32_e32 v134, 1.0, v134
	v_rcp_f32_e32 v159, v134
	v_add_f32_e32 v134, v143, v151
	v_add_f32_e32 v150, v150, v134
	v_mov_b32_e32 v134, v147
	v_pk_mul_f32 v[146:147], v[134:135], v[232:233]
	v_mov_b32_e32 v162, v152
	v_add_f32_e32 v147, v147, v150
	v_add_f32_e32 v150, v146, v147
	v_mul_f32_e32 v146, 0xbfb8aa3b, v150
	v_exp_f32_e32 v146, v146
	v_mul_f32_e32 v147, v158, v159
	v_cndmask_b32_e64 v151, v147, v158, s[4:5]
	v_mov_b32_e32 v163, v140
	v_add_f32_e32 v146, 1.0, v146
	v_rcp_f32_e32 v154, v146
	v_mov_b32_e32 v146, v164
	v_mov_b32_e32 v147, v156
	v_pk_mul_f32 v[146:147], v[162:163], v[146:147]
	v_mov_b32_e32 v170, v148
	v_add_f32_e32 v140, v144, v147
	v_mov_b32_e32 v171, v136
	v_mov_b32_e32 v231, v172
	v_add_f32_e32 v140, v146, v140
	v_pk_mul_f32 v[146:147], v[170:171], v[230:231]
	v_mov_b32_e32 v156, v165
	v_add_f32_e32 v136, v147, v140
	v_add_f32_e32 v148, v146, v136
	v_mov_b32_e32 v140, v153
	v_mul_f32_e32 v136, 0xbfb8aa3b, v148
	v_pk_mul_f32 v[146:147], v[140:141], v[156:157]
	v_exp_f32_e32 v152, v136
	v_add_f32_e32 v136, v145, v147
	v_add_f32_e32 v153, v146, v136
	v_mov_b32_e32 v136, v149
	v_mov_b32_e32 v229, v173
	v_pk_mul_f32 v[146:147], v[136:137], v[228:229]
	v_add_f32_e32 v152, 1.0, v152
	v_add_f32_e32 v147, v147, v153
	v_add_f32_e32 v146, v146, v147
	v_mul_f32_e32 v147, 0xbfb8aa3b, v146
	v_exp_f32_e32 v147, v147
	v_rcp_f32_e32 v152, v152
	v_mul_f32_e32 v149, v150, v154
	v_cndmask_b32_e64 v149, v149, v150, s[4:5]
	v_add_f32_e32 v147, 1.0, v147
	v_rcp_f32_e32 v147, v147
	v_mul_f32_e32 v150, v148, v152
	v_cndmask_b32_e64 v148, v150, v148, s[4:5]
	s_mov_b64 s[0:1], -1
	v_mul_f32_e32 v147, v146, v147
	v_cndmask_b32_e64 v147, v147, v146, s[4:5]
	v_cvt_pk_bf16_f32 v146, v151, v149
	v_cvt_pk_bf16_f32 v147, v148, v147
	s_and_b64 vcc, exec, s[18:19]
	v_mov_b32_e32 v172, v38
	v_mov_b32_e32 v164, v39
	v_mov_b32_e32 v156, v40
	v_mov_b32_e32 v154, v41
	v_mov_b32_e32 v14, v146
	v_mov_b32_e32 v15, v147
	s_cbranch_vccnz .LBB0_1457
	v_add_u32_e32 v147, 0xffffe090, v202
	v_ashrrev_i32_e32 v147, 2, v147
	v_lshl_add_u32 v147, v147, 1, v147
	v_mad_i64_i32 v[148:149], s[0:1], v147, s47, 0
	v_lshl_add_u64 v[148:149], v[148:149], 2, v[208:209]
	v_lshl_add_u64 v[150:151], v[148:149], 0, s[24:25]
	s_lshl_b32 s0, s27, 2
	s_mov_b32 s1, s25
	global_load_dwordx4 v[158:161], v[148:149], off offset:512
	s_nop 0
	global_load_dwordx4 v[150:153], v[150:151], off offset:512
	v_lshl_add_u64 v[148:149], v[148:149], 0, s[0:1]
	global_load_dwordx4 v[154:157], v[148:149], off offset:512
	v_mov_b32_e32 v164, 0
	v_mov_b32_e32 v165, 0
	v_mov_b32_e32 v146, 0
	v_mov_b32_dpp v164, v38 row_ror:1 row_mask:0xf bank_mask:0xf
	v_mov_b32_dpp v165, v38 row_ror:2 row_mask:0xf bank_mask:0xf
	v_mov_b32_dpp v146, v38 row_ror:3 row_mask:0xf bank_mask:0xf
	v_cmp_lt_i32_e32 vcc, 1, v205
	s_and_saveexec_b64 s[0:1], vcc
	s_xor_b64 s[0:1], exec, s[0:1]
	s_cbranch_execz .LBB0_1420
	v_cmp_gt_i32_e32 vcc, 3, v205
	s_and_saveexec_b64 s[2:3], vcc
	s_cbranch_execz .LBB0_1419
	s_waitcnt vmcnt(0)
	v_mov_b32_e32 v146, v154

; __device__ __forceinline__ unsigned cvt_pk_bf16(float lo, float hi) { unsigned r; asm("v_cvt_pk_bf16_f32 %0, %1, %2" : "=v"(r) : "v"(lo), "v"(hi)); return r; }
; __device__ __forceinline__ float siluf_(float x) { return x * sigmoidf_(x); }
; __device__ __forceinline__ float dpp_ror1(float v) { return __builtin_bit_cast(float, __builtin_amdgcn_update_dpp(0, __builtin_bit_cast(int, v), 0x121, 0xf, 0xf, false)); }
; __device__ __forceinline__ float dpp_ror2(float v) { return __builtin_bit_cast(float, __builtin_amdgcn_update_dpp(0, __builtin_bit_cast(int, v), 0x122, 0xf, 0xf, false)); }
; __device__ __forceinline__ float dpp_ror3(float v) { return __builtin_bit_cast(float, __builtin_amdgcn_update_dpp(0, __builtin_bit_cast(int, v), 0x123, 0xf, 0xf, false)); }
;     __device__ __forceinline__ void operator()(f32x4 (&acc)[2][2][4][2], const pg8::Unit& u, int wr, int wc, int fr, int fq) const {
;     ...
;                     for (int m = 0; m < 4; ++m) { const int row = row0 + ai * 128 + m * 16; const f32x4 g = acc[ai][bj][m][n]; f32x4 p1, p2, p3;
;                         if (prompt) { const f32x4 gp = (m == 0) ? hal[n] : acc[ai][bj][m > 0 ? m - 1 : 0][n];
; #pragma unroll
;                             for (int j = 0; j < 4; ++j) { p1[j] = dpp_ror1(fr == 15 ? gp[j] : g[j]); p2[j] = dpp_ror2(fr >= 14 ? gp[j] : g[j]); p3[j] = dpp_ror3(fr >= 13 ? gp[j] : g[j]); } }
;                         else { const int t = fr & 3; const float* sp = stp + (size_t)((row - MP) >> 2) * 3 * CW + ch;
;                             const f32x4 b0 = *(const f32x4*)sp, b1 = *(const f32x4*)(sp + CW), b2 = *(const f32x4*)(sp + 2 * CW);
; #pragma unroll
;                             for (int j = 0; j < 4; ++j) { const float r1 = dpp_ror1(g[j]), r2 = dpp_ror2(g[j]), r3 = dpp_ror3(g[j]);
;                                 p1[j] = t >= 1 ? r1 : b2[j]; p2[j] = t >= 2 ? r2 : (t == 1 ? b2[j] : b1[j]); p3[j] = t >= 3 ? r3 : (t == 2 ? b2[j] : (t == 1 ? b1[j] : b0[j])); } }
;                         float o[4];
; #pragma unroll
;                         for (int j = 0; j < 4; ++j) { const float y = bb[j] + w0[j] * p3[j] + w1[j] * p2[j] + w2[j] * p1[j] + w3[j] * g[j]; o[j] = is_rg ? y : siluf_(y); }
;                         u32x2 w; w.x = cvt_pk_bf16(o[0], o[1]); w.y = cvt_pk_bf16(o[2], o[3]);
;                         *(u32x2*)(dst + (size_t)row * ld + bj * 128 + 4 * n) = w; }
.LBB0_1459:
	v_mov_b32_e32 v228, v150
	v_mov_b32_e32 v229, v146
	v_pk_mul_f32 v[228:229], v[166:167], v[228:229]
	v_mov_b32_e32 v173, v158
	v_add_f32_e32 v146, v142, v229
	v_add_f32_e32 v146, v228, v146
	v_pk_mul_f32 v[172:173], v[168:169], v[172:173]
	v_mov_b32_e32 v165, v159
	v_add_f32_e32 v146, v173, v146
	v_add_f32_e32 v150, v172, v146
	v_mul_f32_e32 v146, 0xbfb8aa3b, v150
	v_exp_f32_e32 v146, v146
	v_mov_b32_e32 v157, v160
	s_mov_b64 s[0:1], -1
	s_and_b64 vcc, exec, s[18:19]
	v_add_f32_e32 v146, 1.0, v146
	v_rcp_f32_e32 v155, v146
	v_mov_b32_e32 v146, v151
	v_pk_mul_f32 v[146:147], v[138:139], v[146:147]
	v_mov_b32_e32 v172, v22
	v_add_f32_e32 v147, v143, v147
	v_add_f32_e32 v151, v146, v147
	v_pk_mul_f32 v[146:147], v[134:135], v[164:165]
	v_mov_b32_e32 v164, v23
	v_add_f32_e32 v147, v147, v151
	v_add_f32_e32 v151, v146, v147
	v_mul_f32_e32 v146, 0xbfb8aa3b, v151
	v_exp_f32_e32 v146, v146
	v_mul_f32_e32 v147, v150, v155
	v_cndmask_b32_e64 v150, v147, v150, s[4:5]
	v_mov_b32_e32 v147, v148
	v_add_f32_e32 v146, 1.0, v146
	v_rcp_f32_e32 v158, v146
	v_mov_b32_e32 v146, v152
	v_pk_mul_f32 v[146:147], v[162:163], v[146:147]
	v_mov_b32_e32 v155, v161
	v_add_f32_e32 v147, v144, v147
	v_add_f32_e32 v148, v146, v147
	v_pk_mul_f32 v[146:147], v[170:171], v[156:157]
	s_nop 0
	v_add_f32_e32 v147, v147, v148
	v_add_f32_e32 v152, v146, v147
	v_mul_f32_e32 v146, 0xbfb8aa3b, v152
	v_mov_b32_e32 v148, v153
	v_exp_f32_e32 v156, v146
	v_pk_mul_f32 v[146:147], v[140:141], v[148:149]
	v_add_f32_e32 v149, 1.0, v156
	v_add_f32_e32 v147, v145, v147
	v_add_f32_e32 v148, v146, v147
	v_pk_mul_f32 v[146:147], v[136:137], v[154:155]
	v_rcp_f32_e32 v149, v149
	v_add_f32_e32 v147, v147, v148
	v_add_f32_e32 v146, v146, v147
	v_mul_f32_e32 v147, 0xbfb8aa3b, v146
	v_exp_f32_e32 v147, v147
	v_mul_f32_e32 v148, v151, v158
	v_mul_f32_e32 v149, v152, v149
	v_cndmask_b32_e64 v148, v148, v151, s[4:5]
	v_add_f32_e32 v147, 1.0, v147
	v_rcp_f32_e32 v147, v147
	v_cndmask_b32_e64 v149, v149, v152, s[4:5]
	v_mov_b32_e32 v156, v24
	v_mov_b32_e32 v154, v25
	v_mul_f32_e32 v147, v146, v147
	v_cndmask_b32_e64 v147, v147, v146, s[4:5]
	v_cvt_pk_bf16_f32 v146, v150, v148
	v_cvt_pk_bf16_f32 v147, v149, v147
	v_mov_b32_e32 v54, v146
	v_mov_b32_e32 v55, v147
	s_cbranch_vccnz .LBB0_1501
	v_add_u32_e32 v147, 0xffffe0a0, v202
	v_ashrrev_i32_e32 v147, 2, v147
	v_lshl_add_u32 v147, v147, 1, v147
	v_mad_i64_i32 v[148:149], s[0:1], v147, s47, 0
	v_lshl_add_u64 v[148:149], v[148:149], 2, v[208:209]
	v_lshl_add_u64 v[150:151], v[148:149], 0, s[24:25]
	s_lshl_b32 s0, s27, 2
	s_mov_b32 s1, s25
	global_load_dwordx4 v[158:161], v[148:149], off offset:512
	s_nop 0
	global_load_dwordx4 v[150:153], v[150:151], off offset:512
	v_lshl_add_u64 v[148:149], v[148:149], 0, s[0:1]
	global_load_dwordx4 v[154:157], v[148:149], off offset:512
	v_mov_b32_e32 v164, 0
	v_mov_b32_e32 v165, 0
	v_mov_b32_e32 v146, 0
	v_mov_b32_dpp v164, v22 row_ror:1 row_mask:0xf bank_mask:0xf
	v_mov_b32_dpp v165, v22 row_ror:2 row_mask:0xf bank_mask:0xf
	v_mov_b32_dpp v146, v22 row_ror:3 row_mask:0xf bank_mask:0xf
	v_cmp_lt_i32_e32 vcc, 1, v205
	s_and_saveexec_b64 s[0:1], vcc
	s_xor_b64 s[0:1], exec, s[0:1]
	s_cbranch_execz .LBB0_1464
	v_cmp_gt_i32_e32 vcc, 3, v205
	s_and_saveexec_b64 s[2:3], vcc
	s_cbranch_execz .LBB0_1463
	s_waitcnt vmcnt(0)
	v_mov_b32_e32 v146, v154

; __device__ __forceinline__ unsigned cvt_pk_bf16(float lo, float hi) { unsigned r; asm("v_cvt_pk_bf16_f32 %0, %1, %2" : "=v"(r) : "v"(lo), "v"(hi)); return r; }
; __device__ __forceinline__ float siluf_(float x) { return x * sigmoidf_(x); }
; __device__ __forceinline__ float dpp_ror1(float v) { return __builtin_bit_cast(float, __builtin_amdgcn_update_dpp(0, __builtin_bit_cast(int, v), 0x121, 0xf, 0xf, false)); }
; __device__ __forceinline__ float dpp_ror2(float v) { return __builtin_bit_cast(float, __builtin_amdgcn_update_dpp(0, __builtin_bit_cast(int, v), 0x122, 0xf, 0xf, false)); }
; __device__ __forceinline__ float dpp_ror3(float v) { return __builtin_bit_cast(float, __builtin_amdgcn_update_dpp(0, __builtin_bit_cast(int, v), 0x123, 0xf, 0xf, false)); }
;     __device__ __forceinline__ void operator()(f32x4 (&acc)[2][2][4][2], const pg8::Unit& u, int wr, int wc, int fr, int fq) const {
;     ...
;                     for (int m = 0; m < 4; ++m) { const int row = row0 + ai * 128 + m * 16; const f32x4 g = acc[ai][bj][m][n]; f32x4 p1, p2, p3;
;                         if (prompt) { const f32x4 gp = (m == 0) ? hal[n] : acc[ai][bj][m > 0 ? m - 1 : 0][n];
; #pragma unroll
;                             for (int j = 0; j < 4; ++j) { p1[j] = dpp_ror1(fr == 15 ? gp[j] : g[j]); p2[j] = dpp_ror2(fr >= 14 ? gp[j] : g[j]); p3[j] = dpp_ror3(fr >= 13 ? gp[j] : g[j]); } }
;                         else { const int t = fr & 3; const float* sp = stp + (size_t)((row - MP) >> 2) * 3 * CW + ch;
;                             const f32x4 b0 = *(const f32x4*)sp, b1 = *(const f32x4*)(sp + CW), b2 = *(const f32x4*)(sp + 2 * CW);
; #pragma unroll
;                             for (int j = 0; j < 4; ++j) { const float r1 = dpp_ror1(g[j]), r2 = dpp_ror2(g[j]), r3 = dpp_ror3(g[j]);
;                                 p1[j] = t >= 1 ? r1 : b2[j]; p2[j] = t >= 2 ? r2 : (t == 1 ? b2[j] : b1[j]); p3[j] = t >= 3 ? r3 : (t == 2 ? b2[j] : (t == 1 ? b1[j] : b0[j])); } }
;                         float o[4];
; #pragma unroll
;                         for (int j = 0; j < 4; ++j) { const float y = bb[j] + w0[j] * p3[j] + w1[j] * p2[j] + w2[j] * p1[j] + w3[j] * g[j]; o[j] = is_rg ? y : siluf_(y); }
;                         u32x2 w; w.x = cvt_pk_bf16(o[0], o[1]); w.y = cvt_pk_bf16(o[2], o[3]);
;                         *(u32x2*)(dst + (size_t)row * ld + bj * 128 + 4 * n) = w; }
.LBB0_1503:
	v_mov_b32_e32 v228, v150
	v_mov_b32_e32 v229, v146
	v_pk_mul_f32 v[228:229], v[166:167], v[228:229]
	v_mov_b32_e32 v173, v158
	v_add_f32_e32 v146, v142, v229
	v_add_f32_e32 v146, v228, v146
	v_pk_mul_f32 v[172:173], v[168:169], v[172:173]
	v_mov_b32_e32 v165, v159
	v_add_f32_e32 v146, v173, v146
	v_add_f32_e32 v150, v172, v146
	v_mul_f32_e32 v146, 0xbfb8aa3b, v150
	v_exp_f32_e32 v146, v146
	v_mov_b32_e32 v157, v160
	s_mov_b64 s[0:1], -1
	s_and_b64 vcc, exec, s[18:19]
	v_add_f32_e32 v146, 1.0, v146
	v_rcp_f32_e32 v155, v146
	v_mov_b32_e32 v146, v151
	v_pk_mul_f32 v[146:147], v[138:139], v[146:147]
	v_mov_b32_e32 v172, v6
	v_add_f32_e32 v147, v143, v147
	v_add_f32_e32 v151, v146, v147
	v_pk_mul_f32 v[146:147], v[134:135], v[164:165]
	v_mov_b32_e32 v164, v7
	v_add_f32_e32 v147, v147, v151
	v_add_f32_e32 v151, v146, v147
	v_mul_f32_e32 v146, 0xbfb8aa3b, v151
	v_exp_f32_e32 v146, v146
	v_mul_f32_e32 v147, v150, v155
	v_cndmask_b32_e64 v150, v147, v150, s[4:5]
	v_mov_b32_e32 v147, v148
	v_add_f32_e32 v146, 1.0, v146
	v_rcp_f32_e32 v158, v146
	v_mov_b32_e32 v146, v152
	v_pk_mul_f32 v[146:147], v[162:163], v[146:147]
	v_mov_b32_e32 v155, v161
	v_add_f32_e32 v147, v144, v147
	v_add_f32_e32 v148, v146, v147
	v_pk_mul_f32 v[146:147], v[170:171], v[156:157]
	s_nop 0
	v_add_f32_e32 v147, v147, v148
	v_add_f32_e32 v152, v146, v147
	v_mul_f32_e32 v146, 0xbfb8aa3b, v152
	v_mov_b32_e32 v148, v153
	v_exp_f32_e32 v156, v146
	v_pk_mul_f32 v[146:147], v[140:141], v[148:149]
	v_add_f32_e32 v149, 1.0, v156
	v_add_f32_e32 v147, v145, v147
	v_add_f32_e32 v148, v146, v147
	v_pk_mul_f32 v[146:147], v[136:137], v[154:155]
	v_rcp_f32_e32 v149, v149
	v_add_f32_e32 v147, v147, v148
	v_add_f32_e32 v146, v146, v147
	v_mul_f32_e32 v147, 0xbfb8aa3b, v146
	v_exp_f32_e32 v147, v147
	v_mul_f32_e32 v148, v151, v158
	v_mul_f32_e32 v149, v152, v149
	v_cndmask_b32_e64 v148, v148, v151, s[4:5]
	v_add_f32_e32 v147, 1.0, v147
	v_rcp_f32_e32 v147, v147
	v_cndmask_b32_e64 v149, v149, v152, s[4:5]
	v_mov_b32_e32 v156, v8
	v_mov_b32_e32 v154, v9
	v_mul_f32_e32 v147, v146, v147
	v_cndmask_b32_e64 v147, v147, v146, s[4:5]
	v_cvt_pk_bf16_f32 v146, v150, v148
	v_cvt_pk_bf16_f32 v147, v149, v147
	v_mov_b32_e32 v38, v146
	v_mov_b32_e32 v39, v147
	s_cbranch_vccnz .LBB0_1545
	v_add_u32_e32 v147, 0xffffe0b0, v202
	v_ashrrev_i32_e32 v147, 2, v147
	v_lshl_add_u32 v147, v147, 1, v147
	v_mad_i64_i32 v[148:149], s[0:1], v147, s47, 0
	v_lshl_add_u64 v[148:149], v[148:149], 2, v[208:209]
	v_lshl_add_u64 v[150:151], v[148:149], 0, s[24:25]
	s_lshl_b32 s0, s27, 2
	s_mov_b32 s1, s25
	global_load_dwordx4 v[158:161], v[148:149], off offset:512
	s_nop 0
	global_load_dwordx4 v[150:153], v[150:151], off offset:512
	v_lshl_add_u64 v[148:149], v[148:149], 0, s[0:1]
	global_load_dwordx4 v[154:157], v[148:149], off offset:512
	v_mov_b32_e32 v164, 0
	v_mov_b32_e32 v165, 0
	v_mov_b32_e32 v146, 0
	v_mov_b32_dpp v164, v6 row_ror:1 row_mask:0xf bank_mask:0xf
	v_mov_b32_dpp v165, v6 row_ror:2 row_mask:0xf bank_mask:0xf
	v_mov_b32_dpp v146, v6 row_ror:3 row_mask:0xf bank_mask:0xf
	v_cmp_lt_i32_e32 vcc, 1, v205
	s_and_saveexec_b64 s[0:1], vcc
	s_xor_b64 s[0:1], exec, s[0:1]
	s_cbranch_execz .LBB0_1508
	v_cmp_gt_i32_e32 vcc, 3, v205
	s_and_saveexec_b64 s[2:3], vcc
	s_cbranch_execz .LBB0_1507
	s_waitcnt vmcnt(0)
	v_mov_b32_e32 v146, v154

; __device__ __forceinline__ unsigned cvt_pk_bf16(float lo, float hi) { unsigned r; asm("v_cvt_pk_bf16_f32 %0, %1, %2" : "=v"(r) : "v"(lo), "v"(hi)); return r; }
; __device__ __forceinline__ float siluf_(float x) { return x * sigmoidf_(x); }
; __device__ __forceinline__ float dpp_ror1(float v) { return __builtin_bit_cast(float, __builtin_amdgcn_update_dpp(0, __builtin_bit_cast(int, v), 0x121, 0xf, 0xf, false)); }
;     __device__ __forceinline__ void operator()(f32x4 (&acc)[2][2][4][2], const pg8::Unit& u, int wr, int wc, int fr, int fq) const {
;     ...
;                     const f32x4 w0 = *(const f32x4*)(cw + ch), w1 = *(const f32x4*)(cw + CW + ch), w2 = *(const f32x4*)(cw + 2 * CW + ch), w3 = *(const f32x4*)(cw + 3 * CW + ch), bb = *(const f32x4*)(cb + ch);
; #pragma unroll
;                     for (int m = 0; m < 4; ++m) { const int row = row0 + ai * 128 + m * 16; const f32x4 g = acc[ai][bj][m][n]; f32x4 p1, p2, p3;
;                         if (prompt) { const f32x4 gp = (m == 0) ? hal[n] : acc[ai][bj][m > 0 ? m - 1 : 0][n];
; #pragma unroll
;                             for (int j = 0; j < 4; ++j) { p1[j] = dpp_ror1(fr == 15 ? gp[j] : g[j]); p2[j] = dpp_ror2(fr >= 14 ? gp[j] : g[j]); p3[j] = dpp_ror3(fr >= 13 ? gp[j] : g[j]); } }
;                         else { const int t = fr & 3; const float* sp = stp + (size_t)((row - MP) >> 2) * 3 * CW + ch;
;                             const f32x4 b0 = *(const f32x4*)sp, b1 = *(const f32x4*)(sp + CW), b2 = *(const f32x4*)(sp + 2 * CW);
; #pragma unroll
;                             for (int j = 0; j < 4; ++j) { const float r1 = dpp_ror1(g[j]), r2 = dpp_ror2(g[j]), r3 = dpp_ror3(g[j]);
;                                 p1[j] = t >= 1 ? r1 : b2[j]; p2[j] = t >= 2 ? r2 : (t == 1 ? b2[j] : b1[j]); p3[j] = t >= 3 ? r3 : (t == 2 ? b2[j] : (t == 1 ? b1[j] : b0[j])); } }
;                         float o[4];
; #pragma unroll
;                         for (int j = 0; j < 4; ++j) { const float y = bb[j] + w0[j] * p3[j] + w1[j] * p2[j] + w2[j] * p1[j] + w3[j] * g[j]; o[j] = is_rg ? y : siluf_(y); }
;                         u32x2 w; w.x = cvt_pk_bf16(o[0], o[1]); w.y = cvt_pk_bf16(o[2], o[3]);
;                         *(u32x2*)(dst + (size_t)row * ld + bj * 128 + 4 * n) = w; }
.LBB0_1547:
	v_mov_b32_e32 v228, v150
	v_mov_b32_e32 v229, v146
	v_pk_mul_f32 v[166:167], v[166:167], v[228:229]
	v_mov_b32_e32 v173, v158
	v_add_f32_e32 v142, v142, v167
	v_add_f32_e32 v142, v166, v142
	v_pk_mul_f32 v[166:167], v[168:169], v[172:173]
	v_mov_b32_e32 v165, v159
	v_add_f32_e32 v142, v167, v142
	v_add_f32_e32 v142, v166, v142
	v_mul_f32_e32 v146, 0xbfb8aa3b, v142
	v_exp_f32_e32 v146, v146
	v_pk_mul_f32 v[134:135], v[134:135], v[164:165]
	v_mov_b32_e32 v157, v160
	v_mov_b32_e32 v155, v161
	v_add_f32_e32 v146, 1.0, v146
	v_rcp_f32_e32 v150, v146
	v_mov_b32_e32 v146, v151
	v_pk_mul_f32 v[138:139], v[138:139], v[146:147]
	s_mov_b64 s[0:1], -1
	v_add_f32_e32 v139, v143, v139
	v_add_f32_e32 v138, v138, v139
	v_add_f32_e32 v135, v135, v138
	v_add_f32_e32 v138, v134, v135
	v_mul_f32_e32 v134, 0xbfb8aa3b, v138
	v_exp_f32_e32 v134, v134
	v_mul_f32_e32 v135, v142, v150
	v_cndmask_b32_e64 v139, v135, v142, s[4:5]
	v_mov_b32_e32 v135, v148
	v_add_f32_e32 v134, 1.0, v134
	v_rcp_f32_e32 v142, v134
	v_mov_b32_e32 v134, v152
	v_pk_mul_f32 v[134:135], v[162:163], v[134:135]
	v_mov_b32_e32 v148, v153
	v_add_f32_e32 v135, v144, v135
	v_add_f32_e32 v143, v134, v135
	v_pk_mul_f32 v[134:135], v[170:171], v[156:157]
	s_and_b64 vcc, exec, s[18:19]
	v_add_f32_e32 v135, v135, v143
	v_add_f32_e32 v143, v134, v135
	v_mul_f32_e32 v134, 0xbfb8aa3b, v143
	v_exp_f32_e32 v144, v134
	v_pk_mul_f32 v[134:135], v[140:141], v[148:149]
	v_mov_b32_e32 v172, v52
	v_add_f32_e32 v135, v145, v135
	v_add_f32_e32 v140, v134, v135
	v_pk_mul_f32 v[134:135], v[136:137], v[154:155]
	v_add_f32_e32 v137, 1.0, v144
	v_add_f32_e32 v135, v135, v140
	v_add_f32_e32 v134, v134, v135
	v_mul_f32_e32 v135, 0xbfb8aa3b, v134
	v_exp_f32_e32 v135, v135
	v_rcp_f32_e32 v137, v137
	v_mul_f32_e32 v136, v138, v142
	v_cndmask_b32_e64 v136, v136, v138, s[4:5]
	v_add_f32_e32 v135, 1.0, v135
	v_rcp_f32_e32 v135, v135
	v_mul_f32_e32 v137, v143, v137
	v_cndmask_b32_e64 v137, v137, v143, s[4:5]
	v_mov_b32_e32 v170, v53
	v_mul_f32_e32 v135, v134, v135
	v_cndmask_b32_e64 v135, v135, v134, s[4:5]
	v_cvt_pk_bf16_f32 v134, v139, v136
	v_cvt_pk_bf16_f32 v135, v137, v135
	v_mov_b32_e32 v22, v134
	v_mov_b32_e32 v23, v135
	global_load_dwordx4 v[138:141], v[210:211], off offset:528
	global_load_dwordx4 v[150:153], v[212:213], off offset:528
	global_load_dwordx4 v[134:137], v[214:215], off offset:528
	global_load_dwordx4 v[146:149], v[216:217], off offset:528
	global_load_dwordx4 v[142:145], v[218:219], off offset:528
	v_mov_b32_e32 v212, v50
	v_mov_b32_e32 v210, v51
	s_cbranch_vccnz .LBB0_1589
	v_add_u32_e32 v155, 0xffffe080, v202
	v_ashrrev_i32_e32 v155, 2, v155
	v_lshl_add_u32 v155, v155, 1, v155
	v_mad_i64_i32 v[156:157], s[0:1], v155, s47, 0
	v_lshl_add_u64 v[156:157], v[156:157], 2, v[208:209]
	v_lshl_add_u64 v[158:159], v[156:157], 0, s[24:25]
	s_lshl_b32 s0, s27, 2
	s_mov_b32 s1, s25
	global_load_dwordx4 v[166:169], v[156:157], off offset:528
	s_nop 0
	global_load_dwordx4 v[158:161], v[158:159], off offset:528
	v_lshl_add_u64 v[156:157], v[156:157], 0, s[0:1]
	global_load_dwordx4 v[162:165], v[156:157], off offset:528
	v_mov_b32_e32 v170, 0
	v_mov_b32_e32 v171, 0
	v_mov_b32_e32 v154, 0
	v_mov_b32_dpp v170, v50 row_ror:1 row_mask:0xf bank_mask:0xf
	v_mov_b32_dpp v171, v50 row_ror:2 row_mask:0xf bank_mask:0xf
	v_mov_b32_dpp v154, v50 row_ror:3 row_mask:0xf bank_mask:0xf
	v_cmp_lt_i32_e32 vcc, 1, v205
	s_and_saveexec_b64 s[0:1], vcc
	s_xor_b64 s[0:1], exec, s[0:1]
	s_cbranch_execz .LBB0_1552
	v_cmp_gt_i32_e32 vcc, 3, v205
	s_and_saveexec_b64 s[2:3], vcc
	s_cbranch_execz .LBB0_1551
	s_waitcnt vmcnt(0)
	v_mov_b32_e32 v154, v162

; __device__ __forceinline__ unsigned cvt_pk_bf16(float lo, float hi) { unsigned r; asm("v_cvt_pk_bf16_f32 %0, %1, %2" : "=v"(r) : "v"(lo), "v"(hi)); return r; }
; __device__ __forceinline__ float siluf_(float x) { return x * sigmoidf_(x); }
; __device__ __forceinline__ float dpp_ror1(float v) { return __builtin_bit_cast(float, __builtin_amdgcn_update_dpp(0, __builtin_bit_cast(int, v), 0x121, 0xf, 0xf, false)); }
; __device__ __forceinline__ float dpp_ror2(float v) { return __builtin_bit_cast(float, __builtin_amdgcn_update_dpp(0, __builtin_bit_cast(int, v), 0x122, 0xf, 0xf, false)); }
; __device__ __forceinline__ float dpp_ror3(float v) { return __builtin_bit_cast(float, __builtin_amdgcn_update_dpp(0, __builtin_bit_cast(int, v), 0x123, 0xf, 0xf, false)); }
;     __device__ __forceinline__ void operator()(f32x4 (&acc)[2][2][4][2], const pg8::Unit& u, int wr, int wc, int fr, int fq) const {
;     ...
;                     for (int m = 0; m < 4; ++m) { const int row = row0 + ai * 128 + m * 16; const f32x4 g = acc[ai][bj][m][n]; f32x4 p1, p2, p3;
;                         if (prompt) { const f32x4 gp = (m == 0) ? hal[n] : acc[ai][bj][m > 0 ? m - 1 : 0][n];
; #pragma unroll
;                             for (int j = 0; j < 4; ++j) { p1[j] = dpp_ror1(fr == 15 ? gp[j] : g[j]); p2[j] = dpp_ror2(fr >= 14 ? gp[j] : g[j]); p3[j] = dpp_ror3(fr >= 13 ? gp[j] : g[j]); } }
;                         else { const int t = fr & 3; const float* sp = stp + (size_t)((row - MP) >> 2) * 3 * CW + ch;
;                             const f32x4 b0 = *(const f32x4*)sp, b1 = *(const f32x4*)(sp + CW), b2 = *(const f32x4*)(sp + 2 * CW);
; #pragma unroll
;                             for (int j = 0; j < 4; ++j) { const float r1 = dpp_ror1(g[j]), r2 = dpp_ror2(g[j]), r3 = dpp_ror3(g[j]);
;                                 p1[j] = t >= 1 ? r1 : b2[j]; p2[j] = t >= 2 ? r2 : (t == 1 ? b2[j] : b1[j]); p3[j] = t >= 3 ? r3 : (t == 2 ? b2[j] : (t == 1 ? b1[j] : b0[j])); } }
;                         float o[4];
; #pragma unroll
;                         for (int j = 0; j < 4; ++j) { const float y = bb[j] + w0[j] * p3[j] + w1[j] * p2[j] + w2[j] * p1[j] + w3[j] * g[j]; o[j] = is_rg ? y : siluf_(y); }
;                         u32x2 w; w.x = cvt_pk_bf16(o[0], o[1]); w.y = cvt_pk_bf16(o[2], o[3]);
;                         *(u32x2*)(dst + (size_t)row * ld + bj * 128 + 4 * n) = w; }
.LBB0_1591:
	s_waitcnt vmcnt(0)
	v_mov_b32_e32 v162, v150
	v_mov_b32_e32 v163, v138
	v_mov_b32_e32 v130, v158
	v_mov_b32_e32 v131, v154
	v_pk_mul_f32 v[130:131], v[162:163], v[130:131]
	v_mov_b32_e32 v164, v146
	v_add_f32_e32 v131, v142, v131
	v_mov_b32_e32 v165, v134
	v_mov_b32_e32 v213, v166
	v_add_f32_e32 v132, v130, v131
	v_pk_mul_f32 v[130:131], v[164:165], v[212:213]
	v_mov_b32_e32 v138, v151
	v_add_f32_e32 v131, v131, v132
	v_add_f32_e32 v132, v130, v131
	v_mul_f32_e32 v130, 0xbfb8aa3b, v132
	v_exp_f32_e32 v130, v130
	v_mov_b32_e32 v154, v159
	v_mov_b32_e32 v134, v147
	v_mov_b32_e32 v211, v167
	v_add_f32_e32 v130, 1.0, v130
	v_rcp_f32_e32 v133, v130
	v_pk_mul_f32 v[130:131], v[138:139], v[154:155]
	v_mov_b32_e32 v158, v152
	v_add_f32_e32 v131, v143, v131
	v_add_f32_e32 v146, v130, v131
	v_pk_mul_f32 v[130:131], v[134:135], v[210:211]
	v_mov_b32_e32 v159, v140
	v_add_f32_e32 v131, v131, v146
	v_add_f32_e32 v146, v130, v131
	v_mul_f32_e32 v130, 0xbfb8aa3b, v146
	v_exp_f32_e32 v130, v130
	v_mul_f32_e32 v131, v132, v133
	v_cndmask_b32_e64 v132, v131, v132, s[4:5]
	v_mov_b32_e32 v131, v156
	v_add_f32_e32 v130, 1.0, v130
	v_rcp_f32_e32 v133, v130
	v_mov_b32_e32 v130, v160
	v_pk_mul_f32 v[130:131], v[158:159], v[130:131]
	v_mov_b32_e32 v166, v148
	v_add_f32_e32 v131, v144, v131
	v_mov_b32_e32 v167, v136
	v_mov_b32_e32 v173, v168
	v_add_f32_e32 v140, v130, v131
	v_pk_mul_f32 v[130:131], v[166:167], v[172:173]
	v_mov_b32_e32 v156, v161
	v_add_f32_e32 v131, v131, v140
	v_add_f32_e32 v147, v130, v131
	v_mul_f32_e32 v130, 0xbfb8aa3b, v147
	v_mov_b32_e32 v140, v153
	v_exp_f32_e32 v148, v130
	v_pk_mul_f32 v[130:131], v[140:141], v[156:157]
	v_mov_b32_e32 v136, v149
	v_add_f32_e32 v131, v145, v131
	v_mov_b32_e32 v171, v169
	v_add_f32_e32 v150, v130, v131
	v_pk_mul_f32 v[130:131], v[136:137], v[170:171]
	v_add_f32_e32 v148, 1.0, v148
	v_add_f32_e32 v131, v131, v150
	v_add_f32_e32 v130, v130, v131
	v_mul_f32_e32 v131, 0xbfb8aa3b, v130
	v_exp_f32_e32 v131, v131
	v_rcp_f32_e32 v148, v148
	v_mul_f32_e32 v133, v146, v133
	v_cndmask_b32_e64 v133, v133, v146, s[4:5]
	v_add_f32_e32 v131, 1.0, v131
	v_rcp_f32_e32 v131, v131
	v_mul_f32_e32 v146, v147, v148
	v_cndmask_b32_e64 v146, v146, v147, s[4:5]
	s_mov_b64 s[0:1], -1
	v_mul_f32_e32 v131, v130, v131
	v_cndmask_b32_e64 v131, v131, v130, s[4:5]
	v_cvt_pk_bf16_f32 v130, v132, v133
	v_cvt_pk_bf16_f32 v131, v146, v131
	s_and_b64 vcc, exec, s[18:19]
	v_mov_b32_e32 v168, v34
	v_mov_b32_e32 v160, v35
	v_mov_b32_e32 v152, v36
	v_mov_b32_e32 v150, v37
	v_mov_b32_e32 v16, v130
	v_mov_b32_e32 v17, v131
	flat_store_dwordx4 v[222:223], v[14:17] offset:256
	s_cbranch_vccnz .LBB0_1633
	v_add_u32_e32 v131, 0xffffe090, v202
	v_ashrrev_i32_e32 v131, 2, v131
	v_lshl_add_u32 v131, v131, 1, v131
	v_mad_i64_i32 v[132:133], s[0:1], v131, s47, 0
	v_lshl_add_u64 v[132:133], v[132:133], 2, v[208:209]
	v_lshl_add_u64 v[146:147], v[132:133], 0, s[24:25]
	s_lshl_b32 s0, s27, 2
	s_mov_b32 s1, s25
	global_load_dwordx4 v[154:157], v[132:133], off offset:528
	s_nop 0
	global_load_dwordx4 v[146:149], v[146:147], off offset:528
	v_lshl_add_u64 v[132:133], v[132:133], 0, s[0:1]
	global_load_dwordx4 v[150:153], v[132:133], off offset:528
	v_mov_b32_e32 v160, 0
	v_mov_b32_e32 v161, 0
	v_mov_b32_e32 v130, 0
	v_mov_b32_dpp v160, v34 row_ror:1 row_mask:0xf bank_mask:0xf
	v_mov_b32_dpp v161, v34 row_ror:2 row_mask:0xf bank_mask:0xf
	v_mov_b32_dpp v130, v34 row_ror:3 row_mask:0xf bank_mask:0xf
	v_cmp_lt_i32_e32 vcc, 1, v205
	s_and_saveexec_b64 s[0:1], vcc
	s_xor_b64 s[0:1], exec, s[0:1]
	s_cbranch_execz .LBB0_1596
	v_cmp_gt_i32_e32 vcc, 3, v205
	s_and_saveexec_b64 s[2:3], vcc
	s_cbranch_execz .LBB0_1595
	s_waitcnt vmcnt(0)
	v_mov_b32_e32 v130, v150

; __device__ __forceinline__ unsigned cvt_pk_bf16(float lo, float hi) { unsigned r; asm("v_cvt_pk_bf16_f32 %0, %1, %2" : "=v"(r) : "v"(lo), "v"(hi)); return r; }
; __device__ __forceinline__ float siluf_(float x) { return x * sigmoidf_(x); }
; __device__ __forceinline__ float dpp_ror1(float v) { return __builtin_bit_cast(float, __builtin_amdgcn_update_dpp(0, __builtin_bit_cast(int, v), 0x121, 0xf, 0xf, false)); }
; __device__ __forceinline__ float dpp_ror2(float v) { return __builtin_bit_cast(float, __builtin_amdgcn_update_dpp(0, __builtin_bit_cast(int, v), 0x122, 0xf, 0xf, false)); }
; __device__ __forceinline__ float dpp_ror3(float v) { return __builtin_bit_cast(float, __builtin_amdgcn_update_dpp(0, __builtin_bit_cast(int, v), 0x123, 0xf, 0xf, false)); }
;     __device__ __forceinline__ void operator()(f32x4 (&acc)[2][2][4][2], const pg8::Unit& u, int wr, int wc, int fr, int fq) const {
;     ...
;                     for (int m = 0; m < 4; ++m) { const int row = row0 + ai * 128 + m * 16; const f32x4 g = acc[ai][bj][m][n]; f32x4 p1, p2, p3;
;                         if (prompt) { const f32x4 gp = (m == 0) ? hal[n] : acc[ai][bj][m > 0 ? m - 1 : 0][n];
; #pragma unroll
;                             for (int j = 0; j < 4; ++j) { p1[j] = dpp_ror1(fr == 15 ? gp[j] : g[j]); p2[j] = dpp_ror2(fr >= 14 ? gp[j] : g[j]); p3[j] = dpp_ror3(fr >= 13 ? gp[j] : g[j]); } }
;                         else { const int t = fr & 3; const float* sp = stp + (size_t)((row - MP) >> 2) * 3 * CW + ch;
;                             const f32x4 b0 = *(const f32x4*)sp, b1 = *(const f32x4*)(sp + CW), b2 = *(const f32x4*)(sp + 2 * CW);
; #pragma unroll
;                             for (int j = 0; j < 4; ++j) { const float r1 = dpp_ror1(g[j]), r2 = dpp_ror2(g[j]), r3 = dpp_ror3(g[j]);
;                                 p1[j] = t >= 1 ? r1 : b2[j]; p2[j] = t >= 2 ? r2 : (t == 1 ? b2[j] : b1[j]); p3[j] = t >= 3 ? r3 : (t == 2 ? b2[j] : (t == 1 ? b1[j] : b0[j])); } }
;                         float o[4];
; #pragma unroll
;                         for (int j = 0; j < 4; ++j) { const float y = bb[j] + w0[j] * p3[j] + w1[j] * p2[j] + w2[j] * p1[j] + w3[j] * g[j]; o[j] = is_rg ? y : siluf_(y); }
;                         u32x2 w; w.x = cvt_pk_bf16(o[0], o[1]); w.y = cvt_pk_bf16(o[2], o[3]);
;                         *(u32x2*)(dst + (size_t)row * ld + bj * 128 + 4 * n) = w; }
.LBB0_1635:
	v_mov_b32_e32 v170, v146
	v_mov_b32_e32 v171, v130
	v_pk_mul_f32 v[170:171], v[162:163], v[170:171]
	v_mov_b32_e32 v169, v154
	v_add_f32_e32 v130, v142, v171
	v_add_f32_e32 v130, v170, v130
	v_pk_mul_f32 v[168:169], v[164:165], v[168:169]
	v_mov_b32_e32 v161, v155
	v_add_f32_e32 v130, v169, v130
	v_add_f32_e32 v146, v168, v130
	v_mul_f32_e32 v130, 0xbfb8aa3b, v146
	v_exp_f32_e32 v130, v130
	v_mov_b32_e32 v153, v156
	s_mov_b64 s[0:1], -1
	s_and_b64 vcc, exec, s[18:19]
	v_add_f32_e32 v130, 1.0, v130
	v_rcp_f32_e32 v151, v130
	v_mov_b32_e32 v130, v147
	v_pk_mul_f32 v[130:131], v[138:139], v[130:131]
	v_mov_b32_e32 v168, v18
	v_add_f32_e32 v131, v143, v131
	v_add_f32_e32 v147, v130, v131
	v_pk_mul_f32 v[130:131], v[134:135], v[160:161]
	v_mov_b32_e32 v160, v19
	v_add_f32_e32 v131, v131, v147
	v_add_f32_e32 v147, v130, v131
	v_mul_f32_e32 v130, 0xbfb8aa3b, v147
	v_exp_f32_e32 v130, v130
	v_mul_f32_e32 v131, v146, v151
	v_cndmask_b32_e64 v146, v131, v146, s[4:5]
	v_mov_b32_e32 v131, v132
	v_add_f32_e32 v130, 1.0, v130
	v_rcp_f32_e32 v154, v130
	v_mov_b32_e32 v130, v148
	v_pk_mul_f32 v[130:131], v[158:159], v[130:131]
	v_mov_b32_e32 v151, v157
	v_add_f32_e32 v131, v144, v131
	v_add_f32_e32 v132, v130, v131
	v_pk_mul_f32 v[130:131], v[166:167], v[152:153]
	s_nop 0
	v_add_f32_e32 v131, v131, v132
	v_add_f32_e32 v148, v130, v131
	v_mul_f32_e32 v130, 0xbfb8aa3b, v148
	v_mov_b32_e32 v132, v149
	v_exp_f32_e32 v152, v130
	v_pk_mul_f32 v[130:131], v[140:141], v[132:133]
	v_add_f32_e32 v133, 1.0, v152
	v_add_f32_e32 v131, v145, v131
	v_add_f32_e32 v132, v130, v131
	v_pk_mul_f32 v[130:131], v[136:137], v[150:151]
	v_rcp_f32_e32 v133, v133
	v_add_f32_e32 v131, v131, v132
	v_add_f32_e32 v130, v130, v131
	v_mul_f32_e32 v131, 0xbfb8aa3b, v130
	v_exp_f32_e32 v131, v131
	v_mul_f32_e32 v132, v147, v154
	v_mul_f32_e32 v133, v148, v133
	v_cndmask_b32_e64 v132, v132, v147, s[4:5]
	v_add_f32_e32 v131, 1.0, v131
	v_rcp_f32_e32 v131, v131
	v_cndmask_b32_e64 v133, v133, v148, s[4:5]
	v_mov_b32_e32 v152, v20
	v_mov_b32_e32 v150, v21
	v_mul_f32_e32 v131, v130, v131
	v_cndmask_b32_e64 v131, v131, v130, s[4:5]
	v_cvt_pk_bf16_f32 v130, v146, v132
	v_cvt_pk_bf16_f32 v131, v133, v131
	v_mov_b32_e32 v56, v130
	v_mov_b32_e32 v57, v131
	flat_store_dwordx4 v[224:225], v[54:57] offset:256
	s_cbranch_vccnz .LBB0_1677
	v_add_u32_e32 v131, 0xffffe0a0, v202
	v_ashrrev_i32_e32 v131, 2, v131
	v_lshl_add_u32 v131, v131, 1, v131
	v_mad_i64_i32 v[132:133], s[0:1], v131, s47, 0
	v_lshl_add_u64 v[132:133], v[132:133], 2, v[208:209]
	v_lshl_add_u64 v[146:147], v[132:133], 0, s[24:25]
	s_lshl_b32 s0, s27, 2
	s_mov_b32 s1, s25
	global_load_dwordx4 v[154:157], v[132:133], off offset:528
	s_nop 0
	global_load_dwordx4 v[146:149], v[146:147], off offset:528
	v_lshl_add_u64 v[132:133], v[132:133], 0, s[0:1]
	global_load_dwordx4 v[150:153], v[132:133], off offset:528
	v_mov_b32_e32 v160, 0
	v_mov_b32_e32 v161, 0
	v_mov_b32_e32 v130, 0
	v_mov_b32_dpp v160, v18 row_ror:1 row_mask:0xf bank_mask:0xf
	v_mov_b32_dpp v161, v18 row_ror:2 row_mask:0xf bank_mask:0xf
	v_mov_b32_dpp v130, v18 row_ror:3 row_mask:0xf bank_mask:0xf
	v_cmp_lt_i32_e32 vcc, 1, v205
	s_and_saveexec_b64 s[0:1], vcc
	s_xor_b64 s[0:1], exec, s[0:1]
	s_cbranch_execz .LBB0_1640
	v_cmp_gt_i32_e32 vcc, 3, v205
	s_and_saveexec_b64 s[2:3], vcc
	s_cbranch_execz .LBB0_1639
	s_waitcnt vmcnt(0)
	v_mov_b32_e32 v130, v150

; __device__ __forceinline__ unsigned cvt_pk_bf16(float lo, float hi) { unsigned r; asm("v_cvt_pk_bf16_f32 %0, %1, %2" : "=v"(r) : "v"(lo), "v"(hi)); return r; }
; __device__ __forceinline__ float siluf_(float x) { return x * sigmoidf_(x); }
; __device__ __forceinline__ float dpp_ror1(float v) { return __builtin_bit_cast(float, __builtin_amdgcn_update_dpp(0, __builtin_bit_cast(int, v), 0x121, 0xf, 0xf, false)); }
; __device__ __forceinline__ float dpp_ror2(float v) { return __builtin_bit_cast(float, __builtin_amdgcn_update_dpp(0, __builtin_bit_cast(int, v), 0x122, 0xf, 0xf, false)); }
; __device__ __forceinline__ float dpp_ror3(float v) { return __builtin_bit_cast(float, __builtin_amdgcn_update_dpp(0, __builtin_bit_cast(int, v), 0x123, 0xf, 0xf, false)); }
;     __device__ __forceinline__ void operator()(f32x4 (&acc)[2][2][4][2], const pg8::Unit& u, int wr, int wc, int fr, int fq) const {
;     ...
;                     for (int m = 0; m < 4; ++m) { const int row = row0 + ai * 128 + m * 16; const f32x4 g = acc[ai][bj][m][n]; f32x4 p1, p2, p3;
;                         if (prompt) { const f32x4 gp = (m == 0) ? hal[n] : acc[ai][bj][m > 0 ? m - 1 : 0][n];
; #pragma unroll
;                             for (int j = 0; j < 4; ++j) { p1[j] = dpp_ror1(fr == 15 ? gp[j] : g[j]); p2[j] = dpp_ror2(fr >= 14 ? gp[j] : g[j]); p3[j] = dpp_ror3(fr >= 13 ? gp[j] : g[j]); } }
;                         else { const int t = fr & 3; const float* sp = stp + (size_t)((row - MP) >> 2) * 3 * CW + ch;
;                             const f32x4 b0 = *(const f32x4*)sp, b1 = *(const f32x4*)(sp + CW), b2 = *(const f32x4*)(sp + 2 * CW);
; #pragma unroll
;                             for (int j = 0; j < 4; ++j) { const float r1 = dpp_ror1(g[j]), r2 = dpp_ror2(g[j]), r3 = dpp_ror3(g[j]);
;                                 p1[j] = t >= 1 ? r1 : b2[j]; p2[j] = t >= 2 ? r2 : (t == 1 ? b2[j] : b1[j]); p3[j] = t >= 3 ? r3 : (t == 2 ? b2[j] : (t == 1 ? b1[j] : b0[j])); } }
;                         float o[4];
; #pragma unroll
;                         for (int j = 0; j < 4; ++j) { const float y = bb[j] + w0[j] * p3[j] + w1[j] * p2[j] + w2[j] * p1[j] + w3[j] * g[j]; o[j] = is_rg ? y : siluf_(y); }
;                         u32x2 w; w.x = cvt_pk_bf16(o[0], o[1]); w.y = cvt_pk_bf16(o[2], o[3]);
;                         *(u32x2*)(dst + (size_t)row * ld + bj * 128 + 4 * n) = w; }
.LBB0_1679:
	v_mov_b32_e32 v170, v146
	v_mov_b32_e32 v171, v130
	v_pk_mul_f32 v[170:171], v[162:163], v[170:171]
	v_mov_b32_e32 v169, v154
	v_add_f32_e32 v130, v142, v171
	v_add_f32_e32 v130, v170, v130
	v_pk_mul_f32 v[168:169], v[164:165], v[168:169]
	v_mov_b32_e32 v161, v155
	v_add_f32_e32 v130, v169, v130
	v_add_f32_e32 v146, v168, v130
	v_mul_f32_e32 v130, 0xbfb8aa3b, v146
	v_exp_f32_e32 v130, v130
	v_mov_b32_e32 v153, v156
	s_and_b64 vcc, exec, s[18:19]
	s_mov_b64 s[0:1], -1
	v_add_f32_e32 v130, 1.0, v130
	v_rcp_f32_e32 v151, v130
	v_mov_b32_e32 v130, v147
	v_pk_mul_f32 v[130:131], v[138:139], v[130:131]
	s_nop 0
	v_add_f32_e32 v131, v143, v131
	v_add_f32_e32 v147, v130, v131
	v_pk_mul_f32 v[130:131], v[134:135], v[160:161]
	s_nop 0
	v_add_f32_e32 v131, v131, v147
	v_add_f32_e32 v147, v130, v131
	v_mul_f32_e32 v130, 0xbfb8aa3b, v147
	v_exp_f32_e32 v130, v130
	v_mul_f32_e32 v131, v146, v151
	v_cndmask_b32_e64 v146, v131, v146, s[4:5]
	v_mov_b32_e32 v131, v132
	v_add_f32_e32 v130, 1.0, v130
	v_rcp_f32_e32 v154, v130
	v_mov_b32_e32 v130, v148
	v_pk_mul_f32 v[130:131], v[158:159], v[130:131]
	v_mov_b32_e32 v151, v157
	v_add_f32_e32 v131, v144, v131
	v_add_f32_e32 v132, v130, v131
	v_pk_mul_f32 v[130:131], v[166:167], v[152:153]
	s_nop 0
	v_add_f32_e32 v131, v131, v132
	v_add_f32_e32 v148, v130, v131
	v_mul_f32_e32 v130, 0xbfb8aa3b, v148
	v_mov_b32_e32 v132, v149
	v_exp_f32_e32 v152, v130
	v_pk_mul_f32 v[130:131], v[140:141], v[132:133]
	v_add_f32_e32 v133, 1.0, v152
	v_add_f32_e32 v131, v145, v131
	v_add_f32_e32 v132, v130, v131
	v_pk_mul_f32 v[130:131], v[136:137], v[150:151]
	v_rcp_f32_e32 v133, v133
	v_add_f32_e32 v131, v131, v132
	v_add_f32_e32 v130, v130, v131
	v_mul_f32_e32 v131, 0xbfb8aa3b, v130
	v_exp_f32_e32 v131, v131
	v_mul_f32_e32 v132, v147, v154
	v_mul_f32_e32 v133, v148, v133
	v_cndmask_b32_e64 v132, v132, v147, s[4:5]
	v_add_f32_e32 v131, 1.0, v131
	v_rcp_f32_e32 v131, v131
	v_cndmask_b32_e64 v133, v133, v148, s[4:5]
	v_mul_f32_e32 v131, v130, v131
	v_cndmask_b32_e64 v131, v131, v130, s[4:5]
	v_cvt_pk_bf16_f32 v130, v146, v132
	v_cvt_pk_bf16_f32 v131, v133, v131
	v_mov_b32_e32 v40, v130
	v_mov_b32_e32 v41, v131
	flat_store_dwordx4 v[226:227], v[38:41] offset:256
	s_cbranch_vccnz .LBB0_1721
	v_add_u32_e32 v131, 0xffffe0b0, v202
	v_ashrrev_i32_e32 v131, 2, v131
	v_lshl_add_u32 v131, v131, 1, v131
	v_mad_i64_i32 v[132:133], s[0:1], v131, s47, 0
	v_lshl_add_u64 v[132:133], v[132:133], 2, v[208:209]
	v_lshl_add_u64 v[146:147], v[132:133], 0, s[24:25]
	s_lshl_b32 s24, s27, 2
	global_load_dwordx4 v[154:157], v[132:133], off offset:528
	s_nop 0
	global_load_dwordx4 v[146:149], v[146:147], off offset:528
	v_lshl_add_u64 v[132:133], v[132:133], 0, s[24:25]
	global_load_dwordx4 v[150:153], v[132:133], off offset:528
	v_mov_b32_e32 v160, 0
	v_mov_b32_e32 v161, 0
	v_mov_b32_e32 v130, 0
	v_mov_b32_dpp v160, v2 row_ror:1 row_mask:0xf bank_mask:0xf
	v_mov_b32_dpp v161, v2 row_ror:2 row_mask:0xf bank_mask:0xf
	v_mov_b32_dpp v130, v2 row_ror:3 row_mask:0xf bank_mask:0xf
	v_cmp_lt_i32_e32 vcc, 1, v205
	s_and_saveexec_b64 s[0:1], vcc
	s_xor_b64 s[0:1], exec, s[0:1]
	s_cbranch_execz .LBB0_1684
	v_cmp_gt_i32_e32 vcc, 3, v205
	s_and_saveexec_b64 s[2:3], vcc
	s_cbranch_execz .LBB0_1683
	s_waitcnt vmcnt(0)
	v_mov_b32_e32 v130, v150

; __device__ __forceinline__ unsigned cvt_pk_bf16(float lo, float hi) { unsigned r; asm("v_cvt_pk_bf16_f32 %0, %1, %2" : "=v"(r) : "v"(lo), "v"(hi)); return r; }
; __device__ __forceinline__ float siluf_(float x) { return x * sigmoidf_(x); }
;     __device__ __forceinline__ void operator()(f32x4 (&acc)[2][2][4][2], const pg8::Unit& u, int wr, int wc, int fr, int fq) const {
;     ...
;                         float o[4];
; #pragma unroll
;                         for (int j = 0; j < 4; ++j) { const float y = bb[j] + w0[j] * p3[j] + w1[j] * p2[j] + w2[j] * p1[j] + w3[j] * g[j]; o[j] = is_rg ? y : siluf_(y); }
;                         u32x2 w; w.x = cvt_pk_bf16(o[0], o[1]); w.y = cvt_pk_bf16(o[2], o[3]);
;                         *(u32x2*)(dst + (size_t)row * ld + bj * 128 + 4 * n) = w; }
.LBB0_1723:
	v_mov_b32_e32 v150, v146
	v_mov_b32_e32 v151, v130
	v_pk_mul_f32 v[150:151], v[162:163], v[150:151]
	s_mov_b64 s[0:1], 0
	v_add_f32_e32 v130, v142, v151
	v_add_f32_e32 v130, v150, v130
	v_mov_b32_e32 v150, v2
	v_mov_b32_e32 v151, v154
	v_pk_mul_f32 v[150:151], v[164:165], v[150:151]
	v_mov_b32_e32 v154, v3
	v_add_f32_e32 v130, v151, v130
	v_add_f32_e32 v142, v150, v130
	v_mul_f32_e32 v130, 0xbfb8aa3b, v142
	v_exp_f32_e32 v130, v130
	v_readlane_b32 s24, v255, 21
	v_add_f32_e32 v130, 1.0, v130
	v_rcp_f32_e32 v146, v130
	v_mov_b32_e32 v130, v147
	v_pk_mul_f32 v[130:131], v[138:139], v[130:131]
	s_nop 0
	v_add_f32_e32 v131, v143, v131
	v_add_f32_e32 v138, v130, v131
	v_pk_mul_f32 v[130:131], v[134:135], v[154:155]
	s_nop 0
	v_add_f32_e32 v131, v131, v138
	v_add_f32_e32 v134, v130, v131
	v_mul_f32_e32 v130, 0xbfb8aa3b, v134
	v_exp_f32_e32 v130, v130
	v_mul_f32_e32 v131, v142, v146
	v_cndmask_b32_e64 v135, v131, v142, s[4:5]
	v_mov_b32_e32 v131, v132
	v_add_f32_e32 v130, 1.0, v130
	v_rcp_f32_e32 v138, v130
	v_mov_b32_e32 v130, v148
	v_pk_mul_f32 v[130:131], v[158:159], v[130:131]
	s_nop 0
	v_add_f32_e32 v131, v144, v131
	v_add_f32_e32 v132, v130, v131
	v_mov_b32_e32 v130, v4
	v_mov_b32_e32 v131, v156
	v_pk_mul_f32 v[130:131], v[166:167], v[130:131]
	v_mov_b32_e32 v156, v5
	v_add_f32_e32 v131, v131, v132
	v_add_f32_e32 v139, v130, v131
	v_mul_f32_e32 v130, 0xbfb8aa3b, v139
	v_mov_b32_e32 v132, v149
	v_exp_f32_e32 v142, v130
	v_pk_mul_f32 v[130:131], v[140:141], v[132:133]
	v_add_f32_e32 v133, 1.0, v142
	v_add_f32_e32 v131, v145, v131
	v_add_f32_e32 v132, v130, v131
	v_pk_mul_f32 v[130:131], v[136:137], v[156:157]
	v_rcp_f32_e32 v133, v133
	v_add_f32_e32 v131, v131, v132
	v_add_f32_e32 v130, v130, v131
	v_mul_f32_e32 v131, 0xbfb8aa3b, v130
	v_exp_f32_e32 v131, v131
	v_mul_f32_e32 v132, v134, v138
	v_mul_f32_e32 v133, v139, v133
	v_cndmask_b32_e64 v132, v132, v134, s[4:5]
	v_add_f32_e32 v131, 1.0, v131
	v_rcp_f32_e32 v131, v131
	v_cndmask_b32_e64 v133, v133, v139, s[4:5]
	v_mul_f32_e32 v131, v130, v131
	v_cndmask_b32_e64 v131, v131, v130, s[4:5]
	v_cvt_pk_bf16_f32 v130, v135, v132
	v_cvt_pk_bf16_f32 v131, v133, v131
	v_mov_b32_e32 v24, v130
	v_mov_b32_e32 v25, v131
	flat_store_dwordx4 v[220:221], v[22:25] offset:256
